# k19 + lever 7: attention xor-32 row-max exchanges via v_permlane32_swap and NSA importance xor-1/2 via DPP quad_perm instead of ds_bpermute round trips
# speedup vs baseline: 1.0072x; 1.0052x over previous
.LBB0_1505:
	s_cmp_gt_u32 s42, 23
	v_mov_b32_e32 v37, 0
	s_cselect_b64 s[20:21], -1, 0
	s_cmp_lt_u32 s42, 24
	v_mov_b32_e32 v38, 0
	s_cbranch_scc1 .LBB0_1507
	ds_read_b128 v[38:41], v52 offset:528
	ds_read_b128 v[42:45], v52 offset:512
	s_waitcnt lgkmcnt(0)
	v_fma_f32 v46, v42, v29, 0
	v_fmac_f32_e32 v46, v38, v30
	v_fmac_f32_e32 v46, v43, v31
	v_fmac_f32_e32 v46, v39, v32
	v_fmac_f32_e32 v46, v44, v33
	v_fmac_f32_e32 v46, v40, v34
	v_fmac_f32_e32 v46, v45, v35
	v_fmac_f32_e32 v46, v41, v36
	ds_read_b128 v[38:41], v52 offset:592
	ds_read_b128 v[42:45], v52 offset:576
	s_waitcnt lgkmcnt(0)
	v_fmac_f32_e32 v46, v42, v21
	v_fmac_f32_e32 v46, v38, v22
	v_fmac_f32_e32 v46, v43, v23
	v_fmac_f32_e32 v46, v39, v24
	v_fmac_f32_e32 v46, v44, v25
	v_fmac_f32_e32 v46, v40, v26
	v_fmac_f32_e32 v46, v45, v27
	v_fmac_f32_e32 v46, v41, v28
	ds_read_b128 v[38:41], v52 offset:656
	ds_read_b128 v[42:45], v52 offset:640
	s_waitcnt lgkmcnt(0)
	v_fmac_f32_e32 v46, v42, v17
	v_fmac_f32_e32 v46, v38, v18
	v_fmac_f32_e32 v46, v43, v19
	v_fmac_f32_e32 v46, v39, v20
	v_mov_b32_e32 v38, v40
	v_mov_b32_e32 v39, v44
	v_pk_mul_f32 v[38:39], v[38:39], v[14:15]
	v_mov_b32_e32 v44, v41
	v_add_f32_e32 v39, v39, v46
	v_add_f32_e32 v40, v38, v39
	v_pk_mul_f32 v[38:39], v[44:45], v[12:13]
	s_nop 0
	v_add_f32_e32 v39, v39, v40
	v_add_f32_e32 v48, v38, v39
	ds_read_b128 v[38:41], v52 offset:720
	ds_read_b128 v[42:45], v52 offset:704
	s_waitcnt lgkmcnt(1)
	v_mov_b32_e32 v46, v38
	s_waitcnt lgkmcnt(0)
	v_mov_b32_e32 v47, v42
	v_pk_mul_f32 v[46:47], v[46:47], v[10:11]
	v_mov_b32_e32 v42, v39
	v_add_f32_e32 v38, v47, v48
	v_add_f32_e32 v46, v46, v38
	v_pk_mul_f32 v[38:39], v[42:43], v[8:9]
	s_nop 0
	v_add_f32_e32 v39, v39, v46
	v_add_f32_e32 v42, v38, v39
	v_mov_b32_e32 v38, v40
	v_mov_b32_e32 v39, v44
	v_pk_mul_f32 v[38:39], v[38:39], v[6:7]
	v_mov_b32_e32 v44, v41
	v_add_f32_e32 v39, v39, v42
	v_add_f32_e32 v40, v38, v39
	v_pk_mul_f32 v[38:39], v[44:45], v[4:5]
	s_nop 0
	v_add_f32_e32 v39, v39, v40
	v_and_b32_e32 v40, 64, v235
	v_add_f32_e32 v38, v38, v39
	v_xor_b32_e32 v39, 32, v235
	v_add_u32_e32 v40, 64, v40
	v_cmp_lt_i32_e32 vcc, v39, v40
	s_nop 1
	v_cndmask_b32_e32 v39, v235, v39, vcc
	v_lshlrev_b32_e32 v39, 2, v39
	v_mov_b32_e32 v39, v38
	s_nop 1
	v_permlane32_swap_b32 v39, v38
	s_waitcnt lgkmcnt(0)
	v_add_f32_e32 v38, v38, v39

.LBB0_1509:
	s_cmp_gt_u32 s42, 39
	v_mov_b32_e32 v39, 0
	s_cselect_b64 s[24:25], -1, 0
	s_cmp_lt_u32 s42, 40
	v_mov_b32_e32 v40, 0
	s_cbranch_scc1 .LBB0_1511
	ds_read_b128 v[40:43], v52 offset:1040
	ds_read_b128 v[44:47], v52 offset:1024
	s_waitcnt lgkmcnt(0)
	v_fma_f32 v48, v44, v29, 0
	v_fmac_f32_e32 v48, v40, v30
	v_fmac_f32_e32 v48, v45, v31
	v_fmac_f32_e32 v48, v41, v32
	v_fmac_f32_e32 v48, v46, v33
	v_fmac_f32_e32 v48, v42, v34
	v_fmac_f32_e32 v48, v47, v35
	v_fmac_f32_e32 v48, v43, v36
	ds_read_b128 v[40:43], v52 offset:1104
	ds_read_b128 v[44:47], v52 offset:1088
	s_waitcnt lgkmcnt(0)
	v_fmac_f32_e32 v48, v44, v21
	v_fmac_f32_e32 v48, v40, v22
	v_fmac_f32_e32 v48, v45, v23
	v_fmac_f32_e32 v48, v41, v24
	v_fmac_f32_e32 v48, v46, v25
	v_fmac_f32_e32 v48, v42, v26
	v_fmac_f32_e32 v48, v47, v27
	v_fmac_f32_e32 v48, v43, v28
	ds_read_b128 v[40:43], v52 offset:1168
	ds_read_b128 v[44:47], v52 offset:1152
	s_waitcnt lgkmcnt(0)
	v_fmac_f32_e32 v48, v44, v17
	v_fmac_f32_e32 v48, v40, v18
	v_fmac_f32_e32 v48, v45, v19
	v_fmac_f32_e32 v48, v41, v20
	v_mov_b32_e32 v40, v42
	v_mov_b32_e32 v41, v46
	v_pk_mul_f32 v[40:41], v[40:41], v[14:15]
	v_mov_b32_e32 v46, v43
	v_add_f32_e32 v41, v41, v48
	v_add_f32_e32 v42, v40, v41
	v_pk_mul_f32 v[40:41], v[46:47], v[12:13]
	s_nop 0
	v_add_f32_e32 v41, v41, v42
	v_add_f32_e32 v50, v40, v41
	ds_read_b128 v[40:43], v52 offset:1232
	ds_read_b128 v[44:47], v52 offset:1216
	s_waitcnt lgkmcnt(1)
	v_mov_b32_e32 v48, v40
	s_waitcnt lgkmcnt(0)
	v_mov_b32_e32 v49, v44
	v_pk_mul_f32 v[48:49], v[48:49], v[10:11]
	v_mov_b32_e32 v44, v41
	v_add_f32_e32 v40, v49, v50
	v_add_f32_e32 v48, v48, v40
	v_pk_mul_f32 v[40:41], v[44:45], v[8:9]
	s_nop 0
	v_add_f32_e32 v41, v41, v48
	v_add_f32_e32 v44, v40, v41
	v_mov_b32_e32 v40, v42
	v_mov_b32_e32 v41, v46
	v_pk_mul_f32 v[40:41], v[40:41], v[6:7]
	v_mov_b32_e32 v46, v43
	v_add_f32_e32 v41, v41, v44
	v_add_f32_e32 v42, v40, v41
	v_pk_mul_f32 v[40:41], v[46:47], v[4:5]
	s_nop 0
	v_add_f32_e32 v41, v41, v42
	v_and_b32_e32 v42, 64, v235
	v_add_f32_e32 v40, v40, v41
	v_xor_b32_e32 v41, 32, v235
	v_add_u32_e32 v42, 64, v42
	v_cmp_lt_i32_e32 vcc, v41, v42
	s_nop 1
	v_cndmask_b32_e32 v41, v235, v41, vcc
	v_lshlrev_b32_e32 v41, 2, v41
	v_mov_b32_e32 v41, v40
	s_nop 1
	v_permlane32_swap_b32 v41, v40
	s_waitcnt lgkmcnt(0)
	v_add_f32_e32 v40, v40, v41

.LBB0_1513:
	s_lshr_b32 s19, s42, 3
	s_cmp_eq_u32 s19, 7
	s_cselect_b64 s[4:5], -1, 0
	s_cmp_lg_u32 s19, 7
	v_mov_b32_e32 v41, 0
	s_cbranch_scc1 .LBB0_1515
	ds_read_b128 v[42:45], v52 offset:1552
	ds_read_b128 v[46:49], v52 offset:1536
	s_waitcnt lgkmcnt(0)
	v_fma_f32 v41, v46, v29, 0
	v_fmac_f32_e32 v41, v42, v30
	v_fmac_f32_e32 v41, v47, v31
	v_fmac_f32_e32 v41, v43, v32
	v_fmac_f32_e32 v41, v48, v33
	v_fmac_f32_e32 v41, v44, v34
	v_fmac_f32_e32 v41, v49, v35
	v_fmac_f32_e32 v41, v45, v36
	ds_read_b128 v[30:33], v52 offset:1616
	ds_read_b128 v[42:45], v52 offset:1600
	s_waitcnt lgkmcnt(0)
	v_fmac_f32_e32 v41, v42, v21
	v_fmac_f32_e32 v41, v30, v22
	v_fmac_f32_e32 v41, v43, v23
	v_fmac_f32_e32 v41, v31, v24
	v_fmac_f32_e32 v41, v44, v25
	v_fmac_f32_e32 v41, v32, v26
	v_fmac_f32_e32 v41, v45, v27
	v_fmac_f32_e32 v41, v33, v28
	ds_read_b128 v[22:25], v52 offset:1680
	ds_read_b128 v[26:29], v52 offset:1664
	s_waitcnt lgkmcnt(0)
	v_fmac_f32_e32 v41, v26, v17
	v_fmac_f32_e32 v41, v22, v18
	v_fmac_f32_e32 v41, v27, v19
	v_mov_b32_e32 v18, v24
	v_mov_b32_e32 v19, v28
	v_fmac_f32_e32 v41, v23, v20
	v_pk_mul_f32 v[14:15], v[18:19], v[14:15]
	v_mov_b32_e32 v28, v25
	v_add_f32_e32 v15, v15, v41
	v_add_f32_e32 v14, v14, v15
	v_pk_mul_f32 v[12:13], v[28:29], v[12:13]
	s_nop 0
	v_add_f32_e32 v13, v13, v14
	v_add_f32_e32 v17, v12, v13
	ds_read_b128 v[12:15], v52 offset:1744
	ds_read_b128 v[18:21], v52 offset:1728
	s_waitcnt lgkmcnt(1)
	v_mov_b32_e32 v2, v12
	s_waitcnt lgkmcnt(0)
	v_mov_b32_e32 v3, v18
	v_pk_mul_f32 v[2:3], v[2:3], v[10:11]
	v_mov_b32_e32 v18, v13
	v_add_f32_e32 v3, v3, v17
	v_add_f32_e32 v10, v2, v3
	v_pk_mul_f32 v[2:3], v[18:19], v[8:9]
	s_nop 0
	v_add_f32_e32 v3, v3, v10
	v_add_f32_e32 v8, v2, v3
	v_mov_b32_e32 v2, v14
	v_mov_b32_e32 v3, v20
	v_pk_mul_f32 v[2:3], v[2:3], v[6:7]
	v_mov_b32_e32 v20, v15
	v_add_f32_e32 v3, v3, v8
	v_add_f32_e32 v6, v2, v3
	v_pk_mul_f32 v[2:3], v[20:21], v[4:5]
	v_and_b32_e32 v4, 64, v235
	v_add_f32_e32 v3, v3, v6
	v_add_f32_e32 v2, v2, v3
	v_xor_b32_e32 v3, 32, v235
	v_add_u32_e32 v4, 64, v4
	v_cmp_lt_i32_e32 vcc, v3, v4
	s_nop 1
	v_cndmask_b32_e32 v3, v235, v3, vcc
	v_lshlrev_b32_e32 v3, 2, v3
	v_mov_b32_e32 v3, v2
	s_nop 1
	v_permlane32_swap_b32 v3, v2
	s_waitcnt lgkmcnt(0)
	v_add_f32_e32 v41, v2, v3

.LBB0_1529:
	s_lshl_b32 s4, s0, 6
	s_or_b32 s2, s4, 63
	s_ashr_i32 s3, s0, 2
	s_cmp_eq_u32 s3, s19
	s_cselect_b64 s[0:1], -1, 0
	s_lshl_b32 s3, 1, s3
	v_and_b32_e32 v0, s3, v185
	v_cmp_ne_u32_e32 vcc, 0, v0
	s_or_b64 s[8:9], s[0:1], vcc
	s_cmp_gt_i32 s2, s41
	s_mov_b64 s[0:1], -1
	s_cbranch_scc1 .LBB0_1536
	v_cndmask_b32_e64 v0, 0, 1, s[8:9]
	v_cmp_ne_u32_e32 vcc, 0, v0
	v_max_i32_e32 v0, v20, v4
	v_max3_i32 v0, v18, v2, v0
	v_max_i32_e32 v180, v21, v5
	v_max_i32_e32 v181, v22, v6
	v_max_i32_e32 v179, v24, v8
	v_max3_i32 v180, v19, v3, v180
	v_max_i32_e32 v178, v23, v7
	v_max3_i32 v0, v0, v181, v179
	v_max_i32_e32 v181, v25, v9
	v_max3_i32 v180, v180, v178, v181
	v_max_i32_e32 v181, v26, v10
	v_max_i32_e32 v179, v28, v12
	v_max_i32_e32 v178, v27, v11
	v_max3_i32 v0, v0, v181, v179
	v_max_i32_e32 v181, v29, v13
	v_max3_i32 v180, v180, v178, v181
	v_max_i32_e32 v181, v30, v14
	v_max_i32_e32 v179, v32, v16
	v_max_i32_e32 v178, v31, v15
	v_max3_i32 v0, v0, v181, v179
	v_max_i32_e32 v181, v33, v17
	v_max3_i32 v180, v180, v178, v181
	s_cmp_eq_u64 vcc, exec
	v_max3_i32 v194, v0, v180, 0
	s_cbranch_scc1 .LBB0_1532
	v_and_b32_e32 v181, 64, v235
	v_xor_b32_e32 v180, 32, v235
	v_add_u32_e32 v181, 64, v181
	v_cmp_lt_i32_e32 vcc, v180, v181
	v_cndmask_b32_e64 v0, v239, v194, s[8:9]
	s_mov_b64 s[0:1], 0
	v_cndmask_b32_e32 v180, v235, v180, vcc
	v_lshlrev_b32_e32 v180, 2, v180
	v_mov_b32_e32 v180, v0
	s_nop 1
	v_permlane32_swap_b32 v180, v0
	s_waitcnt lgkmcnt(0)
	v_max3_f32 v193, v192, v0, v180
	v_cmp_neq_f32_e32 vcc, s69, v193
	s_nop 1
	v_cndmask_b32_e32 v178, 0, v193, vcc
	v_mul_f32_e32 v0, 0xbe38aa3b, v178
	v_cndmask_b32_e64 v195, v239, v0, s[8:9]
	v_fmamk_f32 v0, v18, 0x3e38aa3b, v195
	v_exp_f32_e32 v160, v0
	v_fmamk_f32 v0, v2, 0x3e38aa3b, v195
	v_exp_f32_e32 v197, v0
	v_fmamk_f32 v0, v19, 0x3e38aa3b, v195
	v_exp_f32_e32 v152, v0
	v_fmamk_f32 v0, v3, 0x3e38aa3b, v195
	v_exp_f32_e32 v0, v0
	v_add_f32_e32 v153, v160, v197
	v_cvt_pk_bf16_f32 v206, v160, v152
	v_pk_add_f32 v[180:181], v[152:153], v[0:1]
	s_nop 0
	v_pk_add_f32 v[202:203], v[180:181], v[180:181] op_sel_hi:[0,1]
	v_fmamk_f32 v180, v20, 0x3e38aa3b, v195
	v_exp_f32_e32 v153, v180
	v_fmamk_f32 v180, v4, 0x3e38aa3b, v195
	v_exp_f32_e32 v205, v180
	v_fmamk_f32 v180, v21, 0x3e38aa3b, v195
	v_exp_f32_e32 v154, v180
	v_fmamk_f32 v180, v5, 0x3e38aa3b, v195
	v_exp_f32_e32 v202, v180
	v_add_f32_e32 v155, v153, v205
	v_cvt_pk_bf16_f32 v207, v153, v154
	v_pk_add_f32 v[180:181], v[154:155], v[202:203]
	s_nop 0
	v_pk_add_f32 v[210:211], v[180:181], v[180:181] op_sel_hi:[0,1]
	v_fmamk_f32 v180, v22, 0x3e38aa3b, v195
	v_exp_f32_e32 v155, v180
	v_fmamk_f32 v180, v6, 0x3e38aa3b, v195
	v_exp_f32_e32 v203, v180
	v_fmamk_f32 v180, v23, 0x3e38aa3b, v195
	v_exp_f32_e32 v156, v180
	v_fmamk_f32 v180, v7, 0x3e38aa3b, v195
	v_exp_f32_e32 v210, v180
	v_add_f32_e32 v157, v155, v203
	v_cvt_pk_bf16_f32 v208, v155, v156
	v_pk_add_f32 v[180:181], v[156:157], v[210:211]
	s_nop 0
	v_pk_add_f32 v[212:213], v[180:181], v[180:181] op_sel_hi:[0,1]
	v_fmamk_f32 v180, v24, 0x3e38aa3b, v195
	v_exp_f32_e32 v157, v180
	v_fmamk_f32 v180, v8, 0x3e38aa3b, v195
	v_exp_f32_e32 v211, v180
	v_fmamk_f32 v180, v25, 0x3e38aa3b, v195
	v_exp_f32_e32 v158, v180
	v_fmamk_f32 v180, v9, 0x3e38aa3b, v195
	v_exp_f32_e32 v212, v180
	v_add_f32_e32 v159, v157, v211
	v_cvt_pk_bf16_f32 v209, v157, v158
	v_pk_add_f32 v[180:181], v[158:159], v[212:213]
	s_nop 0
	v_pk_add_f32 v[214:215], v[180:181], v[180:181] op_sel_hi:[0,1]
	v_fmamk_f32 v180, v26, 0x3e38aa3b, v195
	v_exp_f32_e32 v213, v180
	v_fmamk_f32 v180, v10, 0x3e38aa3b, v195
	v_exp_f32_e32 v223, v180
	v_fmamk_f32 v180, v27, 0x3e38aa3b, v195
	v_exp_f32_e32 v216, v180
	v_fmamk_f32 v180, v11, 0x3e38aa3b, v195
	v_exp_f32_e32 v214, v180
	v_sub_f32_e32 v180, v192, v178
	v_add_f32_e32 v217, v213, v223
	v_mul_f32_e32 v178, 0x3e38aa3b, v180
	v_pk_add_f32 v[180:181], v[216:217], v[214:215]
	v_exp_f32_e32 v222, v178
	v_pk_add_f32 v[218:219], v[180:181], v[180:181] op_sel_hi:[0,1]
	v_fmamk_f32 v180, v28, 0x3e38aa3b, v195
	v_exp_f32_e32 v215, v180
	v_fmamk_f32 v180, v12, 0x3e38aa3b, v195
	v_exp_f32_e32 v227, v180
	v_fmamk_f32 v180, v29, 0x3e38aa3b, v195
	v_exp_f32_e32 v220, v180
	v_fmamk_f32 v180, v30, 0x3e38aa3b, v195
	v_exp_f32_e32 v225, v180
	v_fmamk_f32 v180, v31, 0x3e38aa3b, v195
	v_exp_f32_e32 v224, v180
	v_pk_mul_f32 v[34:35], v[34:35], v[222:223] op_sel_hi:[1,0]
	v_pk_mul_f32 v[50:51], v[50:51], v[222:223] op_sel_hi:[1,0]
	v_pk_mul_f32 v[36:37], v[36:37], v[222:223] op_sel_hi:[1,0]
	v_pk_mul_f32 v[38:39], v[38:39], v[222:223] op_sel_hi:[1,0]
	v_pk_mul_f32 v[40:41], v[40:41], v[222:223] op_sel_hi:[1,0]
	v_pk_mul_f32 v[42:43], v[42:43], v[222:223] op_sel_hi:[1,0]
	v_pk_mul_f32 v[44:45], v[44:45], v[222:223] op_sel_hi:[1,0]
	v_pk_mul_f32 v[46:47], v[46:47], v[222:223] op_sel_hi:[1,0]
	v_pk_mul_f32 v[48:49], v[48:49], v[222:223] op_sel_hi:[1,0]
	v_pk_mul_f32 v[52:53], v[52:53], v[222:223] op_sel_hi:[1,0]
	v_pk_mul_f32 v[54:55], v[54:55], v[222:223] op_sel_hi:[1,0]
	v_pk_mul_f32 v[56:57], v[56:57], v[222:223] op_sel_hi:[1,0]
	v_pk_mul_f32 v[58:59], v[58:59], v[222:223] op_sel_hi:[1,0]
	v_pk_mul_f32 v[60:61], v[60:61], v[222:223] op_sel_hi:[1,0]
	v_pk_mul_f32 v[62:63], v[62:63], v[222:223] op_sel_hi:[1,0]
	v_pk_mul_f32 v[64:65], v[64:65], v[222:223] op_sel_hi:[1,0]
	s_waitcnt vmcnt(15)
	v_mfma_f32_32x32x16_bf16 v[34:49], v[142:145], v[206:209], v[34:49]
	v_fmamk_f32 v217, v32, 0x3e38aa3b, v195
	v_exp_f32_e32 v228, v217
	v_add_f32_e32 v221, v215, v227
	s_waitcnt vmcnt(14)
	v_mfma_f32_32x32x16_bf16 v[50:65], v[138:141], v[206:209], v[50:65]
	v_fmamk_f32 v206, v33, 0x3e38aa3b, v195
	v_exp_f32_e32 v226, v206
	v_cvt_pk_bf16_f32 v206, v213, v216
	v_fmamk_f32 v213, v13, 0x3e38aa3b, v195
	v_cvt_pk_bf16_f32 v207, v215, v220
	v_cvt_pk_bf16_f32 v208, v225, v224
	v_cvt_pk_bf16_f32 v209, v228, v226
	v_exp_f32_e32 v218, v213
	v_fmamk_f32 v215, v15, 0x3e38aa3b, v195
	s_waitcnt vmcnt(13)
	v_mfma_f32_32x32x16_bf16 v[34:49], v[134:137], v[206:209], v[34:49]
	v_add_f32_e64 v216, v220, v218
	v_add_f32_e64 v217, v221, v219
	v_pk_add_f32 v[216:217], v[216:217], v[216:217] op_sel_hi:[0,1]
	v_exp_f32_e32 v216, v215
	s_waitcnt vmcnt(12)
	v_mfma_f32_32x32x16_bf16 v[50:65], v[130:133], v[206:209], v[50:65]
	v_fmamk_f32 v206, v14, 0x3e38aa3b, v195
	v_exp_f32_e32 v213, v206
	v_cvt_pk_bf16_f32 v206, v197, v0
	v_cvt_pk_bf16_f32 v207, v205, v202
	v_cvt_pk_bf16_f32 v208, v203, v210
	v_cvt_pk_bf16_f32 v209, v211, v212
	v_add_f32_e32 v225, v225, v213
	v_pk_add_f32 v[202:203], v[224:225], v[216:217]
	s_waitcnt vmcnt(11)
	v_mfma_f32_32x32x16_bf16 v[34:49], v[126:129], v[206:209], v[34:49]
	v_pk_add_f32 v[202:203], v[202:203], v[202:203] op_sel_hi:[0,1]
	v_fmamk_f32 v0, v16, 0x3e38aa3b, v195
	v_fmac_f32_e32 v195, 0x3e38aa3b, v17
	v_exp_f32_e32 v0, v0
	v_exp_f32_e32 v202, v195
	s_waitcnt vmcnt(10)
	v_mfma_f32_32x32x16_bf16 v[50:65], v[122:125], v[206:209], v[50:65]
	v_cvt_pk_bf16_f32 v206, v223, v214
	v_cvt_pk_bf16_f32 v207, v227, v218
	v_cvt_pk_bf16_f32 v208, v213, v216
	v_cvt_pk_bf16_f32 v209, v0, v202
	v_add_f32_e32 v227, v228, v0
	v_pk_add_f32 v[202:203], v[226:227], v[202:203]
	s_waitcnt vmcnt(9)
	v_mfma_f32_32x32x16_bf16 v[34:49], v[118:121], v[206:209], v[34:49]
	v_add_f32_e32 v0, v202, v203
	v_fmac_f32_e32 v0, v191, v222
	s_waitcnt vmcnt(8)
	v_mfma_f32_32x32x16_bf16 v[50:65], v[114:117], v[206:209], v[50:65]
.LBB0_1532:
	s_andn2_b64 vcc, exec, s[0:1]
	s_cbranch_vccnz .LBB0_1534
	s_nop 5
	v_and_b32_e32 v180, 64, v235
	v_xor_b32_e32 v0, 32, v235
	v_add_u32_e32 v180, 64, v180
	v_cmp_lt_i32_e32 vcc, v0, v180
	s_nop 1
	v_cndmask_b32_e32 v0, v235, v0, vcc
	v_lshlrev_b32_e32 v0, 2, v0
	v_mov_b32_e32 v0, v194
	s_nop 1
	v_permlane32_swap_b32 v0, v194
	s_waitcnt lgkmcnt(0)
	v_max3_f32 v193, v192, v194, v0
	v_cmp_neq_f32_e32 vcc, s69, v193
	s_nop 1
	v_cndmask_b32_e32 v178, 0, v193, vcc
	v_mul_f32_e32 v197, 0xbe38aa3b, v178
	v_fmamk_f32 v0, v18, 0x3e38aa3b, v197
	v_fmamk_f32 v180, v2, 0x3e38aa3b, v197
	v_exp_f32_e32 v160, v0
	v_fmamk_f32 v0, v19, 0x3e38aa3b, v197
	v_exp_f32_e32 v205, v180
	v_exp_f32_e32 v152, v0
	v_fmamk_f32 v0, v3, 0x3e38aa3b, v197
	v_exp_f32_e32 v0, v0
	v_add_f32_e32 v153, v160, v205
	v_cvt_pk_bf16_f32 v206, v160, v152
	v_pk_add_f32 v[180:181], v[152:153], v[0:1]
	s_nop 0
	v_pk_add_f32 v[194:195], v[180:181], v[180:181] op_sel_hi:[0,1]
	v_fmamk_f32 v180, v20, 0x3e38aa3b, v197
	v_exp_f32_e32 v153, v180
	v_fmamk_f32 v180, v4, 0x3e38aa3b, v197
	v_exp_f32_e32 v221, v180
	v_fmamk_f32 v180, v21, 0x3e38aa3b, v197
	v_exp_f32_e32 v154, v180
	v_fmamk_f32 v180, v5, 0x3e38aa3b, v197
	v_exp_f32_e32 v194, v180
	v_add_f32_e32 v155, v153, v221
	v_cvt_pk_bf16_f32 v207, v153, v154
	v_pk_add_f32 v[180:181], v[154:155], v[194:195]
	s_nop 0
	v_pk_add_f32 v[202:203], v[180:181], v[180:181] op_sel_hi:[0,1]
	v_fmamk_f32 v180, v22, 0x3e38aa3b, v197
	v_exp_f32_e32 v155, v180
	v_fmamk_f32 v180, v6, 0x3e38aa3b, v197
	v_exp_f32_e32 v195, v180
	v_fmamk_f32 v180, v23, 0x3e38aa3b, v197
	v_exp_f32_e32 v156, v180
	v_fmamk_f32 v180, v7, 0x3e38aa3b, v197
	v_exp_f32_e32 v202, v180
	v_add_f32_e32 v157, v155, v195
	v_cvt_pk_bf16_f32 v208, v155, v156
	v_pk_add_f32 v[180:181], v[156:157], v[202:203]
	s_nop 0
	v_pk_add_f32 v[210:211], v[180:181], v[180:181] op_sel_hi:[0,1]
	v_fmamk_f32 v180, v24, 0x3e38aa3b, v197
	v_exp_f32_e32 v157, v180
	v_fmamk_f32 v180, v8, 0x3e38aa3b, v197
	v_exp_f32_e32 v203, v180
	v_fmamk_f32 v180, v25, 0x3e38aa3b, v197
	v_exp_f32_e32 v158, v180
	v_fmamk_f32 v180, v9, 0x3e38aa3b, v197
	v_exp_f32_e32 v210, v180
	v_add_f32_e32 v159, v157, v203
	v_cvt_pk_bf16_f32 v209, v157, v158
	v_pk_add_f32 v[180:181], v[158:159], v[210:211]
	s_nop 0
	v_pk_add_f32 v[212:213], v[180:181], v[180:181] op_sel_hi:[0,1]
	v_fmamk_f32 v180, v26, 0x3e38aa3b, v197
	v_exp_f32_e32 v211, v180
	v_fmamk_f32 v180, v10, 0x3e38aa3b, v197
	v_exp_f32_e32 v225, v180
	v_fmamk_f32 v180, v27, 0x3e38aa3b, v197
	v_exp_f32_e32 v214, v180
	v_fmamk_f32 v180, v11, 0x3e38aa3b, v197
	v_exp_f32_e32 v212, v180
	v_sub_f32_e32 v180, v192, v178
	v_add_f32_e32 v215, v211, v225
	v_mul_f32_e32 v178, 0x3e38aa3b, v180
	v_pk_add_f32 v[180:181], v[214:215], v[212:213]
	v_exp_f32_e32 v220, v178
	v_pk_add_f32 v[216:217], v[180:181], v[180:181] op_sel_hi:[0,1]
	v_fmamk_f32 v180, v28, 0x3e38aa3b, v197
	v_exp_f32_e32 v213, v180
	v_fmamk_f32 v180, v12, 0x3e38aa3b, v197
	v_exp_f32_e32 v226, v180
	v_fmamk_f32 v180, v29, 0x3e38aa3b, v197
	v_exp_f32_e32 v218, v180
	v_fmamk_f32 v180, v30, 0x3e38aa3b, v197
	v_exp_f32_e32 v223, v180
	v_fmamk_f32 v180, v31, 0x3e38aa3b, v197
	v_exp_f32_e32 v222, v180
	v_pk_mul_f32 v[34:35], v[34:35], v[220:221] op_sel_hi:[1,0]
	v_pk_mul_f32 v[50:51], v[50:51], v[220:221] op_sel_hi:[1,0]
	v_pk_mul_f32 v[36:37], v[36:37], v[220:221] op_sel_hi:[1,0]
	v_pk_mul_f32 v[38:39], v[38:39], v[220:221] op_sel_hi:[1,0]
	v_pk_mul_f32 v[40:41], v[40:41], v[220:221] op_sel_hi:[1,0]
	v_pk_mul_f32 v[42:43], v[42:43], v[220:221] op_sel_hi:[1,0]
	v_pk_mul_f32 v[44:45], v[44:45], v[220:221] op_sel_hi:[1,0]
	v_pk_mul_f32 v[46:47], v[46:47], v[220:221] op_sel_hi:[1,0]
	v_pk_mul_f32 v[48:49], v[48:49], v[220:221] op_sel_hi:[1,0]
	v_pk_mul_f32 v[52:53], v[52:53], v[220:221] op_sel_hi:[1,0]
	v_pk_mul_f32 v[54:55], v[54:55], v[220:221] op_sel_hi:[1,0]
	v_pk_mul_f32 v[56:57], v[56:57], v[220:221] op_sel_hi:[1,0]
	v_pk_mul_f32 v[58:59], v[58:59], v[220:221] op_sel_hi:[1,0]
	v_pk_mul_f32 v[60:61], v[60:61], v[220:221] op_sel_hi:[1,0]
	v_pk_mul_f32 v[62:63], v[62:63], v[220:221] op_sel_hi:[1,0]
	v_pk_mul_f32 v[64:65], v[64:65], v[220:221] op_sel_hi:[1,0]
	s_waitcnt vmcnt(15)
	v_mfma_f32_32x32x16_bf16 v[34:49], v[142:145], v[206:209], v[34:49]
	v_fmamk_f32 v215, v32, 0x3e38aa3b, v197
	v_exp_f32_e32 v227, v215
	v_add_f32_e32 v219, v213, v226
	s_waitcnt vmcnt(14)
	v_mfma_f32_32x32x16_bf16 v[50:65], v[138:141], v[206:209], v[50:65]
	v_fmamk_f32 v206, v33, 0x3e38aa3b, v197
	v_exp_f32_e32 v224, v206
	v_cvt_pk_bf16_f32 v206, v211, v214
	v_fmamk_f32 v211, v13, 0x3e38aa3b, v197
	v_cvt_pk_bf16_f32 v207, v213, v218
	v_cvt_pk_bf16_f32 v208, v223, v222
	v_cvt_pk_bf16_f32 v209, v227, v224
	v_exp_f32_e32 v216, v211
	v_fmamk_f32 v213, v15, 0x3e38aa3b, v197
	s_waitcnt vmcnt(13)
	v_mfma_f32_32x32x16_bf16 v[34:49], v[134:137], v[206:209], v[34:49]
	v_add_f32_e64 v214, v218, v216
	v_add_f32_e64 v215, v219, v217
	v_pk_add_f32 v[214:215], v[214:215], v[214:215] op_sel_hi:[0,1]
	v_exp_f32_e32 v214, v213
	s_waitcnt vmcnt(12)
	v_mfma_f32_32x32x16_bf16 v[50:65], v[130:133], v[206:209], v[50:65]
	v_fmamk_f32 v206, v14, 0x3e38aa3b, v197
	v_exp_f32_e32 v211, v206
	v_cvt_pk_bf16_f32 v206, v205, v0
	v_cvt_pk_bf16_f32 v207, v221, v194
	v_cvt_pk_bf16_f32 v208, v195, v202
	v_cvt_pk_bf16_f32 v209, v203, v210
	v_add_f32_e32 v223, v223, v211
	v_pk_add_f32 v[194:195], v[222:223], v[214:215]
	s_waitcnt vmcnt(11)
	v_mfma_f32_32x32x16_bf16 v[34:49], v[126:129], v[206:209], v[34:49]
	v_pk_add_f32 v[194:195], v[194:195], v[194:195] op_sel_hi:[0,1]
	v_fmamk_f32 v0, v16, 0x3e38aa3b, v197
	v_fmac_f32_e32 v197, 0x3e38aa3b, v17
	v_exp_f32_e32 v0, v0
	v_exp_f32_e32 v194, v197
	s_waitcnt vmcnt(10)
	v_mfma_f32_32x32x16_bf16 v[50:65], v[122:125], v[206:209], v[50:65]
	v_cvt_pk_bf16_f32 v206, v225, v212
	v_cvt_pk_bf16_f32 v207, v226, v216
	v_cvt_pk_bf16_f32 v208, v211, v214
	v_cvt_pk_bf16_f32 v209, v0, v194
	v_add_f32_e32 v225, v227, v0
	v_pk_add_f32 v[194:195], v[224:225], v[194:195]
	s_waitcnt vmcnt(9)
	v_mfma_f32_32x32x16_bf16 v[34:49], v[118:121], v[206:209], v[34:49]
	v_add_f32_e32 v0, v194, v195
	v_fmac_f32_e32 v0, v191, v220
	s_waitcnt vmcnt(8)
	v_mfma_f32_32x32x16_bf16 v[50:65], v[114:117], v[206:209], v[50:65]

.LBB0_1537:
	v_add_u32_e32 v0, s4, v186
	v_cmp_le_i32_e32 vcc, v0, v190
	v_cmp_le_i32_e64 s[0:1], v0, v187
	s_and_b64 vcc, s[8:9], vcc
	v_cndmask_b32_e32 v18, v239, v18, vcc
	s_and_b64 vcc, s[8:9], s[0:1]
	v_cndmask_b32_e32 v2, v239, v2, vcc
	v_cmp_lt_i32_e32 vcc, v0, v190
	v_cmp_lt_i32_e64 s[0:1], v0, v187
	s_and_b64 vcc, s[8:9], vcc
	v_cndmask_b32_e32 v19, v239, v19, vcc
	s_and_b64 vcc, s[8:9], s[0:1]
	v_or_b32_e32 v180, 2, v0
	v_cndmask_b32_e32 v3, v239, v3, vcc
	v_cmp_le_i32_e32 vcc, v180, v190
	v_cmp_le_i32_e64 s[0:1], v180, v187
	s_and_b64 vcc, s[8:9], vcc
	v_cndmask_b32_e32 v20, v239, v20, vcc
	s_and_b64 vcc, s[8:9], s[0:1]
	v_cndmask_b32_e32 v180, v239, v4, vcc
	v_or_b32_e32 v4, 3, v0
	v_cmp_le_i32_e32 vcc, v4, v190
	v_cmp_le_i32_e64 s[0:1], v4, v187
	s_and_b64 vcc, s[8:9], vcc
	v_cndmask_b32_e32 v21, v239, v21, vcc
	s_and_b64 vcc, s[8:9], s[0:1]
	v_add_u32_e32 v4, 8, v0
	v_cndmask_b32_e32 v181, v239, v5, vcc
	v_cmp_le_i32_e32 vcc, v4, v190
	v_cmp_le_i32_e64 s[0:1], v4, v187
	s_and_b64 vcc, s[8:9], vcc
	v_cndmask_b32_e32 v22, v239, v22, vcc
	s_and_b64 vcc, s[8:9], s[0:1]
	v_add_u32_e32 v4, 9, v0
	v_cndmask_b32_e32 v178, v239, v6, vcc
	v_cmp_le_i32_e32 vcc, v4, v190
	v_cmp_le_i32_e64 s[0:1], v4, v187
	s_and_b64 vcc, s[8:9], vcc
	v_cndmask_b32_e32 v23, v239, v23, vcc
	s_and_b64 vcc, s[8:9], s[0:1]
	v_add_u32_e32 v4, 10, v0
	v_cndmask_b32_e32 v179, v239, v7, vcc
	v_cmp_le_i32_e32 vcc, v4, v190
	v_cmp_le_i32_e64 s[0:1], v4, v187
	s_and_b64 vcc, s[8:9], vcc
	v_cndmask_b32_e32 v24, v239, v24, vcc
	s_and_b64 vcc, s[8:9], s[0:1]
	v_add_u32_e32 v4, 11, v0
	v_cndmask_b32_e32 v176, v239, v8, vcc
	v_cmp_le_i32_e32 vcc, v4, v190
	v_cmp_le_i32_e64 s[0:1], v4, v187
	s_and_b64 vcc, s[8:9], vcc
	v_cndmask_b32_e32 v25, v239, v25, vcc
	s_and_b64 vcc, s[8:9], s[0:1]
	v_add_u32_e32 v4, 16, v0
	v_cndmask_b32_e32 v177, v239, v9, vcc
	v_cmp_le_i32_e32 vcc, v4, v190
	v_cmp_le_i32_e64 s[0:1], v4, v187
	s_and_b64 vcc, s[8:9], vcc
	v_cndmask_b32_e32 v26, v239, v26, vcc
	s_and_b64 vcc, s[8:9], s[0:1]
	v_add_u32_e32 v4, 17, v0
	v_cndmask_b32_e32 v174, v239, v10, vcc
	v_cmp_le_i32_e32 vcc, v4, v190
	v_cmp_le_i32_e64 s[0:1], v4, v187
	s_and_b64 vcc, s[8:9], vcc
	v_cndmask_b32_e32 v27, v239, v27, vcc
	s_and_b64 vcc, s[8:9], s[0:1]
	v_add_u32_e32 v4, 18, v0
	v_cndmask_b32_e32 v175, v239, v11, vcc
	v_cmp_le_i32_e32 vcc, v4, v190
	v_cmp_le_i32_e64 s[0:1], v4, v187
	s_and_b64 vcc, s[8:9], vcc
	v_cndmask_b32_e32 v28, v239, v28, vcc
	s_and_b64 vcc, s[8:9], s[0:1]
	v_add_u32_e32 v4, 19, v0
	v_cndmask_b32_e32 v172, v239, v12, vcc
	v_cmp_le_i32_e32 vcc, v4, v190
	v_cmp_le_i32_e64 s[0:1], v4, v187
	s_and_b64 vcc, s[8:9], vcc
	v_cndmask_b32_e32 v29, v239, v29, vcc
	s_and_b64 vcc, s[8:9], s[0:1]
	v_add_u32_e32 v4, 24, v0
	v_cndmask_b32_e32 v194, v239, v13, vcc
	v_cmp_le_i32_e32 vcc, v4, v190
	v_cmp_le_i32_e64 s[0:1], v4, v187
	s_and_b64 vcc, s[8:9], vcc
	v_cndmask_b32_e32 v30, v239, v30, vcc
	s_and_b64 vcc, s[8:9], s[0:1]
	v_add_u32_e32 v4, 25, v0
	v_cndmask_b32_e32 v195, v239, v14, vcc
	v_cmp_le_i32_e32 vcc, v4, v190
	v_cmp_le_i32_e64 s[0:1], v4, v187
	s_and_b64 vcc, s[8:9], vcc
	v_cndmask_b32_e32 v31, v239, v31, vcc
	s_and_b64 vcc, s[8:9], s[0:1]
	v_add_u32_e32 v4, 26, v0
	v_cndmask_b32_e32 v197, v239, v15, vcc
	v_cmp_le_i32_e32 vcc, v4, v190
	v_cmp_le_i32_e64 s[0:1], v4, v187
	s_and_b64 vcc, s[8:9], vcc
	v_cndmask_b32_e32 v32, v239, v32, vcc
	s_and_b64 vcc, s[8:9], s[0:1]
	v_add_u32_e32 v0, 27, v0
	v_cndmask_b32_e32 v202, v239, v16, vcc
	v_cmp_le_i32_e32 vcc, v0, v190
	v_cmp_le_i32_e64 s[0:1], v0, v187
	v_max_i32_e32 v0, v20, v180
	v_max3_i32 v0, v18, v2, v0
	v_max_i32_e32 v4, v21, v181
	v_max_i32_e32 v5, v22, v178
	v_max_i32_e32 v7, v24, v176
	v_max3_i32 v4, v19, v3, v4
	v_max_i32_e32 v6, v23, v179
	v_max3_i32 v0, v0, v5, v7
	v_max_i32_e32 v5, v25, v177
	s_and_b64 vcc, s[8:9], vcc
	v_max3_i32 v4, v4, v6, v5
	v_max_i32_e32 v5, v26, v174
	v_max_i32_e32 v7, v28, v172
	v_cndmask_b32_e32 v33, v239, v33, vcc
	s_and_b64 vcc, s[8:9], s[0:1]
	v_max_i32_e32 v6, v27, v175
	v_max3_i32 v0, v0, v5, v7
	v_max_i32_e32 v5, v29, v194
	v_cndmask_b32_e32 v203, v239, v17, vcc
	v_max3_i32 v4, v4, v6, v5
	v_max_i32_e32 v5, v30, v195
	v_max_i32_e32 v7, v32, v202
	v_max_i32_e32 v6, v31, v197
	v_max3_i32 v0, v0, v5, v7
	v_max_i32_e32 v5, v33, v203
	v_max3_i32 v4, v4, v6, v5
	v_and_b32_e32 v5, 64, v235
	v_max3_i32 v0, v0, v4, 0
	v_xor_b32_e32 v4, 32, v235
	v_add_u32_e32 v5, 64, v5
	v_cmp_lt_i32_e32 vcc, v4, v5
	s_nop 1
	v_cndmask_b32_e32 v4, v235, v4, vcc
	v_lshlrev_b32_e32 v4, 2, v4
	v_mov_b32_e32 v4, v0
	s_nop 1
	v_permlane32_swap_b32 v4, v0
	s_waitcnt lgkmcnt(0)
	v_max3_f32 v193, v192, v0, v4
	v_cmp_neq_f32_e32 vcc, s69, v193
	s_nop 1
	v_cndmask_b32_e32 v173, 0, v193, vcc
	v_mul_f32_e32 v205, 0xbe38aa3b, v173
	v_fmamk_f32 v0, v18, 0x3e38aa3b, v205
	v_exp_f32_e32 v152, v0
	v_fmamk_f32 v0, v2, 0x3e38aa3b, v205
	v_exp_f32_e32 v206, v0
	v_fmamk_f32 v0, v19, 0x3e38aa3b, v205
	v_exp_f32_e32 v2, v0
	v_fmamk_f32 v0, v3, 0x3e38aa3b, v205
	v_exp_f32_e32 v0, v0
	v_add_f32_e32 v3, v152, v206
	v_pk_add_f32 v[4:5], v[2:3], v[0:1]
	s_nop 0
	v_pk_add_f32 v[6:7], v[4:5], v[4:5] op_sel_hi:[0,1]
	v_fmamk_f32 v3, v20, 0x3e38aa3b, v205
	v_fmamk_f32 v4, v180, 0x3e38aa3b, v205
	v_exp_f32_e32 v3, v3
	v_exp_f32_e32 v207, v4
	v_fmamk_f32 v4, v21, 0x3e38aa3b, v205
	v_fmamk_f32 v5, v181, 0x3e38aa3b, v205
	v_exp_f32_e32 v4, v4
	v_exp_f32_e32 v6, v5
	v_add_f32_e32 v5, v3, v207
	v_cvt_pk_bf16_f32 v2, v152, v2
	v_cvt_pk_bf16_f32 v3, v3, v4
	v_pk_add_f32 v[8:9], v[4:5], v[6:7]
	v_fmamk_f32 v5, v22, 0x3e38aa3b, v205
	v_pk_add_f32 v[8:9], v[8:9], v[8:9] op_sel_hi:[0,1]
	v_fmamk_f32 v7, v178, 0x3e38aa3b, v205
	v_fmamk_f32 v8, v23, 0x3e38aa3b, v205
	v_exp_f32_e32 v5, v5
	v_exp_f32_e32 v7, v7
	v_exp_f32_e32 v10, v8
	v_fmamk_f32 v8, v179, 0x3e38aa3b, v205
	v_exp_f32_e32 v8, v8
	v_add_f32_e32 v11, v5, v7
	v_cvt_pk_bf16_f32 v4, v5, v10
	v_pk_add_f32 v[12:13], v[10:11], v[8:9]
	s_nop 0
	v_pk_add_f32 v[12:13], v[12:13], v[12:13] op_sel_hi:[0,1]
	v_fmamk_f32 v9, v24, 0x3e38aa3b, v205
	v_fmamk_f32 v11, v176, 0x3e38aa3b, v205
	v_fmamk_f32 v12, v25, 0x3e38aa3b, v205
	v_exp_f32_e32 v9, v9
	v_exp_f32_e32 v11, v11
	v_exp_f32_e32 v14, v12
	v_fmamk_f32 v12, v177, 0x3e38aa3b, v205
	v_exp_f32_e32 v12, v12
	v_add_f32_e32 v15, v9, v11
	v_cvt_pk_bf16_f32 v5, v9, v14
	v_pk_add_f32 v[16:17], v[14:15], v[12:13]
	v_fmamk_f32 v15, v174, 0x3e38aa3b, v205
	v_exp_f32_e32 v25, v15
	v_fmamk_f32 v15, v27, 0x3e38aa3b, v205
	v_pk_add_f32 v[16:17], v[16:17], v[16:17] op_sel_hi:[0,1]
	v_exp_f32_e32 v18, v15
	v_fmamk_f32 v15, v175, 0x3e38aa3b, v205
	v_fmamk_f32 v13, v26, 0x3e38aa3b, v205
	v_exp_f32_e32 v16, v15
	v_sub_f32_e32 v15, v192, v173
	v_exp_f32_e32 v13, v13
	v_mul_f32_e32 v15, 0x3e38aa3b, v15
	v_exp_f32_e32 v24, v15
	v_fmamk_f32 v15, v31, 0x3e38aa3b, v205
	v_add_f32_e32 v19, v13, v25
	v_pk_add_f32 v[20:21], v[18:19], v[16:17]
	v_fmamk_f32 v19, v172, 0x3e38aa3b, v205
	v_pk_mul_f32 v[34:35], v[34:35], v[24:25] op_sel_hi:[1,0]
	v_pk_mul_f32 v[50:51], v[50:51], v[24:25] op_sel_hi:[1,0]
	v_pk_mul_f32 v[36:37], v[36:37], v[24:25] op_sel_hi:[1,0]
	v_pk_mul_f32 v[38:39], v[38:39], v[24:25] op_sel_hi:[1,0]
	v_pk_mul_f32 v[40:41], v[40:41], v[24:25] op_sel_hi:[1,0]
	v_pk_mul_f32 v[42:43], v[42:43], v[24:25] op_sel_hi:[1,0]
	v_pk_mul_f32 v[44:45], v[44:45], v[24:25] op_sel_hi:[1,0]
	v_pk_mul_f32 v[46:47], v[46:47], v[24:25] op_sel_hi:[1,0]
	v_pk_mul_f32 v[48:49], v[48:49], v[24:25] op_sel_hi:[1,0]
	v_pk_mul_f32 v[52:53], v[52:53], v[24:25] op_sel_hi:[1,0]
	v_pk_mul_f32 v[54:55], v[54:55], v[24:25] op_sel_hi:[1,0]
	v_pk_mul_f32 v[56:57], v[56:57], v[24:25] op_sel_hi:[1,0]
	v_pk_mul_f32 v[58:59], v[58:59], v[24:25] op_sel_hi:[1,0]
	v_pk_mul_f32 v[60:61], v[60:61], v[24:25] op_sel_hi:[1,0]
	v_pk_mul_f32 v[62:63], v[62:63], v[24:25] op_sel_hi:[1,0]
	v_pk_mul_f32 v[64:65], v[64:65], v[24:25] op_sel_hi:[1,0]
	v_pk_add_f32 v[20:21], v[20:21], v[20:21] op_sel_hi:[0,1]
	s_waitcnt vmcnt(15)
	v_mfma_f32_32x32x16_bf16 v[34:49], v[142:145], v[2:5], v[34:49]
	v_fmamk_f32 v20, v29, 0x3e38aa3b, v205
	v_fmamk_f32 v17, v28, 0x3e38aa3b, v205
	v_exp_f32_e32 v22, v20
	v_fmamk_f32 v20, v30, 0x3e38aa3b, v205
	v_exp_f32_e32 v26, v15
	v_fmamk_f32 v15, v32, 0x3e38aa3b, v205
	v_exp_f32_e32 v17, v17
	s_waitcnt vmcnt(14)
	v_mfma_f32_32x32x16_bf16 v[50:65], v[138:141], v[2:5], v[50:65]
	v_fmamk_f32 v2, v33, 0x3e38aa3b, v205
	v_exp_f32_e32 v27, v20
	v_exp_f32_e32 v9, v15
	v_exp_f32_e32 v10, v2
	v_exp_f32_e32 v19, v19
	v_cvt_pk_bf16_f32 v2, v13, v18
	v_fmamk_f32 v13, v194, 0x3e38aa3b, v205
	v_exp_f32_e32 v20, v13
	v_cvt_pk_bf16_f32 v3, v17, v22
	v_cvt_pk_bf16_f32 v4, v27, v26
	v_cvt_pk_bf16_f32 v5, v9, v10
	v_add_f32_e32 v23, v17, v19
	v_pk_add_f32 v[14:15], v[22:23], v[20:21]
	s_waitcnt vmcnt(13)
	v_mfma_f32_32x32x16_bf16 v[34:49], v[134:137], v[2:5], v[34:49]
	v_pk_add_f32 v[14:15], v[14:15], v[14:15] op_sel_hi:[0,1]
	v_fmamk_f32 v14, v197, 0x3e38aa3b, v205
	v_exp_f32_e32 v14, v14
	s_waitcnt vmcnt(12)
	v_mfma_f32_32x32x16_bf16 v[50:65], v[130:133], v[2:5], v[50:65]
	v_fmamk_f32 v2, v195, 0x3e38aa3b, v205
	v_exp_f32_e32 v13, v2
	v_cvt_pk_bf16_f32 v2, v206, v0
	v_cvt_pk_bf16_f32 v3, v207, v6
	v_cvt_pk_bf16_f32 v4, v7, v8
	v_cvt_pk_bf16_f32 v5, v11, v12
	v_add_f32_e32 v27, v27, v13
	v_pk_add_f32 v[6:7], v[26:27], v[14:15]
	s_waitcnt vmcnt(11)
	v_mfma_f32_32x32x16_bf16 v[34:49], v[126:129], v[2:5], v[34:49]
	v_pk_add_f32 v[6:7], v[6:7], v[6:7] op_sel_hi:[0,1]
	v_fmamk_f32 v0, v202, 0x3e38aa3b, v205
	v_fmac_f32_e32 v205, 0x3e38aa3b, v203
	v_exp_f32_e32 v0, v0
	v_exp_f32_e32 v6, v205
	v_add_f32_e32 v11, v9, v0
	s_waitcnt vmcnt(10)
	v_mfma_f32_32x32x16_bf16 v[50:65], v[122:125], v[2:5], v[50:65]
	v_cvt_pk_bf16_f32 v2, v25, v16
	v_cvt_pk_bf16_f32 v3, v19, v20
	v_cvt_pk_bf16_f32 v4, v13, v14
	v_cvt_pk_bf16_f32 v5, v0, v6
	v_add_f32_e64 v6, v10, v6
	v_add_f32_e64 v7, v11, v7
	v_add_f32_e32 v0, v6, v7
	s_waitcnt vmcnt(9)
	v_mfma_f32_32x32x16_bf16 v[34:49], v[118:121], v[2:5], v[34:49]
	v_fmac_f32_e32 v0, v191, v24
	s_waitcnt vmcnt(8)
	v_mfma_f32_32x32x16_bf16 v[50:65], v[114:117], v[2:5], v[50:65]
	s_xor_b64 s[0:1], s[22:23], -1
	s_andn2_b64 vcc, exec, s[0:1]
	s_cbranch_vccz .LBB0_1540

.LBB0_1540:
	v_and_b32_e32 v3, 64, v235
	v_xor_b32_e32 v2, 32, v235
	v_add_u32_e32 v3, 64, v3
	v_cmp_lt_i32_e32 vcc, v2, v3
	s_mov_b32 s19, s37
	s_nop 0
	v_cndmask_b32_e32 v2, v235, v2, vcc
	v_lshlrev_b32_e32 v2, 2, v2
	v_mov_b32_e32 v2, v0
	s_nop 1
	v_permlane32_swap_b32 v2, v0
	s_waitcnt lgkmcnt(0)
	v_add_f32_e32 v0, v0, v2
	v_max_f32_e32 v0, 0xda24260, v0
	v_div_scale_f32 v2, s[0:1], v0, v0, 1.0
	v_rcp_f32_e32 v3, v2
	v_div_scale_f32 v4, vcc, 1.0, v0, 1.0
	v_readlane_b32 s0, v254, 41
	v_fma_f32 v5, -v2, v3, 1.0
	v_fmac_f32_e32 v3, v5, v3
	v_mul_f32_e32 v5, v4, v3
	v_fma_f32 v6, -v2, v5, v4
	v_fmac_f32_e32 v5, v6, v3
	v_fma_f32 v2, -v2, v5, v4
	v_div_fmas_f32 v2, v2, v3, v5
	v_div_fixup_f32 v0, v2, v0, 1.0
	v_pk_mul_f32 v[4:5], v[34:35], v[0:1] op_sel_hi:[1,0]
	v_pk_mul_f32 v[2:3], v[50:51], v[0:1] op_sel_hi:[1,0]
	v_pk_mul_f32 v[8:9], v[36:37], v[0:1] op_sel_hi:[1,0]
	v_pk_mul_f32 v[6:7], v[52:53], v[0:1] op_sel_hi:[1,0]
	v_pk_mul_f32 v[12:13], v[38:39], v[0:1] op_sel_hi:[1,0]
	v_pk_mul_f32 v[10:11], v[54:55], v[0:1] op_sel_hi:[1,0]
	v_pk_mul_f32 v[18:19], v[40:41], v[0:1] op_sel_hi:[1,0]
	v_pk_mul_f32 v[14:15], v[56:57], v[0:1] op_sel_hi:[1,0]
	v_pk_mul_f32 v[20:21], v[42:43], v[0:1] op_sel_hi:[1,0]
	v_pk_mul_f32 v[16:17], v[58:59], v[0:1] op_sel_hi:[1,0]
	v_pk_mul_f32 v[24:25], v[44:45], v[0:1] op_sel_hi:[1,0]
	v_pk_mul_f32 v[22:23], v[60:61], v[0:1] op_sel_hi:[1,0]
	v_pk_mul_f32 v[28:29], v[46:47], v[0:1] op_sel_hi:[1,0]
	v_pk_mul_f32 v[26:27], v[62:63], v[0:1] op_sel_hi:[1,0]
	v_pk_mul_f32 v[32:33], v[48:49], v[0:1] op_sel_hi:[1,0]
	v_pk_mul_f32 v[30:31], v[64:65], v[0:1] op_sel_hi:[1,0]
	v_lshlrev_b32_e32 v0, 11, v184
	v_readlane_b32 s1, v254, 42
	s_nop 1
	v_lshl_add_u64 v[34:35], s[0:1], 0, v[0:1]
	v_lshl_add_u64 v[34:35], v[34:35], 0, s[18:19]
	s_mov_b64 s[0:1], 0xb400600
	v_lshl_add_u64 v[34:35], v[34:35], 0, s[0:1]
	s_mov_b64 s[0:1], 0

.LBB0_1556:
	s_or_b32 s1, s4, 63
	s_cmp_gt_i32 s1, s41
	s_mov_b64 s[18:19], -1
	s_cbranch_scc1 .LBB0_1559
	s_nop 6
	v_max_i32_e32 v0, v34, v50
	v_max3_i32 v0, v32, v48, v0
	v_max_i32_e32 v184, v35, v51
	v_max_i32_e32 v185, v36, v52
	v_max_i32_e32 v183, v38, v54
	v_max3_i32 v184, v33, v49, v184
	v_max_i32_e32 v182, v37, v53
	v_max3_i32 v0, v0, v185, v183
	v_max_i32_e32 v185, v39, v55
	v_max3_i32 v184, v184, v182, v185
	v_max_i32_e32 v185, v40, v56
	v_max_i32_e32 v183, v42, v58
	v_max_i32_e32 v182, v41, v57
	v_max3_i32 v0, v0, v185, v183
	v_max_i32_e32 v185, v43, v59
	v_max3_i32 v184, v184, v182, v185
	v_max_i32_e32 v185, v44, v60
	v_max_i32_e32 v183, v46, v62
	v_max_i32_e32 v182, v45, v61
	v_max3_i32 v0, v0, v185, v183
	v_max_i32_e32 v185, v47, v63
	v_max3_i32 v184, v184, v182, v185
	v_and_b32_e32 v185, 64, v235
	v_max3_i32 v0, v0, v184, 0
	v_xor_b32_e32 v184, 32, v235
	v_add_u32_e32 v185, 64, v185
	v_cmp_lt_i32_e32 vcc, v184, v185
	s_nop 1
	v_cndmask_b32_e32 v184, v235, v184, vcc
	v_lshlrev_b32_e32 v184, 2, v184
	v_mov_b32_e32 v184, v0
	s_nop 1
	v_permlane32_swap_b32 v184, v0
	s_waitcnt lgkmcnt(0)
	v_max3_f32 v192, v191, v0, v184
	v_cmp_neq_f32_e32 vcc, s69, v192
	s_nop 1
	v_cndmask_b32_e32 v182, 0, v192, vcc
	v_mul_f32_e32 v193, 0xbe38aa3b, v182
	v_fmamk_f32 v0, v32, 0x3e38aa3b, v193
	v_exp_f32_e32 v164, v0
	v_fmamk_f32 v0, v48, 0x3e38aa3b, v193
	v_exp_f32_e32 v197, v0
	v_fmamk_f32 v0, v33, 0x3e38aa3b, v193
	v_exp_f32_e32 v156, v0
	v_fmamk_f32 v0, v49, 0x3e38aa3b, v193
	v_exp_f32_e32 v0, v0
	v_add_f32_e32 v157, v164, v197
	v_cvt_pk_bf16_f32 v206, v164, v156
	v_pk_add_f32 v[184:185], v[156:157], v[0:1]
	s_nop 0
	v_pk_add_f32 v[194:195], v[184:185], v[184:185] op_sel_hi:[0,1]
	v_fmamk_f32 v184, v34, 0x3e38aa3b, v193
	v_exp_f32_e32 v157, v184
	v_fmamk_f32 v184, v50, 0x3e38aa3b, v193
	v_exp_f32_e32 v205, v184
	v_fmamk_f32 v184, v35, 0x3e38aa3b, v193
	v_exp_f32_e32 v158, v184
	v_fmamk_f32 v184, v51, 0x3e38aa3b, v193
	v_exp_f32_e32 v194, v184
	v_add_f32_e32 v159, v157, v205
	v_cvt_pk_bf16_f32 v207, v157, v158
	v_pk_add_f32 v[184:185], v[158:159], v[194:195]
	s_nop 0
	v_pk_add_f32 v[202:203], v[184:185], v[184:185] op_sel_hi:[0,1]
	v_fmamk_f32 v184, v36, 0x3e38aa3b, v193
	v_exp_f32_e32 v159, v184
	v_fmamk_f32 v184, v52, 0x3e38aa3b, v193
	v_exp_f32_e32 v195, v184
	v_fmamk_f32 v184, v37, 0x3e38aa3b, v193
	v_exp_f32_e32 v160, v184
	v_fmamk_f32 v184, v53, 0x3e38aa3b, v193
	v_exp_f32_e32 v202, v184
	v_add_f32_e32 v161, v159, v195
	v_cvt_pk_bf16_f32 v208, v159, v160
	v_pk_add_f32 v[184:185], v[160:161], v[202:203]
	s_nop 0
	v_pk_add_f32 v[210:211], v[184:185], v[184:185] op_sel_hi:[0,1]
	v_fmamk_f32 v184, v38, 0x3e38aa3b, v193
	v_exp_f32_e32 v161, v184
	v_fmamk_f32 v184, v54, 0x3e38aa3b, v193
	v_exp_f32_e32 v203, v184
	v_fmamk_f32 v184, v39, 0x3e38aa3b, v193
	v_exp_f32_e32 v162, v184
	v_fmamk_f32 v184, v55, 0x3e38aa3b, v193
	v_exp_f32_e32 v210, v184
	v_add_f32_e32 v163, v161, v203
	v_cvt_pk_bf16_f32 v209, v161, v162
	v_pk_add_f32 v[184:185], v[162:163], v[210:211]
	s_nop 0
	v_pk_add_f32 v[212:213], v[184:185], v[184:185] op_sel_hi:[0,1]
	v_fmamk_f32 v184, v40, 0x3e38aa3b, v193
	v_exp_f32_e32 v211, v184
	v_fmamk_f32 v184, v56, 0x3e38aa3b, v193
	v_exp_f32_e32 v221, v184
	v_fmamk_f32 v184, v41, 0x3e38aa3b, v193
	v_exp_f32_e32 v214, v184
	v_fmamk_f32 v184, v57, 0x3e38aa3b, v193
	v_exp_f32_e32 v212, v184
	v_sub_f32_e32 v184, v191, v182
	v_add_f32_e32 v215, v211, v221
	v_mul_f32_e32 v182, 0x3e38aa3b, v184
	v_pk_add_f32 v[184:185], v[214:215], v[212:213]
	v_exp_f32_e32 v220, v182
	v_pk_add_f32 v[216:217], v[184:185], v[184:185] op_sel_hi:[0,1]
	v_fmamk_f32 v184, v42, 0x3e38aa3b, v193
	v_exp_f32_e32 v213, v184
	v_fmamk_f32 v184, v58, 0x3e38aa3b, v193
	v_exp_f32_e32 v225, v184
	v_fmamk_f32 v184, v43, 0x3e38aa3b, v193
	v_exp_f32_e32 v218, v184
	v_fmamk_f32 v184, v44, 0x3e38aa3b, v193
	v_exp_f32_e32 v223, v184
	v_fmamk_f32 v184, v45, 0x3e38aa3b, v193
	v_exp_f32_e32 v222, v184
	v_pk_mul_f32 v[16:17], v[16:17], v[220:221] op_sel_hi:[1,0]
	v_pk_mul_f32 v[64:65], v[64:65], v[220:221] op_sel_hi:[1,0]
	v_pk_mul_f32 v[18:19], v[18:19], v[220:221] op_sel_hi:[1,0]
	v_pk_mul_f32 v[20:21], v[20:21], v[220:221] op_sel_hi:[1,0]
	v_pk_mul_f32 v[22:23], v[22:23], v[220:221] op_sel_hi:[1,0]
	v_pk_mul_f32 v[24:25], v[24:25], v[220:221] op_sel_hi:[1,0]
	v_pk_mul_f32 v[26:27], v[26:27], v[220:221] op_sel_hi:[1,0]
	v_pk_mul_f32 v[28:29], v[28:29], v[220:221] op_sel_hi:[1,0]
	v_pk_mul_f32 v[30:31], v[30:31], v[220:221] op_sel_hi:[1,0]
	v_pk_mul_f32 v[66:67], v[66:67], v[220:221] op_sel_hi:[1,0]
	v_pk_mul_f32 v[68:69], v[68:69], v[220:221] op_sel_hi:[1,0]
	v_pk_mul_f32 v[70:71], v[70:71], v[220:221] op_sel_hi:[1,0]
	v_pk_mul_f32 v[72:73], v[72:73], v[220:221] op_sel_hi:[1,0]
	v_pk_mul_f32 v[74:75], v[74:75], v[220:221] op_sel_hi:[1,0]
	v_pk_mul_f32 v[76:77], v[76:77], v[220:221] op_sel_hi:[1,0]
	v_pk_mul_f32 v[78:79], v[78:79], v[220:221] op_sel_hi:[1,0]
	s_waitcnt vmcnt(15)
	v_mfma_f32_32x32x16_bf16 v[16:31], v[144:147], v[206:209], v[16:31]
	v_fmamk_f32 v215, v46, 0x3e38aa3b, v193
	v_exp_f32_e32 v226, v215
	v_add_f32_e32 v219, v213, v225
	s_waitcnt vmcnt(14)
	v_mfma_f32_32x32x16_bf16 v[64:79], v[140:143], v[206:209], v[64:79]
	v_fmamk_f32 v206, v47, 0x3e38aa3b, v193
	v_exp_f32_e32 v224, v206
	v_cvt_pk_bf16_f32 v206, v211, v214
	v_fmamk_f32 v211, v59, 0x3e38aa3b, v193
	v_cvt_pk_bf16_f32 v207, v213, v218
	v_cvt_pk_bf16_f32 v208, v223, v222
	v_cvt_pk_bf16_f32 v209, v226, v224
	v_exp_f32_e32 v216, v211
	v_fmamk_f32 v213, v61, 0x3e38aa3b, v193
	s_waitcnt vmcnt(13)
	v_mfma_f32_32x32x16_bf16 v[16:31], v[136:139], v[206:209], v[16:31]
	v_add_f32_e64 v214, v218, v216
	v_add_f32_e64 v215, v219, v217
	v_pk_add_f32 v[214:215], v[214:215], v[214:215] op_sel_hi:[0,1]
	v_exp_f32_e32 v214, v213
	s_waitcnt vmcnt(12)
	v_mfma_f32_32x32x16_bf16 v[64:79], v[132:135], v[206:209], v[64:79]
	v_fmamk_f32 v206, v60, 0x3e38aa3b, v193
	v_exp_f32_e32 v211, v206
	v_cvt_pk_bf16_f32 v206, v197, v0
	v_cvt_pk_bf16_f32 v207, v205, v194
	v_cvt_pk_bf16_f32 v208, v195, v202
	v_cvt_pk_bf16_f32 v209, v203, v210
	v_add_f32_e32 v223, v223, v211
	v_pk_add_f32 v[194:195], v[222:223], v[214:215]
	s_waitcnt vmcnt(11)
	v_mfma_f32_32x32x16_bf16 v[16:31], v[128:131], v[206:209], v[16:31]
	v_pk_add_f32 v[194:195], v[194:195], v[194:195] op_sel_hi:[0,1]
	v_fmamk_f32 v0, v62, 0x3e38aa3b, v193
	v_fmac_f32_e32 v193, 0x3e38aa3b, v63
	v_exp_f32_e32 v0, v0
	v_exp_f32_e32 v194, v193
	s_waitcnt vmcnt(10)
	v_mfma_f32_32x32x16_bf16 v[64:79], v[124:127], v[206:209], v[64:79]
	v_cvt_pk_bf16_f32 v206, v221, v212
	v_cvt_pk_bf16_f32 v207, v225, v216
	v_cvt_pk_bf16_f32 v208, v211, v214
	v_cvt_pk_bf16_f32 v209, v0, v194
	v_add_f32_e32 v225, v226, v0
	v_pk_add_f32 v[194:195], v[224:225], v[194:195]
	s_waitcnt vmcnt(9)
	v_mfma_f32_32x32x16_bf16 v[16:31], v[120:123], v[206:209], v[16:31]
	v_add_f32_e32 v0, v194, v195
	v_fmac_f32_e32 v0, v151, v220
	s_waitcnt vmcnt(8)
	v_mfma_f32_32x32x16_bf16 v[64:79], v[116:119], v[206:209], v[64:79]
	s_cbranch_execz .LBB0_1560

.LBB0_1560:
	v_add_u32_e32 v0, s4, v150
	v_cmp_le_i32_e32 vcc, v0, v190
	s_nop 4
	v_or_b32_e32 v180, 2, v0
	v_or_b32_e32 v178, 3, v0
	v_cndmask_b32_e32 v184, v239, v32, vcc
	v_cmp_le_i32_e32 vcc, v0, v149
	v_add_u32_e32 v176, 8, v0
	v_add_u32_e32 v174, 9, v0
	v_cndmask_b32_e32 v185, v239, v48, vcc
	v_cmp_lt_i32_e32 vcc, v0, v190
	v_add_u32_e32 v172, 10, v0
	v_add_u32_e32 v170, 11, v0
	v_cndmask_b32_e32 v182, v239, v33, vcc
	v_cmp_lt_i32_e32 vcc, v0, v149
	v_add_u32_e32 v32, 16, v0
	s_nop 0
	v_cndmask_b32_e32 v183, v239, v49, vcc
	v_cmp_le_i32_e32 vcc, v180, v190
	s_nop 1
	v_cndmask_b32_e32 v181, v239, v34, vcc
	v_cmp_le_i32_e32 vcc, v180, v149
	s_nop 1
	v_cndmask_b32_e32 v180, v239, v50, vcc
	v_cmp_le_i32_e32 vcc, v178, v190
	s_nop 1
	v_cndmask_b32_e32 v179, v239, v35, vcc
	v_cmp_le_i32_e32 vcc, v178, v149
	s_nop 1
	v_cndmask_b32_e32 v178, v239, v51, vcc
	v_cmp_le_i32_e32 vcc, v176, v190
	s_nop 1
	v_cndmask_b32_e32 v177, v239, v36, vcc
	v_cmp_le_i32_e32 vcc, v176, v149
	s_nop 1
	v_cndmask_b32_e32 v176, v239, v52, vcc
	v_cmp_le_i32_e32 vcc, v174, v190
	v_max_i32_e32 v33, v177, v176
	s_nop 0
	v_cndmask_b32_e32 v175, v239, v37, vcc
	v_cmp_le_i32_e32 vcc, v174, v149
	s_nop 1
	v_cndmask_b32_e32 v174, v239, v53, vcc
	v_cmp_le_i32_e32 vcc, v172, v190
	v_max_i32_e32 v34, v175, v174
	s_nop 0
	v_cndmask_b32_e32 v173, v239, v38, vcc
	v_cmp_le_i32_e32 vcc, v172, v149
	s_nop 1
	v_cndmask_b32_e32 v172, v239, v54, vcc
	v_cmp_le_i32_e32 vcc, v170, v190
	v_max_i32_e32 v35, v173, v172
	s_nop 0
	v_cndmask_b32_e32 v171, v239, v39, vcc
	v_cmp_le_i32_e32 vcc, v170, v149
	s_nop 1
	v_cndmask_b32_e32 v170, v239, v55, vcc
	v_cmp_le_i32_e32 vcc, v32, v190
	s_nop 1
	v_cndmask_b32_e32 v48, v239, v40, vcc
	v_cmp_le_i32_e32 vcc, v32, v149
	v_add_u32_e32 v32, 17, v0
	s_nop 0
	v_cndmask_b32_e32 v49, v239, v56, vcc
	v_cmp_le_i32_e32 vcc, v32, v190
	s_nop 1
	v_cndmask_b32_e32 v50, v239, v41, vcc
	v_cmp_le_i32_e32 vcc, v32, v149
	v_add_u32_e32 v32, 18, v0
	s_nop 0
	v_cndmask_b32_e32 v51, v239, v57, vcc
	v_cmp_le_i32_e32 vcc, v32, v190
	s_nop 1
	v_cndmask_b32_e32 v52, v239, v42, vcc
	v_cmp_le_i32_e32 vcc, v32, v149
	v_add_u32_e32 v32, 19, v0
	s_nop 0
	v_cndmask_b32_e32 v53, v239, v58, vcc
	v_cmp_le_i32_e32 vcc, v32, v190
	s_nop 1
	v_cndmask_b32_e32 v54, v239, v43, vcc
	v_cmp_le_i32_e32 vcc, v32, v149
	v_add_u32_e32 v32, 24, v0
	s_nop 0
	v_cndmask_b32_e32 v55, v239, v59, vcc
	v_cmp_le_i32_e32 vcc, v32, v190
	s_nop 1
	v_cndmask_b32_e32 v56, v239, v44, vcc
	v_cmp_le_i32_e32 vcc, v32, v149
	v_add_u32_e32 v32, 25, v0
	s_nop 0
	v_cndmask_b32_e32 v57, v239, v60, vcc
	v_cmp_le_i32_e32 vcc, v32, v190
	s_nop 1
	v_cndmask_b32_e32 v58, v239, v45, vcc
	v_cmp_le_i32_e32 vcc, v32, v149
	v_add_u32_e32 v32, 26, v0
	v_add_u32_e32 v0, 27, v0
	v_cndmask_b32_e32 v59, v239, v61, vcc
	v_cmp_le_i32_e32 vcc, v32, v190
	s_nop 1
	v_cndmask_b32_e32 v60, v239, v46, vcc
	v_cmp_le_i32_e32 vcc, v32, v149
	v_max_i32_e32 v32, v179, v178
	v_max3_i32 v32, v182, v183, v32
	v_cndmask_b32_e32 v61, v239, v62, vcc
	v_cmp_le_i32_e32 vcc, v0, v190
	s_nop 1
	v_cndmask_b32_e32 v62, v239, v47, vcc
	v_cmp_le_i32_e32 vcc, v0, v149
	v_max_i32_e32 v0, v181, v180
	v_max3_i32 v0, v184, v185, v0
	v_max3_i32 v0, v0, v33, v35
	v_max_i32_e32 v33, v171, v170
	v_max3_i32 v32, v32, v34, v33
	v_max_i32_e32 v33, v48, v49
	v_max_i32_e32 v35, v52, v53
	v_max_i32_e32 v34, v50, v51
	v_max3_i32 v0, v0, v33, v35
	v_max_i32_e32 v33, v54, v55
	v_cndmask_b32_e32 v63, v239, v63, vcc
	v_max3_i32 v32, v32, v34, v33
	v_max_i32_e32 v33, v56, v57
	v_max_i32_e32 v35, v60, v61
	v_max_i32_e32 v34, v58, v59
	v_max3_i32 v0, v0, v33, v35
	v_max_i32_e32 v33, v62, v63
	v_max3_i32 v32, v32, v34, v33
	v_and_b32_e32 v33, 64, v235
	v_max3_i32 v0, v0, v32, 0
	v_xor_b32_e32 v32, 32, v235
	v_add_u32_e32 v33, 64, v33
	v_cmp_lt_i32_e32 vcc, v32, v33
	s_nop 1
	v_cndmask_b32_e32 v32, v235, v32, vcc
	v_lshlrev_b32_e32 v32, 2, v32
	v_mov_b32_e32 v32, v0
	s_nop 1
	v_permlane32_swap_b32 v32, v0
	s_waitcnt lgkmcnt(0)
	v_max3_f32 v192, v191, v0, v32
	v_cmp_neq_f32_e32 vcc, s69, v192
	s_nop 1
	v_cndmask_b32_e32 v186, 0, v192, vcc
	v_mul_f32_e32 v193, 0xbe38aa3b, v186
	v_fmamk_f32 v0, v184, 0x3e38aa3b, v193
	v_exp_f32_e32 v156, v0
	v_fmamk_f32 v0, v185, 0x3e38aa3b, v193
	v_exp_f32_e32 v194, v0
	v_fmamk_f32 v0, v182, 0x3e38aa3b, v193
	v_exp_f32_e32 v32, v0
	v_fmamk_f32 v0, v183, 0x3e38aa3b, v193
	v_exp_f32_e32 v0, v0
	v_add_f32_e32 v33, v156, v194
	v_pk_add_f32 v[184:185], v[32:33], v[0:1]
	s_nop 0
	v_pk_add_f32 v[36:37], v[184:185], v[184:185] op_sel_hi:[0,1]
	v_fmamk_f32 v184, v181, 0x3e38aa3b, v193
	v_exp_f32_e32 v33, v184
	v_fmamk_f32 v184, v180, 0x3e38aa3b, v193
	v_exp_f32_e32 v195, v184
	v_fmamk_f32 v184, v179, 0x3e38aa3b, v193
	v_exp_f32_e32 v34, v184
	v_fmamk_f32 v184, v178, 0x3e38aa3b, v193
	v_exp_f32_e32 v36, v184
	v_add_f32_e32 v35, v33, v195
	v_cvt_pk_bf16_f32 v32, v156, v32
	v_cvt_pk_bf16_f32 v33, v33, v34
	v_pk_add_f32 v[184:185], v[34:35], v[36:37]
	s_nop 0
	v_pk_add_f32 v[38:39], v[184:185], v[184:185] op_sel_hi:[0,1]
	v_fmamk_f32 v184, v177, 0x3e38aa3b, v193
	v_exp_f32_e32 v35, v184
	v_fmamk_f32 v184, v176, 0x3e38aa3b, v193
	v_exp_f32_e32 v37, v184
	v_fmamk_f32 v184, v175, 0x3e38aa3b, v193
	v_exp_f32_e32 v40, v184
	v_fmamk_f32 v184, v174, 0x3e38aa3b, v193
	v_exp_f32_e32 v38, v184
	v_add_f32_e32 v41, v35, v37
	v_cvt_pk_bf16_f32 v34, v35, v40
	v_pk_add_f32 v[184:185], v[40:41], v[38:39]
	s_nop 0
	v_pk_add_f32 v[42:43], v[184:185], v[184:185] op_sel_hi:[0,1]
	v_fmamk_f32 v184, v173, 0x3e38aa3b, v193
	v_exp_f32_e32 v39, v184
	v_fmamk_f32 v184, v172, 0x3e38aa3b, v193
	v_exp_f32_e32 v41, v184
	v_fmamk_f32 v184, v171, 0x3e38aa3b, v193
	v_exp_f32_e32 v44, v184
	v_fmamk_f32 v184, v170, 0x3e38aa3b, v193
	v_exp_f32_e32 v42, v184
	v_add_f32_e32 v45, v39, v41
	v_cvt_pk_bf16_f32 v35, v39, v44
	v_pk_add_f32 v[184:185], v[44:45], v[42:43]
	s_nop 0
	v_pk_add_f32 v[46:47], v[184:185], v[184:185] op_sel_hi:[0,1]
	v_fmamk_f32 v184, v48, 0x3e38aa3b, v193
	v_exp_f32_e32 v43, v184
	v_fmamk_f32 v184, v49, 0x3e38aa3b, v193
	v_exp_f32_e32 v197, v184
	v_fmamk_f32 v184, v50, 0x3e38aa3b, v193
	v_exp_f32_e32 v48, v184
	v_fmamk_f32 v184, v51, 0x3e38aa3b, v193
	v_exp_f32_e32 v46, v184
	v_sub_f32_e32 v184, v191, v186
	v_add_f32_e32 v49, v43, v197
	v_mul_f32_e32 v182, 0x3e38aa3b, v184
	v_pk_add_f32 v[184:185], v[48:49], v[46:47]
	s_nop 0
	v_pk_add_f32 v[50:51], v[184:185], v[184:185] op_sel_hi:[0,1]
	v_fmamk_f32 v184, v52, 0x3e38aa3b, v193
	v_exp_f32_e32 v45, v184
	v_fmamk_f32 v184, v53, 0x3e38aa3b, v193
	v_exp_f32_e32 v47, v184
	v_fmamk_f32 v184, v54, 0x3e38aa3b, v193
	v_exp_f32_e32 v54, v182
	v_exp_f32_e32 v52, v184
	v_fmamk_f32 v184, v56, 0x3e38aa3b, v193
	v_exp_f32_e32 v49, v184
	v_fmamk_f32 v184, v58, 0x3e38aa3b, v193
	v_exp_f32_e32 v56, v184
	v_pk_mul_f32 v[16:17], v[16:17], v[54:55] op_sel_hi:[1,0]
	v_pk_mul_f32 v[64:65], v[64:65], v[54:55] op_sel_hi:[1,0]
	v_pk_mul_f32 v[18:19], v[18:19], v[54:55] op_sel_hi:[1,0]
	v_pk_mul_f32 v[20:21], v[20:21], v[54:55] op_sel_hi:[1,0]
	v_pk_mul_f32 v[22:23], v[22:23], v[54:55] op_sel_hi:[1,0]
	v_pk_mul_f32 v[24:25], v[24:25], v[54:55] op_sel_hi:[1,0]
	v_pk_mul_f32 v[26:27], v[26:27], v[54:55] op_sel_hi:[1,0]
	v_pk_mul_f32 v[28:29], v[28:29], v[54:55] op_sel_hi:[1,0]
	v_pk_mul_f32 v[30:31], v[30:31], v[54:55] op_sel_hi:[1,0]
	v_pk_mul_f32 v[66:67], v[66:67], v[54:55] op_sel_hi:[1,0]
	v_pk_mul_f32 v[68:69], v[68:69], v[54:55] op_sel_hi:[1,0]
	v_pk_mul_f32 v[70:71], v[70:71], v[54:55] op_sel_hi:[1,0]
	v_pk_mul_f32 v[72:73], v[72:73], v[54:55] op_sel_hi:[1,0]
	v_pk_mul_f32 v[74:75], v[74:75], v[54:55] op_sel_hi:[1,0]
	v_pk_mul_f32 v[76:77], v[76:77], v[54:55] op_sel_hi:[1,0]
	v_pk_mul_f32 v[78:79], v[78:79], v[54:55] op_sel_hi:[1,0]
	s_waitcnt vmcnt(15)
	v_mfma_f32_32x32x16_bf16 v[16:31], v[144:147], v[32:35], v[16:31]
	v_fmamk_f32 v50, v60, 0x3e38aa3b, v193
	v_exp_f32_e32 v39, v50
	v_add_f32_e32 v53, v45, v47
	s_waitcnt vmcnt(14)
	v_mfma_f32_32x32x16_bf16 v[64:79], v[140:143], v[32:35], v[64:79]
	v_fmamk_f32 v32, v62, 0x3e38aa3b, v193
	v_exp_f32_e32 v40, v32
	v_cvt_pk_bf16_f32 v32, v43, v48
	v_fmamk_f32 v43, v55, 0x3e38aa3b, v193
	v_exp_f32_e32 v50, v43
	v_cvt_pk_bf16_f32 v33, v45, v52
	v_cvt_pk_bf16_f32 v34, v49, v56
	v_cvt_pk_bf16_f32 v35, v39, v40
	v_pk_add_f32 v[44:45], v[52:53], v[50:51]
	s_waitcnt vmcnt(13)
	v_mfma_f32_32x32x16_bf16 v[16:31], v[136:139], v[32:35], v[16:31]
	v_pk_add_f32 v[44:45], v[44:45], v[44:45] op_sel_hi:[0,1]
	v_fmamk_f32 v44, v59, 0x3e38aa3b, v193
	v_exp_f32_e32 v44, v44
	s_waitcnt vmcnt(12)
	v_mfma_f32_32x32x16_bf16 v[64:79], v[132:135], v[32:35], v[64:79]
	v_fmamk_f32 v32, v57, 0x3e38aa3b, v193
	v_exp_f32_e32 v43, v32
	v_cvt_pk_bf16_f32 v32, v194, v0
	v_cvt_pk_bf16_f32 v33, v195, v36
	v_cvt_pk_bf16_f32 v34, v37, v38
	v_cvt_pk_bf16_f32 v35, v41, v42
	v_add_f32_e32 v57, v49, v43
	v_pk_add_f32 v[36:37], v[56:57], v[44:45]
	s_waitcnt vmcnt(11)
	v_mfma_f32_32x32x16_bf16 v[16:31], v[128:131], v[32:35], v[16:31]
	v_pk_add_f32 v[36:37], v[36:37], v[36:37] op_sel_hi:[0,1]
	v_fmamk_f32 v0, v61, 0x3e38aa3b, v193
	v_fmac_f32_e32 v193, 0x3e38aa3b, v63
	v_exp_f32_e32 v0, v0
	v_exp_f32_e32 v36, v193
	v_add_f32_e32 v41, v39, v0
	s_waitcnt vmcnt(10)
	v_mfma_f32_32x32x16_bf16 v[64:79], v[124:127], v[32:35], v[64:79]
	v_cvt_pk_bf16_f32 v32, v197, v46
	v_cvt_pk_bf16_f32 v33, v47, v50
	v_cvt_pk_bf16_f32 v34, v43, v44
	v_cvt_pk_bf16_f32 v35, v0, v36
	v_add_f32_e64 v36, v40, v36
	v_add_f32_e64 v37, v41, v37
	v_add_f32_e32 v0, v36, v37
	s_waitcnt vmcnt(9)
	v_mfma_f32_32x32x16_bf16 v[16:31], v[120:123], v[32:35], v[16:31]
	v_fmac_f32_e32 v0, v151, v54
	s_waitcnt vmcnt(8)
	v_mfma_f32_32x32x16_bf16 v[64:79], v[116:119], v[32:35], v[64:79]
	s_xor_b64 s[2:3], s[8:9], -1
	s_andn2_b64 vcc, exec, s[2:3]
	s_cbranch_vccz .LBB0_1563

.LBB0_1563:
	v_and_b32_e32 v3, 64, v235
	v_xor_b32_e32 v2, 32, v235
	v_add_u32_e32 v3, 64, v3
	v_cmp_lt_i32_e32 vcc, v2, v3
	s_lshl_b32 s36, s24, 1
	s_nop 0
	v_cndmask_b32_e32 v2, v235, v2, vcc
	v_lshlrev_b32_e32 v2, 2, v2
	v_mov_b32_e32 v2, v0
	s_nop 1
	v_permlane32_swap_b32 v2, v0
	s_waitcnt lgkmcnt(0)
	v_add_f32_e32 v0, v0, v2
	v_max_f32_e32 v0, 0xda24260, v0
	v_div_scale_f32 v2, s[0:1], v0, v0, 1.0
	v_rcp_f32_e32 v3, v2
	v_div_scale_f32 v4, vcc, 1.0, v0, 1.0
	v_readlane_b32 s0, v254, 41
	v_fma_f32 v5, -v2, v3, 1.0
	v_fmac_f32_e32 v3, v5, v3
	v_mul_f32_e32 v5, v4, v3
	v_fma_f32 v6, -v2, v5, v4
	v_fmac_f32_e32 v5, v6, v3
	v_fma_f32 v2, -v2, v5, v4
	v_div_fmas_f32 v2, v2, v3, v5
	v_div_fixup_f32 v0, v2, v0, 1.0
	v_pk_mul_f32 v[4:5], v[16:17], v[0:1] op_sel_hi:[1,0]
	v_pk_mul_f32 v[2:3], v[64:65], v[0:1] op_sel_hi:[1,0]
	v_pk_mul_f32 v[8:9], v[18:19], v[0:1] op_sel_hi:[1,0]
	v_pk_mul_f32 v[6:7], v[66:67], v[0:1] op_sel_hi:[1,0]
	v_pk_mul_f32 v[12:13], v[20:21], v[0:1] op_sel_hi:[1,0]
	v_pk_mul_f32 v[10:11], v[68:69], v[0:1] op_sel_hi:[1,0]
	v_pk_mul_f32 v[18:19], v[22:23], v[0:1] op_sel_hi:[1,0]
	v_pk_mul_f32 v[14:15], v[70:71], v[0:1] op_sel_hi:[1,0]
	v_pk_mul_f32 v[20:21], v[24:25], v[0:1] op_sel_hi:[1,0]
	v_pk_mul_f32 v[16:17], v[72:73], v[0:1] op_sel_hi:[1,0]
	v_pk_mul_f32 v[24:25], v[26:27], v[0:1] op_sel_hi:[1,0]
	v_pk_mul_f32 v[22:23], v[74:75], v[0:1] op_sel_hi:[1,0]
	v_pk_mul_f32 v[28:29], v[28:29], v[0:1] op_sel_hi:[1,0]
	v_pk_mul_f32 v[26:27], v[76:77], v[0:1] op_sel_hi:[1,0]
	v_pk_mul_f32 v[32:33], v[30:31], v[0:1] op_sel_hi:[1,0]
	v_pk_mul_f32 v[30:31], v[78:79], v[0:1] op_sel_hi:[1,0]
	v_lshlrev_b32_e32 v0, 11, v148
	v_readlane_b32 s1, v254, 42
	s_nop 1
	v_lshl_add_u64 v[34:35], s[0:1], 0, v[0:1]
	v_lshl_add_u64 v[34:35], v[34:35], 0, s[36:37]
	s_mov_b64 s[0:1], 0xb400400
	v_lshl_add_u64 v[34:35], v[34:35], 0, s[0:1]

.Lnsa_ready:
	s_lshr_b32 s2, s40, 1
	s_and_b32 s2, s2, 0xfc
	s_and_b32 s3, s40, 3
	s_or_b32 s2, s2, s3
	s_xor_b32 s86, s2, 0xfc
	s_lshr_b32 s0, s40, 9
	v_readlane_b32 s1, v254, 63
	s_lshl_b32 s89, s86, 3
	s_waitcnt vmcnt(3)
	v_bfe_u32 v129, v188, 2, 3
	s_or_b32 s0, s0, s1
	v_or_b32_e32 v197, s89, v129
	s_bfe_u32 s1, s40, 0x10002
	v_and_b32_e32 v130, 3, v188
	v_lshl_or_b32 v148, s0, 11, v197
	s_lshl_b32 s0, s0, 1
	v_lshl_or_b32 v128, s1, 2, v130
	s_or_b32 s36, s0, s1
	v_mov_b32_e32 v149, v1
	v_readlane_b32 s0, v254, 61
	v_lshlrev_b64 v[2:3], 10, v[148:149]
	v_readlane_b32 s1, v254, 62
	v_readlane_b32 s2, v254, 57
	v_lshlrev_b32_e32 v154, 3, v188
	v_lshl_add_u64 v[2:3], s[0:1], 0, v[2:3]
	s_lshl_b64 s[0:1], s[36:37], 14
	s_add_u32 s4, s2, s0
	v_readlane_b32 s2, v254, 55
	v_ashrrev_i32_e32 v155, 31, v154
	s_addc_u32 s5, s2, s1
	v_lshlrev_b64 v[152:153], 1, v[154:155]
	v_lshl_add_u64 v[42:43], s[4:5], 0, v[152:153]
	s_movk_i32 s2, 0x2000
	v_add_co_u32_e32 v46, vcc, s2, v42
	v_lshlrev_b32_e32 v0, 7, v128
	s_nop 0
	v_addc_co_u32_e32 v47, vcc, 0, v43, vcc
	v_lshl_add_u64 v[6:7], v[2:3], 0, v[0:1]
	global_load_dwordx4 v[2:5], v[46:47], off offset:-4096
	v_lshlrev_b32_e32 v8, 3, v196
	v_ashrrev_i32_e32 v9, 31, v8
	v_lshl_add_u64 v[52:53], v[8:9], 1, v[6:7]
	global_load_dwordx4 v[80:83], v[52:53], off
	global_load_dwordx4 v[18:21], v[42:43], off
	s_movk_i32 s3, 0x1000
	v_add_co_u32_e32 v50, vcc, s3, v42
	global_load_dwordx4 v[84:87], v[52:53], off offset:32
	s_nop 0
	v_addc_co_u32_e32 v51, vcc, 0, v43, vcc
	global_load_dwordx4 v[38:41], v[50:51], off offset:1024
	v_readlane_b32 s4, v254, 59
	v_readlane_b32 s5, v254, 60
	global_load_dwordx4 v[54:57], v[42:43], off offset:1024
	global_load_dwordx4 v[58:61], v[42:43], off offset:2048
	v_mov_b64_e32 v[6:7], s[4:5]
	s_movk_i32 s4, 0x60
	v_mad_u64_u32 v[6:7], s[4:5], v148, s4, v[6:7]
	v_readlane_b32 s4, v254, 53
	s_add_u32 s0, s4, s0
	v_readlane_b32 s4, v254, 51
	v_mul_u32_u24_e32 v0, 3, v128
	s_addc_u32 s1, s4, s1
	v_lshlrev_b32_e32 v0, 2, v0
	v_lshl_add_u64 v[48:49], s[0:1], 0, v[152:153]
	s_movk_i32 s0, 0x3000
	v_lshl_add_u64 v[150:151], v[6:7], 0, v[0:1]
	v_add_co_u32_e32 v44, vcc, s0, v48
	v_lshlrev_b32_e32 v66, 6, v196
	s_nop 0
	v_addc_co_u32_e32 v45, vcc, 0, v49, vcc
	global_load_dword v0, v[150:151], off
	global_load_dwordx4 v[34:37], v[44:45], off offset:3072
	global_load_dwordx4 v[88:91], v[52:53], off offset:64
	global_load_dwordx4 v[62:65], v[42:43], off offset:3072
	global_load_dwordx4 v[92:95], v[52:53], off offset:96
	v_or_b32_e32 v67, 31, v66
	v_or_b32_e32 v68, 47, v66
	v_cmp_le_i32_e32 vcc, v67, v197
	v_or_b32_e32 v69, 63, v66
	v_add_u32_e32 v70, 0x4f, v66
	v_add_u32_e32 v71, 0x9f, v66
	v_add_u32_e32 v72, 0xaf, v66
	v_add_u32_e32 v73, 0xbf, v66
	v_add_u32_e32 v74, 0xcf, v66
	v_add_u32_e32 v75, 0x19f, v66
	v_add_u32_e32 v76, 0x1af, v66
	v_lshl_add_u32 v206, v188, 2, s83
	v_cmp_eq_u32_e64 s[8:9], 0, v130
	s_waitcnt vmcnt(9)
	v_mfma_f32_32x32x16_bf16 v[18:33], v[18:21], v[80:83], 0
	v_mfma_f32_32x32x16_bf16 v[2:17], v[2:5], v[80:83], 0
	s_waitcnt vmcnt(7)
	v_mfma_f32_32x32x16_bf16 v[2:17], v[38:41], v[84:87], v[2:17]
	global_load_dwordx4 v[38:41], v[50:51], off offset:2048
	s_nop 0
	global_load_dwordx4 v[50:53], v[50:51], off offset:3072
	s_waitcnt vmcnt(8)
	v_mfma_f32_32x32x16_bf16 v[18:33], v[54:57], v[84:87], v[18:33]
	global_load_dwordx4 v[54:57], v[46:47], off
	s_waitcnt vmcnt(5)
	v_mfma_f32_32x32x16_bf16 v[18:33], v[58:61], v[88:91], v[18:33]
	v_add_u32_e32 v58, 0x11f, v66
	v_add_u32_e32 v59, 0x12f, v66
	v_add_u32_e32 v60, 0x13f, v66
	v_add_u32_e32 v61, 0x14f, v66
	s_waitcnt vmcnt(3)
	v_mfma_f32_32x32x16_bf16 v[18:33], v[62:65], v[92:95], v[18:33]
	s_waitcnt vmcnt(2)
	v_mfma_f32_32x32x16_bf16 v[2:17], v[38:41], v[88:91], v[2:17]
	s_nop 9
	v_mul_f32_e32 v18, 0x3e38aa3b, v18
	v_mul_f32_e32 v19, 0x3e38aa3b, v19
	v_cndmask_b32_e32 v62, v239, v18, vcc
	v_cmp_le_i32_e32 vcc, v68, v197
	v_mul_f32_e32 v20, 0x3e38aa3b, v20
	v_mul_f32_e32 v21, 0x3e38aa3b, v21
	v_cndmask_b32_e32 v63, v239, v19, vcc
	v_cmp_le_i32_e32 vcc, v69, v197
	v_mul_f32_e32 v22, 0x3e38aa3b, v22
	v_mul_f32_e32 v23, 0x3e38aa3b, v23
	v_cndmask_b32_e32 v64, v239, v20, vcc
	v_cmp_le_i32_e32 vcc, v70, v197
	v_mul_f32_e32 v24, 0x3e38aa3b, v24
	v_mul_f32_e32 v25, 0x3e38aa3b, v25
	v_cndmask_b32_e32 v65, v239, v21, vcc
	v_cmp_le_i32_e32 vcc, v71, v197
	v_mul_f32_e32 v26, 0x3e38aa3b, v26
	v_mul_f32_e32 v27, 0x3e38aa3b, v27
	v_cndmask_b32_e32 v67, v239, v22, vcc
	v_cmp_le_i32_e32 vcc, v72, v197
	v_mul_f32_e32 v28, 0x3e38aa3b, v28
	global_load_dwordx4 v[38:41], v[46:47], off offset:2048
	v_cndmask_b32_e32 v68, v239, v23, vcc
	v_cmp_le_i32_e32 vcc, v73, v197
	s_waitcnt vmcnt(2)
	v_mfma_f32_32x32x16_bf16 v[2:17], v[50:53], v[92:95], v[2:17]
	v_mul_f32_e32 v29, 0x3e38aa3b, v29
	v_cndmask_b32_e32 v69, v239, v24, vcc
	v_cmp_le_i32_e32 vcc, v74, v197
	v_mul_f32_e32 v30, 0x3e38aa3b, v30
	v_mul_f32_e32 v31, 0x3e38aa3b, v31
	v_cndmask_b32_e32 v70, v239, v25, vcc
	v_cmp_le_i32_e32 vcc, v58, v197
	v_add_u32_e32 v19, 0x1bf, v66
	global_load_dwordx4 v[50:53], v[46:47], off offset:3072
	v_cndmask_b32_e32 v71, v239, v26, vcc
	v_cmp_le_i32_e32 vcc, v59, v197
	v_mul_f32_e32 v20, 0x3e38aa3b, v32
	v_mul_f32_e32 v2, 0x3e38aa3b, v2
	v_cndmask_b32_e32 v72, v239, v27, vcc
	v_cmp_le_i32_e32 vcc, v60, v197
	v_max3_f32 v18, v62, s69, v63
	v_max3_f32 v18, v18, v64, v65
	v_cndmask_b32_e32 v73, v239, v28, vcc
	v_cmp_le_i32_e32 vcc, v61, v197
	global_load_dwordx4 v[58:61], v[46:47], off offset:1024
	v_mul_f32_e32 v3, 0x3e38aa3b, v3
	v_cndmask_b32_e32 v74, v239, v29, vcc
	v_cmp_le_i32_e32 vcc, v75, v197
	v_max3_f32 v18, v18, v67, v68
	v_max3_f32 v18, v18, v69, v70
	v_cndmask_b32_e32 v75, v239, v30, vcc
	v_cmp_le_i32_e32 vcc, v76, v197
	v_mul_f32_e32 v4, 0x3e38aa3b, v4
	v_max3_f32 v18, v18, v71, v72
	v_cndmask_b32_e32 v76, v239, v31, vcc
	v_cmp_le_i32_e32 vcc, v19, v197
	v_add_u32_e32 v19, 0x1cf, v66
	v_max3_f32 v18, v18, v73, v74
	v_cndmask_b32_e32 v77, v239, v20, vcc
	v_mul_f32_e32 v20, 0x3e38aa3b, v33
	v_cmp_le_i32_e32 vcc, v19, v197
	v_add_u32_e32 v19, 0x21f, v66
	v_max3_f32 v18, v18, v75, v76
	v_cndmask_b32_e32 v78, v239, v20, vcc
	v_cmp_le_i32_e32 vcc, v19, v197
	v_max3_f32 v18, v18, v77, v78
	s_nop 0
	v_cndmask_b32_e32 v46, v239, v2, vcc
	v_add_u32_e32 v2, 0x22f, v66
	v_cmp_le_i32_e32 vcc, v2, v197
	s_nop 1
	v_cndmask_b32_e32 v47, v239, v3, vcc
	v_add_u32_e32 v3, 0x23f, v66
	v_cmp_le_i32_e32 vcc, v3, v197
	v_add_u32_e32 v3, 0x24f, v66
	v_max3_f32 v2, v18, v46, v47
	v_cndmask_b32_e32 v96, v239, v4, vcc
	v_mul_f32_e32 v4, 0x3e38aa3b, v5
	v_cmp_le_i32_e32 vcc, v3, v197
	v_add_u32_e32 v3, 0x29f, v66
	s_waitcnt vmcnt(3)
	v_mfma_f32_32x32x16_bf16 v[18:33], v[54:57], v[80:83], 0
	v_cndmask_b32_e32 v97, v239, v4, vcc
	v_mul_f32_e32 v4, 0x3e38aa3b, v6
	v_cmp_le_i32_e32 vcc, v3, v197
	v_add_u32_e32 v3, 0x2af, v66
	v_max3_f32 v2, v2, v96, v97
	v_cndmask_b32_e32 v100, v239, v4, vcc
	v_mul_f32_e32 v4, 0x3e38aa3b, v7
	v_cmp_le_i32_e32 vcc, v3, v197
	v_add_u32_e32 v3, 0x2bf, v66
	s_waitcnt vmcnt(0)
	v_mfma_f32_32x32x16_bf16 v[18:33], v[58:61], v[84:87], v[18:33]
	v_cndmask_b32_e32 v101, v239, v4, vcc
	v_mul_f32_e32 v4, 0x3e38aa3b, v8
	v_cmp_le_i32_e32 vcc, v3, v197
	v_add_u32_e32 v3, 0x2cf, v66
	v_max3_f32 v2, v2, v100, v101
	v_cndmask_b32_e32 v102, v239, v4, vcc
	v_mul_f32_e32 v4, 0x3e38aa3b, v9
	v_cmp_le_i32_e32 vcc, v3, v197
	v_add_u32_e32 v3, 0x31f, v66
	v_mfma_f32_32x32x16_bf16 v[18:33], v[38:41], v[88:91], v[18:33]
	v_cndmask_b32_e32 v103, v239, v4, vcc
	v_mul_f32_e32 v4, 0x3e38aa3b, v10
	v_cmp_le_i32_e32 vcc, v3, v197
	v_add_u32_e32 v3, 0x32f, v66
	v_max3_f32 v2, v2, v102, v103
	v_cndmask_b32_e32 v104, v239, v4, vcc
	v_mul_f32_e32 v4, 0x3e38aa3b, v11
	v_cmp_le_i32_e32 vcc, v3, v197
	v_mul_f32_e32 v3, 0x3e38aa3b, v12
	v_mfma_f32_32x32x16_bf16 v[18:33], v[50:53], v[92:95], v[18:33]
	v_cndmask_b32_e32 v105, v239, v4, vcc
	v_max3_f32 v8, v2, v104, v105
	v_add_u32_e32 v2, 0x33f, v66
	v_cmp_le_i32_e32 vcc, v2, v197
	v_add_u32_e32 v2, 0x34f, v66
	v_add_u32_e32 v9, 0x39f, v66
	v_cndmask_b32_e32 v106, v239, v3, vcc
	v_mul_f32_e32 v3, 0x3e38aa3b, v13
	v_cmp_le_i32_e32 vcc, v2, v197
	v_mul_f32_e32 v10, 0x3e38aa3b, v14
	s_nop 1
	v_mul_f32_e32 v29, 0x3e38aa3b, v29
	v_cndmask_b32_e32 v107, v239, v3, vcc
	v_add_co_u32_e32 v6, vcc, s0, v42
	v_max3_f32 v8, v8, v106, v107
	s_nop 0
	v_addc_co_u32_e32 v7, vcc, 0, v43, vcc
	global_load_dwordx4 v[2:5], v[6:7], off
	global_load_dwordx4 v[54:57], v[6:7], off offset:1024
	global_load_dwordx4 v[58:61], v[6:7], off offset:2048
	global_load_dwordx4 v[38:41], v[6:7], off offset:3072
	v_cmp_le_i32_e32 vcc, v9, v197
	v_add_u32_e32 v9, 0x3af, v66
	v_add_u32_e32 v7, 0x41f, v66
	v_cndmask_b32_e32 v108, v239, v10, vcc
	v_mul_f32_e32 v10, 0x3e38aa3b, v15
	v_cmp_le_i32_e32 vcc, v9, v197
	v_add_u32_e32 v9, 0x3bf, v66
	v_mul_f32_e32 v30, 0x3e38aa3b, v30
	v_cndmask_b32_e32 v109, v239, v10, vcc
	v_mul_f32_e32 v10, 0x3e38aa3b, v16
	v_cmp_le_i32_e32 vcc, v9, v197
	v_add_u32_e32 v9, 0x3cf, v66
	v_max3_f32 v8, v8, v108, v109
	v_cndmask_b32_e32 v110, v239, v10, vcc
	v_mul_f32_e32 v10, 0x3e38aa3b, v17
	v_cmp_le_i32_e32 vcc, v9, v197
	v_mul_f32_e32 v31, 0x3e38aa3b, v31
	v_mul_f32_e32 v32, 0x3e38aa3b, v32
	v_cndmask_b32_e32 v111, v239, v10, vcc
	v_max3_f32 v6, v8, v110, v111
	v_mul_f32_e32 v8, 0x3e38aa3b, v18
	v_cmp_le_i32_e32 vcc, v7, v197
	v_add_u32_e32 v7, 0x42f, v66
	v_mul_f32_e32 v33, 0x3e38aa3b, v33
	v_cndmask_b32_e32 v50, v239, v8, vcc
	v_mul_f32_e32 v8, 0x3e38aa3b, v19
	v_cmp_le_i32_e32 vcc, v7, v197
	v_add_u32_e32 v7, 0x43f, v66
	v_add_u32_e32 v19, 0x54f, v66
	v_cndmask_b32_e32 v51, v239, v8, vcc
	v_mul_f32_e32 v8, 0x3e38aa3b, v20
	v_cmp_le_i32_e32 vcc, v7, v197
	v_add_u32_e32 v7, 0x44f, v66
	v_max3_f32 v6, v6, v50, v51
	v_cndmask_b32_e32 v20, v239, v8, vcc
	v_mul_f32_e32 v8, 0x3e38aa3b, v21
	v_cmp_le_i32_e32 vcc, v7, v197
	v_add_u32_e32 v7, 0x49f, v66
	s_nop 0
	v_cndmask_b32_e32 v21, v239, v8, vcc
	v_mul_f32_e32 v8, 0x3e38aa3b, v22
	v_cmp_le_i32_e32 vcc, v7, v197
	v_add_u32_e32 v7, 0x4af, v66
	v_max3_f32 v6, v6, v20, v21
	v_cndmask_b32_e32 v22, v239, v8, vcc
	v_mul_f32_e32 v8, 0x3e38aa3b, v23
	v_cmp_le_i32_e32 vcc, v7, v197
	v_add_u32_e32 v7, 0x4bf, v66
	s_nop 0
	v_cndmask_b32_e32 v23, v239, v8, vcc
	v_mul_f32_e32 v8, 0x3e38aa3b, v24
	v_cmp_le_i32_e32 vcc, v7, v197
	v_add_u32_e32 v7, 0x4cf, v66
	v_max3_f32 v6, v6, v22, v23
	v_cndmask_b32_e32 v24, v239, v8, vcc
	v_mul_f32_e32 v8, 0x3e38aa3b, v25
	v_cmp_le_i32_e32 vcc, v7, v197
	v_add_u32_e32 v7, 0x51f, v66
	s_nop 0
	v_cndmask_b32_e32 v25, v239, v8, vcc
	v_mul_f32_e32 v8, 0x3e38aa3b, v26
	v_cmp_le_i32_e32 vcc, v7, v197
	v_add_u32_e32 v7, 0x52f, v66
	v_max3_f32 v6, v6, v24, v25
	v_cndmask_b32_e32 v26, v239, v8, vcc
	v_mul_f32_e32 v8, 0x3e38aa3b, v27
	v_cmp_le_i32_e32 vcc, v7, v197
	v_mul_f32_e32 v7, 0x3e38aa3b, v28
	s_nop 0
	v_cndmask_b32_e32 v27, v239, v8, vcc
	v_max3_f32 v18, v6, v26, v27
	v_add_u32_e32 v6, 0x53f, v66
	v_cmp_le_i32_e32 vcc, v6, v197
	s_nop 1
	v_cndmask_b32_e32 v28, v239, v7, vcc
	s_waitcnt vmcnt(3)
	v_mfma_f32_32x32x16_bf16 v[2:17], v[2:5], v[80:83], 0
	v_cmp_le_i32_e32 vcc, v19, v197
	v_add_u32_e32 v19, 0x59f, v66
	s_nop 0
	v_cndmask_b32_e32 v29, v239, v29, vcc
	v_cmp_le_i32_e32 vcc, v19, v197
	v_add_u32_e32 v19, 0x5af, v66
	v_max3_f32 v18, v18, v28, v29
	s_waitcnt vmcnt(2)
	v_mfma_f32_32x32x16_bf16 v[2:17], v[54:57], v[84:87], v[2:17]
	v_cndmask_b32_e32 v30, v239, v30, vcc
	v_cmp_le_i32_e32 vcc, v19, v197
	v_add_u32_e32 v19, 0x5bf, v66
	s_nop 0
	v_cndmask_b32_e32 v31, v239, v31, vcc
	v_cmp_le_i32_e32 vcc, v19, v197
	v_add_u32_e32 v19, 0x5cf, v66
	s_waitcnt vmcnt(1)
	v_mfma_f32_32x32x16_bf16 v[2:17], v[58:61], v[88:91], v[2:17]
	v_cndmask_b32_e32 v32, v239, v32, vcc
	v_cmp_le_i32_e32 vcc, v19, v197
	v_add_u32_e32 v19, 0x61f, v66
	v_max3_f32 v18, v18, v30, v31
	v_cndmask_b32_e32 v33, v239, v33, vcc
	v_cmp_le_i32_e32 vcc, v19, v197
	v_max3_f32 v18, v18, v32, v33
	s_waitcnt vmcnt(0)
	v_mfma_f32_32x32x16_bf16 v[2:17], v[38:41], v[92:95], v[2:17]
	s_nop 11
	v_mul_f32_e32 v2, 0x3e38aa3b, v2
	v_cndmask_b32_e32 v114, v239, v2, vcc
	v_add_u32_e32 v2, 0x62f, v66
	v_mul_f32_e32 v3, 0x3e38aa3b, v3
	v_cmp_le_i32_e32 vcc, v2, v197
	v_mul_f32_e32 v4, 0x3e38aa3b, v4
	s_nop 0
	v_cndmask_b32_e32 v115, v239, v3, vcc
	v_add_u32_e32 v3, 0x63f, v66
	v_cmp_le_i32_e32 vcc, v3, v197
	v_add_u32_e32 v3, 0x64f, v66
	v_max3_f32 v2, v18, v114, v115
	v_cndmask_b32_e32 v116, v239, v4, vcc
	v_mul_f32_e32 v4, 0x3e38aa3b, v5
	v_cmp_le_i32_e32 vcc, v3, v197
	v_add_u32_e32 v3, 0x69f, v66
	s_nop 0
	v_cndmask_b32_e32 v117, v239, v4, vcc
	v_mul_f32_e32 v4, 0x3e38aa3b, v6
	v_cmp_le_i32_e32 vcc, v3, v197
	v_add_u32_e32 v3, 0x6af, v66
	v_max3_f32 v2, v2, v116, v117
	v_cndmask_b32_e32 v120, v239, v4, vcc
	v_mul_f32_e32 v4, 0x3e38aa3b, v7
	v_cmp_le_i32_e32 vcc, v3, v197
	v_add_u32_e32 v3, 0x6bf, v66
	s_nop 0
	v_cndmask_b32_e32 v121, v239, v4, vcc
	v_mul_f32_e32 v4, 0x3e38aa3b, v8
	v_cmp_le_i32_e32 vcc, v3, v197
	v_add_u32_e32 v3, 0x6cf, v66
	v_max3_f32 v2, v2, v120, v121
	v_cndmask_b32_e32 v122, v239, v4, vcc
	v_mul_f32_e32 v4, 0x3e38aa3b, v9
	v_cmp_le_i32_e32 vcc, v3, v197
	v_add_u32_e32 v3, 0x71f, v66
	s_nop 0
	v_cndmask_b32_e32 v123, v239, v4, vcc
	v_mul_f32_e32 v4, 0x3e38aa3b, v10
	v_cmp_le_i32_e32 vcc, v3, v197
	v_add_u32_e32 v3, 0x72f, v66
	v_max3_f32 v2, v2, v122, v123
	v_cndmask_b32_e32 v132, v239, v4, vcc
	v_mul_f32_e32 v4, 0x3e38aa3b, v11
	v_cmp_le_i32_e32 vcc, v3, v197
	v_add_u32_e32 v3, 0x73f, v66
	s_nop 0
	v_cndmask_b32_e32 v133, v239, v4, vcc
	v_mul_f32_e32 v4, 0x3e38aa3b, v12
	v_cmp_le_i32_e32 vcc, v3, v197
	v_add_u32_e32 v3, 0x74f, v66
	v_max3_f32 v2, v2, v132, v133
	v_cndmask_b32_e32 v134, v239, v4, vcc
	v_mul_f32_e32 v4, 0x3e38aa3b, v13
	v_cmp_le_i32_e32 vcc, v3, v197
	v_add_u32_e32 v3, 0x79f, v66
	s_nop 0
	v_cndmask_b32_e32 v135, v239, v4, vcc
	v_mul_f32_e32 v4, 0x3e38aa3b, v14
	v_cmp_le_i32_e32 vcc, v3, v197
	v_add_u32_e32 v3, 0x7af, v66
	v_max3_f32 v2, v2, v134, v135
	v_cndmask_b32_e32 v14, v239, v4, vcc
	v_mul_f32_e32 v4, 0x3e38aa3b, v15
	v_cmp_le_i32_e32 vcc, v3, v197
	v_add_u32_e32 v3, 0x7bf, v66
	s_nop 0
	v_cndmask_b32_e32 v15, v239, v4, vcc
	v_mul_f32_e32 v4, 0x3e38aa3b, v16
	v_cmp_le_i32_e32 vcc, v3, v197
	v_add_u32_e32 v3, 0x7cf, v66
	v_max3_f32 v2, v2, v14, v15
	v_cndmask_b32_e32 v16, v239, v4, vcc
	v_mul_f32_e32 v4, 0x3e38aa3b, v17
	v_cmp_le_i32_e32 vcc, v3, v197
	v_xor_b32_e32 v3, 32, v235
	s_nop 0
	v_cndmask_b32_e32 v17, v239, v4, vcc
	v_and_b32_e32 v4, 64, v235
	v_add_u32_e32 v131, 64, v4
	v_cmp_lt_i32_e32 vcc, v3, v131
	v_max3_f32 v2, v2, v16, v17
	s_nop 0
	v_cndmask_b32_e32 v3, v235, v3, vcc
	v_lshlrev_b32_e32 v205, 2, v3
	ds_bpermute_b32 v3, v205, v2
	s_waitcnt lgkmcnt(0)
	v_max_f32_e32 v3, v3, v3
	v_max_f32_e32 v2, v2, v3
	v_cmp_neq_f32_e32 vcc, s69, v2
	s_nop 1
	v_cndmask_b32_e32 v136, 0, v2, vcc
	v_sub_f32_e32 v2, v62, v136
	v_exp_f32_e32 v2, v2
	v_sub_f32_e32 v3, v63, v136
	v_exp_f32_e32 v3, v3
	v_sub_f32_e32 v4, v64, v136
	v_exp_f32_e32 v4, v4
	v_sub_f32_e32 v5, v65, v136
	v_exp_f32_e32 v5, v5
	v_add_f32_e32 v6, 0, v2
	v_add_f32_e32 v6, v3, v6
	v_add_f32_e32 v6, v4, v6
	v_add_f32_e32 v10, v5, v6
	v_sub_f32_e32 v6, v67, v136
	v_exp_f32_e32 v6, v6
	v_sub_f32_e32 v7, v68, v136
	v_exp_f32_e32 v7, v7
	v_sub_f32_e32 v8, v69, v136
	v_exp_f32_e32 v8, v8
	v_sub_f32_e32 v9, v70, v136
	v_exp_f32_e32 v9, v9
	v_sub_f32_e32 v11, v71, v136
	v_add_f32_e32 v10, v6, v10
	v_exp_f32_e32 v18, v11
	v_sub_f32_e32 v11, v72, v136
	v_add_f32_e32 v10, v7, v10
	v_exp_f32_e32 v19, v11
	v_sub_f32_e32 v11, v73, v136
	v_add_f32_e32 v10, v8, v10
	v_exp_f32_e32 v38, v11
	v_sub_f32_e32 v11, v74, v136
	v_add_f32_e32 v10, v9, v10
	v_exp_f32_e32 v39, v11
	v_sub_f32_e32 v11, v75, v136
	v_add_f32_e32 v10, v18, v10
	v_exp_f32_e32 v58, v11
	v_sub_f32_e32 v11, v76, v136
	v_add_f32_e32 v10, v19, v10
	v_exp_f32_e32 v59, v11
	v_sub_f32_e32 v11, v77, v136
	v_add_f32_e32 v10, v38, v10
	v_exp_f32_e32 v60, v11
	v_sub_f32_e32 v11, v78, v136
	v_add_f32_e32 v10, v39, v10
	v_exp_f32_e32 v61, v11
	v_sub_f32_e32 v11, v46, v136
	v_add_f32_e32 v10, v58, v10
	v_exp_f32_e32 v78, v11
	v_sub_f32_e32 v11, v47, v136
	v_add_f32_e32 v10, v59, v10
	v_exp_f32_e32 v79, v11
	v_sub_f32_e32 v11, v96, v136
	v_add_f32_e32 v10, v60, v10
	v_exp_f32_e32 v98, v11
	v_sub_f32_e32 v11, v97, v136
	v_add_f32_e32 v10, v61, v10
	v_exp_f32_e32 v99, v11
	v_sub_f32_e32 v11, v100, v136
	v_add_f32_e32 v10, v78, v10
	v_exp_f32_e32 v126, v11
	v_sub_f32_e32 v11, v101, v136
	v_add_f32_e32 v10, v79, v10
	v_exp_f32_e32 v127, v11
	v_sub_f32_e32 v11, v102, v136
	v_add_f32_e32 v10, v98, v10
	v_exp_f32_e32 v62, v11
	v_sub_f32_e32 v11, v103, v136
	v_add_f32_e32 v10, v99, v10
	v_exp_f32_e32 v63, v11
	v_sub_f32_e32 v11, v104, v136
	v_add_f32_e32 v10, v126, v10
	v_exp_f32_e32 v42, v11
	v_sub_f32_e32 v11, v105, v136
	v_add_f32_e32 v10, v127, v10
	v_exp_f32_e32 v43, v11
	v_sub_f32_e32 v11, v106, v136
	v_add_f32_e32 v10, v62, v10
	v_exp_f32_e32 v54, v11
	v_sub_f32_e32 v11, v107, v136
	v_add_f32_e32 v10, v63, v10
	v_exp_f32_e32 v55, v11
	v_sub_f32_e32 v11, v108, v136
	v_add_f32_e32 v10, v42, v10
	v_exp_f32_e32 v96, v11
	v_sub_f32_e32 v11, v109, v136
	v_add_f32_e32 v10, v43, v10
	v_exp_f32_e32 v97, v11
	v_sub_f32_e32 v11, v110, v136
	v_add_f32_e32 v10, v54, v10
	v_exp_f32_e32 v124, v11
	v_sub_f32_e32 v11, v111, v136
	v_add_f32_e32 v10, v55, v10
	v_exp_f32_e32 v125, v11
	v_sub_f32_e32 v11, v50, v136
	v_add_f32_e32 v10, v96, v10
	v_exp_f32_e32 v50, v11
	v_sub_f32_e32 v11, v51, v136
	v_add_f32_e32 v10, v97, v10
	v_exp_f32_e32 v51, v11
	v_sub_f32_e32 v11, v20, v136
	v_add_f32_e32 v10, v124, v10
	v_exp_f32_e32 v76, v11
	v_sub_f32_e32 v11, v21, v136
	v_add_f32_e32 v10, v125, v10
	v_exp_f32_e32 v77, v11
	v_sub_f32_e32 v11, v22, v136
	v_add_f32_e32 v10, v50, v10
	v_exp_f32_e32 v52, v11
	v_sub_f32_e32 v11, v23, v136
	v_add_f32_e32 v10, v51, v10
	v_exp_f32_e32 v53, v11
	v_sub_f32_e32 v11, v24, v136
	v_add_f32_e32 v10, v76, v10
	v_exp_f32_e32 v56, v11
	v_sub_f32_e32 v11, v25, v136
	v_add_f32_e32 v10, v77, v10
	v_exp_f32_e32 v57, v11
	v_sub_f32_e32 v11, v26, v136
	v_add_f32_e32 v10, v52, v10
	v_exp_f32_e32 v40, v11
	v_sub_f32_e32 v11, v27, v136
	v_add_f32_e32 v10, v53, v10
	v_exp_f32_e32 v41, v11
	v_sub_f32_e32 v11, v28, v136
	v_add_f32_e32 v10, v56, v10
	v_exp_f32_e32 v46, v11
	v_sub_f32_e32 v11, v29, v136
	v_add_f32_e32 v10, v57, v10
	v_exp_f32_e32 v47, v11
	v_sub_f32_e32 v11, v30, v136
	v_add_f32_e32 v10, v40, v10
	v_exp_f32_e32 v112, v11
	v_sub_f32_e32 v11, v31, v136
	v_add_f32_e32 v10, v41, v10
	v_exp_f32_e32 v113, v11
	v_sub_f32_e32 v11, v32, v136
	v_add_f32_e32 v10, v46, v10
	v_exp_f32_e32 v118, v11
	v_sub_f32_e32 v11, v33, v136
	v_add_f32_e32 v10, v47, v10
	v_exp_f32_e32 v119, v11
	v_add_f32_e32 v10, v112, v10
	v_add_f32_e32 v10, v113, v10
	v_add_f32_e32 v10, v118, v10
	v_add_f32_e32 v20, v119, v10
	v_sub_f32_e32 v10, v114, v136
	v_exp_f32_e32 v64, v10
	v_sub_f32_e32 v10, v115, v136
	v_sub_f32_e32 v21, v116, v136
	v_exp_f32_e32 v65, v10
	global_load_dwordx4 v[10:13], v[48:49], off
	v_exp_f32_e32 v72, v21
	v_sub_f32_e32 v21, v117, v136
	v_exp_f32_e32 v73, v21
	v_sub_f32_e32 v21, v120, v136
	v_exp_f32_e32 v66, v21
	v_sub_f32_e32 v21, v121, v136
	v_exp_f32_e32 v67, v21
	v_sub_f32_e32 v21, v122, v136
	v_exp_f32_e32 v74, v21
	v_sub_f32_e32 v21, v123, v136
	v_exp_f32_e32 v75, v21
	v_sub_f32_e32 v21, v132, v136
	v_exp_f32_e32 v68, v21
	v_sub_f32_e32 v21, v133, v136
	v_exp_f32_e32 v69, v21
	v_sub_f32_e32 v21, v134, v136
	v_exp_f32_e32 v70, v21
	v_sub_f32_e32 v21, v135, v136
	global_load_dwordx4 v[132:135], v[48:49], off offset:2048
	v_add_f32_e32 v20, v64, v20
	v_add_f32_e32 v20, v65, v20
	v_add_f32_e32 v20, v72, v20
	v_add_f32_e32 v20, v73, v20
	v_add_f32_e32 v20, v66, v20
	v_add_f32_e32 v20, v67, v20
	v_add_f32_e32 v20, v74, v20
	v_add_f32_e32 v20, v75, v20
	v_exp_f32_e32 v71, v21
	v_sub_f32_e32 v14, v14, v136
	v_add_f32_e32 v20, v68, v20
	v_exp_f32_e32 v102, v14
	v_sub_f32_e32 v14, v15, v136
	v_add_f32_e32 v20, v69, v20
	v_exp_f32_e32 v103, v14
	v_sub_f32_e32 v14, v16, v136
	v_add_f32_e32 v20, v70, v20
	v_exp_f32_e32 v106, v14
	v_sub_f32_e32 v14, v17, v136
	v_add_f32_e32 v20, v71, v20
	v_exp_f32_e32 v107, v14
	v_add_f32_e32 v14, v102, v20
	v_add_f32_e32 v14, v103, v14
	v_add_f32_e32 v14, v106, v14
	v_add_f32_e32 v14, v107, v14
	ds_bpermute_b32 v15, v205, v14
	global_load_dwordx4 v[20:23], v[48:49], off offset:1024
	global_load_dwordx4 v[136:139], v[48:49], off offset:3072
	s_waitcnt lgkmcnt(0)
	v_add_f32_e32 v14, v14, v15
	v_max_f32_e32 v14, 0xda24260, v14
	v_div_scale_f32 v15, s[0:1], v14, v14, 1.0
	v_rcp_f32_e32 v16, v15
	s_nop 0
	v_fma_f32 v17, -v15, v16, 1.0
	v_fmac_f32_e32 v16, v17, v16
	v_div_scale_f32 v17, vcc, 1.0, v14, 1.0
	v_mul_f32_e32 v24, v17, v16
	v_fma_f32 v25, -v15, v24, v17
	v_fmac_f32_e32 v24, v25, v16
	v_fma_f32 v15, -v15, v24, v17
	v_div_fmas_f32 v15, v15, v16, v24
	v_div_fixup_f32 v156, v15, v14, 1.0
	v_pk_mul_f32 v[120:121], v[2:3], v[156:157] op_sel_hi:[1,0]
	v_pk_mul_f32 v[122:123], v[4:5], v[156:157] op_sel_hi:[1,0]
	v_pk_mul_f32 v[110:111], v[6:7], v[156:157] op_sel_hi:[1,0]
	v_pk_mul_f32 v[116:117], v[8:9], v[156:157] op_sel_hi:[1,0]
	v_cvt_pk_bf16_f32 v24, v120, v121
	v_cvt_pk_bf16_f32 v25, v122, v123
	v_cvt_pk_bf16_f32 v26, v110, v111
	v_cvt_pk_bf16_f32 v27, v116, v117
	v_add_co_u32_e32 v158, vcc, s2, v48
	s_waitcnt vmcnt(3)
	v_mfma_f32_32x32x16_bf16 v[2:17], v[10:13], v[24:27], 0
	v_addc_co_u32_e32 v159, vcc, 0, v49, vcc
	v_mul_f32_e64 v108, v18, v156
	v_mul_f32_e64 v109, v19, v156
	v_mul_f32_e64 v114, v38, v156
	v_mul_f32_e64 v115, v39, v156
	v_pk_mul_f32 v[100:101], v[58:59], v[156:157] op_sel_hi:[1,0]
	v_pk_mul_f32 v[104:105], v[60:61], v[156:157] op_sel_hi:[1,0]
	v_add_co_u32_e32 v160, vcc, s3, v48
	v_cvt_pk_bf16_f32 v144, v108, v109
	v_cvt_pk_bf16_f32 v145, v114, v115
	v_cvt_pk_bf16_f32 v146, v100, v101
	v_cvt_pk_bf16_f32 v147, v104, v105
	v_addc_co_u32_e32 v161, vcc, 0, v49, vcc
	global_load_dwordx4 v[140:143], v[158:159], off offset:-4096
	s_waitcnt vmcnt(3)
	v_mfma_f32_32x32x16_bf16 v[2:17], v[132:135], v[144:147], v[2:17]
	global_load_dwordx4 v[132:135], v[160:161], off offset:1024
	v_mul_f32_e64 v58, v78, v156
	v_mul_f32_e64 v59, v79, v156
	v_mul_f32_e64 v60, v98, v156
	v_mul_f32_e64 v61, v99, v156
	v_pk_mul_f32 v[38:39], v[126:127], v[156:157] op_sel_hi:[1,0]
	v_pk_mul_f32 v[62:63], v[62:63], v[156:157] op_sel_hi:[1,0]
	v_pk_mul_f32 v[78:79], v[42:43], v[156:157] op_sel_hi:[1,0]
	v_pk_mul_f32 v[98:99], v[54:55], v[156:157] op_sel_hi:[1,0]
	s_waitcnt vmcnt(3)
	v_mfma_f32_32x32x16_bf16 v[18:33], v[20:23], v[24:27], 0
	v_mul_f32_e64 v42, v96, v156
	v_mul_f32_e64 v43, v97, v156
	v_mul_f32_e64 v48, v124, v156
	v_mul_f32_e64 v49, v125, v156
	v_cvt_pk_bf16_f32 v124, v78, v79
	v_cvt_pk_bf16_f32 v125, v98, v99
	v_cvt_pk_bf16_f32 v126, v42, v43
	v_cvt_pk_bf16_f32 v127, v48, v49
	v_pk_mul_f32 v[50:51], v[50:51], v[156:157] op_sel_hi:[1,0]
	s_waitcnt vmcnt(2)
	v_mfma_f32_32x32x16_bf16 v[18:33], v[136:139], v[144:147], v[18:33]
	v_cvt_pk_bf16_f32 v136, v58, v59
	v_cvt_pk_bf16_f32 v137, v60, v61
	v_cvt_pk_bf16_f32 v138, v38, v39
	v_cvt_pk_bf16_f32 v139, v62, v63
	global_load_dwordx4 v[144:147], v[158:159], off
	v_pk_mul_f32 v[54:55], v[76:77], v[156:157] op_sel_hi:[1,0]
	v_pk_mul_f32 v[52:53], v[52:53], v[156:157] op_sel_hi:[1,0]
	s_waitcnt vmcnt(2)
	v_mfma_f32_32x32x16_bf16 v[2:17], v[140:143], v[136:139], v[2:17]
	global_load_dwordx4 v[140:143], v[160:161], off offset:2048
	v_mul_f32_e64 v56, v56, v156
	v_mul_f32_e64 v57, v57, v156
	v_mul_f32_e64 v76, v40, v156
	v_mul_f32_e64 v77, v41, v156
	v_pk_mul_f32 v[96:97], v[46:47], v[156:157] op_sel_hi:[1,0]
	v_pk_mul_f32 v[40:41], v[112:113], v[156:157] op_sel_hi:[1,0]
	v_pk_mul_f32 v[46:47], v[118:119], v[156:157] op_sel_hi:[1,0]
	v_pk_mul_f32 v[64:65], v[64:65], v[156:157] op_sel_hi:[1,0]
	s_waitcnt vmcnt(2)
	v_mfma_f32_32x32x16_bf16 v[18:33], v[132:135], v[136:139], v[18:33]
	global_load_dwordx4 v[132:135], v[160:161], off offset:3072
	global_load_dwordx4 v[136:139], v[44:45], off
	v_mul_f32_e64 v72, v72, v156
	v_mul_f32_e64 v73, v73, v156
	v_mul_f32_e64 v66, v66, v156
	v_mul_f32_e64 v67, v67, v156
	v_pk_mul_f32 v[74:75], v[74:75], v[156:157] op_sel_hi:[1,0]
	v_pk_mul_f32 v[112:113], v[68:69], v[156:157] op_sel_hi:[1,0]
	v_pk_mul_f32 v[70:71], v[70:71], v[156:157] op_sel_hi:[1,0]
	s_waitcnt vmcnt(2)
	v_mfma_f32_32x32x16_bf16 v[2:17], v[140:143], v[124:127], v[2:17]
	global_load_dwordx4 v[140:143], v[158:159], off offset:2048
	v_mul_f32_e64 v68, v106, v156
	v_mul_f32_e64 v69, v107, v156
	s_waitcnt vmcnt(2)
	v_mfma_f32_32x32x16_bf16 v[18:33], v[132:135], v[124:127], v[18:33]
	global_load_dwordx4 v[124:127], v[158:159], off offset:1024
	v_cvt_pk_bf16_f32 v132, v50, v51
	v_cvt_pk_bf16_f32 v133, v54, v55
	v_cvt_pk_bf16_f32 v134, v52, v53
	v_cvt_pk_bf16_f32 v135, v56, v57
	s_nop 1
	v_mfma_f32_32x32x16_bf16 v[2:17], v[144:147], v[132:135], v[2:17]
	s_waitcnt vmcnt(0)
	v_mfma_f32_32x32x16_bf16 v[18:33], v[124:127], v[132:135], v[18:33]
	global_load_dwordx4 v[132:135], v[158:159], off offset:3072
	v_cvt_pk_bf16_f32 v124, v76, v77
	v_cvt_pk_bf16_f32 v125, v96, v97
	v_cvt_pk_bf16_f32 v126, v40, v41
	v_cvt_pk_bf16_f32 v127, v46, v47
	s_nop 1
	v_mfma_f32_32x32x16_bf16 v[2:17], v[140:143], v[124:127], v[2:17]
	s_waitcnt vmcnt(0)
	v_mfma_f32_32x32x16_bf16 v[18:33], v[132:135], v[124:127], v[18:33]
	global_load_dwordx4 v[124:127], v[44:45], off offset:1024
	v_cvt_pk_bf16_f32 v132, v64, v65
	v_cvt_pk_bf16_f32 v133, v72, v73
	v_cvt_pk_bf16_f32 v134, v66, v67
	v_cvt_pk_bf16_f32 v135, v74, v75
	s_nop 1
	v_mfma_f32_32x32x16_bf16 v[2:17], v[136:139], v[132:135], v[2:17]
	global_load_dwordx4 v[136:139], v[44:45], off offset:2048
	v_mul_f32_e64 v44, v102, v156
	v_mul_f32_e64 v45, v103, v156
	s_waitcnt vmcnt(1)
	v_mfma_f32_32x32x16_bf16 v[18:33], v[124:127], v[132:135], v[18:33]
	v_cvt_pk_bf16_f32 v124, v112, v113
	v_cvt_pk_bf16_f32 v125, v70, v71
	v_cvt_pk_bf16_f32 v126, v44, v45
	v_cvt_pk_bf16_f32 v127, v68, v69
	s_waitcnt vmcnt(0)
	s_nop 0
	v_mfma_f32_32x32x16_bf16 v[2:17], v[136:139], v[124:127], v[2:17]
	v_mfma_f32_32x32x16_bf16 v[18:33], v[34:37], v[124:127], v[18:33]
	s_nop 10
	v_mul_f32_e32 v2, v0, v2
	v_mul_f32_e32 v3, v0, v3
	ds_write2st64_b32 v206, v2, v3 offset0:4 offset1:5
	v_mul_f32_e32 v18, v0, v18
	v_mul_f32_e32 v2, v0, v19
	ds_write2st64_b32 v206, v18, v2 offset0:20 offset1:21
	v_mul_f32_e32 v2, v0, v4
	v_mul_f32_e32 v4, v0, v5
	v_mul_f32_e32 v3, v0, v20
	ds_write2st64_b32 v206, v2, v4 offset0:6 offset1:7
	v_mul_f32_e32 v2, v0, v21
	ds_write2st64_b32 v206, v3, v2 offset0:22 offset1:23
	v_mul_f32_e32 v2, v0, v6
	v_mul_f32_e32 v4, v0, v7
	v_mul_f32_e32 v3, v0, v22
	ds_write2st64_b32 v206, v2, v4 offset0:8 offset1:9
	v_mul_f32_e32 v2, v0, v23
	ds_write2st64_b32 v206, v3, v2 offset0:24 offset1:25
	v_mul_f32_e32 v2, v0, v8
	v_mul_f32_e32 v4, v0, v9
	v_mul_f32_e32 v3, v0, v24
	ds_write2st64_b32 v206, v2, v4 offset0:10 offset1:11
	v_mul_f32_e32 v2, v0, v25
	ds_write2st64_b32 v206, v3, v2 offset0:26 offset1:27
	v_mul_f32_e32 v2, v0, v10
	v_mul_f32_e32 v4, v0, v11
	v_mul_f32_e32 v3, v0, v26
	ds_write2st64_b32 v206, v2, v4 offset0:12 offset1:13
	v_mul_f32_e32 v2, v0, v27
	ds_write2st64_b32 v206, v3, v2 offset0:28 offset1:29
	v_mul_f32_e32 v2, v0, v12
	v_mul_f32_e32 v4, v0, v13
	v_mul_f32_e32 v3, v0, v28
	ds_write2st64_b32 v206, v2, v4 offset0:14 offset1:15
	v_mul_f32_e32 v2, v0, v29
	ds_write2st64_b32 v206, v3, v2 offset0:30 offset1:31
	v_mul_f32_e32 v2, v0, v14
	v_mul_f32_e32 v4, v0, v15
	v_mul_f32_e32 v3, v0, v30
	ds_write2st64_b32 v206, v2, v4 offset0:16 offset1:17
	v_mul_f32_e32 v2, v0, v31
	ds_bpermute_b32 v20, v205, v123
	ds_write2st64_b32 v206, v3, v2 offset0:32 offset1:33
	v_mul_f32_e32 v2, v0, v16
	v_mul_f32_e32 v3, v0, v32
	v_mul_f32_e32 v4, v0, v17
	v_mul_f32_e32 v0, v0, v33
	ds_write2st64_b32 v206, v3, v0 offset0:34 offset1:35
	v_xor_b32_e32 v3, 1, v235
	v_cmp_lt_i32_e32 vcc, v3, v131
	ds_write2st64_b32 v206, v2, v4 offset0:18 offset1:19
	v_add_f32_e32 v4, v122, v123
	v_cndmask_b32_e32 v3, v235, v3, vcc
	v_add_f32_e32 v6, v120, v121
	v_cmp_gt_u32_e32 vcc, 32, v188
	v_add_f32_e32 v4, v6, v4
	v_lshlrev_b32_e32 v3, 2, v3
	s_waitcnt lgkmcnt(3)
	v_cndmask_b32_e64 v6, v20, 0, vcc
	v_add_f32_e32 v4, v6, v4
	s_nop 1
	v_mov_b32_dpp v6, v4 quad_perm:[1,0,3,2] row_mask:0xf bank_mask:0xf
	v_xor_b32_e32 v7, 2, v235
	v_cmp_lt_i32_e64 s[0:1], v7, v131
	ds_bpermute_b32 v19, v205, v117
	ds_bpermute_b32 v18, v205, v115
	v_cndmask_b32_e64 v7, v235, v7, s[0:1]
	v_lshlrev_b32_e32 v7, 2, v7
	s_waitcnt lgkmcnt(2)
	v_add_f32_e32 v21, v4, v6
	ds_bpermute_b32 v17, v205, v105
	ds_bpermute_b32 v16, v205, v61
	ds_bpermute_b32 v15, v205, v63
	ds_bpermute_b32 v14, v205, v99
	ds_bpermute_b32 v13, v205, v49
	ds_bpermute_b32 v12, v205, v55
	ds_bpermute_b32 v11, v205, v57
	ds_bpermute_b32 v10, v205, v97
	ds_bpermute_b32 v9, v205, v47
	ds_bpermute_b32 v8, v205, v73
	ds_bpermute_b32 v5, v205, v75
	ds_bpermute_b32 v0, v205, v71
	ds_bpermute_b32 v2, v205, v69
	s_nop 1
	v_mov_b32_dpp v22, v21 quad_perm:[2,3,0,1] row_mask:0xf bank_mask:0xf
	v_lshlrev_b32_e32 v4, 5, v129
	v_add_u32_e32 v6, v4, v196
	v_lshl_add_u32 v6, v6, 2, s83
	s_and_saveexec_b64 s[0:1], s[8:9]
	s_cbranch_execz .LBB0_1568
	s_waitcnt lgkmcnt(0)
	v_add_f32_e32 v21, v21, v22
	ds_write_b32 v6, v21
.LBB0_1568:
	s_or_b64 exec, exec, s[0:1]
	v_add_f32_e32 v21, v116, v117
	s_waitcnt lgkmcnt(0)
	v_add_f32_e32 v22, v110, v111
	v_add_f32_e32 v21, v22, v21
	v_cndmask_b32_e32 v20, v19, v20, vcc
	v_add_f32_e32 v20, v20, v21
	s_nop 1
	v_mov_b32_dpp v21, v20 quad_perm:[1,0,3,2] row_mask:0xf bank_mask:0xf
	s_waitcnt lgkmcnt(0)
	v_add_f32_e32 v20, v20, v21
	s_nop 1
	v_mov_b32_dpp v21, v20 quad_perm:[2,3,0,1] row_mask:0xf bank_mask:0xf
	s_and_saveexec_b64 s[0:1], s[8:9]
	s_cbranch_execz .LBB0_1570
	s_waitcnt lgkmcnt(0)
	v_add_f32_e32 v20, v20, v21
	ds_write_b32 v6, v20 offset:8
.LBB0_1570:
	s_or_b64 exec, exec, s[0:1]
	v_add_f32_e32 v20, v114, v115
	s_waitcnt lgkmcnt(0)
	v_add_f32_e32 v21, v108, v109
	v_add_f32_e32 v20, v21, v20
	v_cndmask_b32_e32 v19, v18, v19, vcc
	v_add_f32_e32 v19, v19, v20
	s_nop 1
	v_mov_b32_dpp v20, v19 quad_perm:[1,0,3,2] row_mask:0xf bank_mask:0xf
	s_waitcnt lgkmcnt(0)
	v_add_f32_e32 v19, v19, v20
	s_nop 1
	v_mov_b32_dpp v20, v19 quad_perm:[2,3,0,1] row_mask:0xf bank_mask:0xf
	s_and_saveexec_b64 s[0:1], s[8:9]
	s_cbranch_execz .LBB0_1572
	s_waitcnt lgkmcnt(0)
	v_add_f32_e32 v19, v19, v20
	ds_write_b32 v6, v19 offset:16
.LBB0_1572:
	s_or_b64 exec, exec, s[0:1]
	v_add_f32_e32 v19, v104, v105
	s_waitcnt lgkmcnt(0)
	v_add_f32_e32 v20, v100, v101
	v_add_f32_e32 v19, v20, v19
	v_cndmask_b32_e32 v18, v17, v18, vcc
	v_add_f32_e32 v18, v18, v19
	s_nop 1
	v_mov_b32_dpp v19, v18 quad_perm:[1,0,3,2] row_mask:0xf bank_mask:0xf
	s_waitcnt lgkmcnt(0)
	v_add_f32_e32 v18, v18, v19
	s_nop 1
	v_mov_b32_dpp v19, v18 quad_perm:[2,3,0,1] row_mask:0xf bank_mask:0xf
	s_and_saveexec_b64 s[0:1], s[8:9]
	s_cbranch_execz .LBB0_1574
	s_waitcnt lgkmcnt(0)
	v_add_f32_e32 v18, v18, v19
	ds_write_b32 v6, v18 offset:24
.LBB0_1574:
	s_or_b64 exec, exec, s[0:1]
	v_add_f32_e32 v18, v60, v61
	s_waitcnt lgkmcnt(0)
	v_add_f32_e32 v19, v58, v59
	v_add_f32_e32 v18, v19, v18
	v_cndmask_b32_e32 v17, v16, v17, vcc
	v_add_f32_e32 v17, v17, v18
	s_nop 1
	v_mov_b32_dpp v18, v17 quad_perm:[1,0,3,2] row_mask:0xf bank_mask:0xf
	s_waitcnt lgkmcnt(0)
	v_add_f32_e32 v17, v17, v18
	s_nop 1
	v_mov_b32_dpp v18, v17 quad_perm:[2,3,0,1] row_mask:0xf bank_mask:0xf
	s_and_saveexec_b64 s[0:1], s[8:9]
	s_cbranch_execz .LBB0_1576
	s_waitcnt lgkmcnt(0)
	v_add_f32_e32 v17, v17, v18
	ds_write_b32 v6, v17 offset:32
.LBB0_1576:
	s_or_b64 exec, exec, s[0:1]
	v_add_f32_e32 v17, v62, v63
	s_waitcnt lgkmcnt(0)
	v_add_f32_e32 v18, v38, v39
	v_add_f32_e32 v17, v18, v17
	v_cndmask_b32_e32 v16, v15, v16, vcc
	v_add_f32_e32 v16, v16, v17
	s_nop 1
	v_mov_b32_dpp v17, v16 quad_perm:[1,0,3,2] row_mask:0xf bank_mask:0xf
	s_waitcnt lgkmcnt(0)
	v_add_f32_e32 v16, v16, v17
	s_nop 1
	v_mov_b32_dpp v17, v16 quad_perm:[2,3,0,1] row_mask:0xf bank_mask:0xf
	s_and_saveexec_b64 s[0:1], s[8:9]
	s_cbranch_execz .LBB0_1578
	s_waitcnt lgkmcnt(0)
	v_add_f32_e32 v16, v16, v17
	ds_write_b32 v6, v16 offset:40
.LBB0_1578:
	s_or_b64 exec, exec, s[0:1]
	v_add_f32_e32 v16, v98, v99
	s_waitcnt lgkmcnt(0)
	v_add_f32_e32 v17, v78, v79
	v_add_f32_e32 v16, v17, v16
	v_cndmask_b32_e32 v15, v14, v15, vcc
	v_add_f32_e32 v15, v15, v16
	s_nop 1
	v_mov_b32_dpp v16, v15 quad_perm:[1,0,3,2] row_mask:0xf bank_mask:0xf
	s_waitcnt lgkmcnt(0)
	v_add_f32_e32 v15, v15, v16
	s_nop 1
	v_mov_b32_dpp v16, v15 quad_perm:[2,3,0,1] row_mask:0xf bank_mask:0xf
	s_and_saveexec_b64 s[0:1], s[8:9]
	s_cbranch_execz .LBB0_1580
	s_waitcnt lgkmcnt(0)
	v_add_f32_e32 v15, v15, v16
	ds_write_b32 v6, v15 offset:48
.LBB0_1580:
	s_or_b64 exec, exec, s[0:1]
	v_add_f32_e32 v15, v48, v49
	s_waitcnt lgkmcnt(0)
	v_add_f32_e32 v16, v42, v43
	v_add_f32_e32 v15, v16, v15
	v_cndmask_b32_e32 v14, v13, v14, vcc
	v_add_f32_e32 v14, v14, v15
	s_nop 1
	v_mov_b32_dpp v15, v14 quad_perm:[1,0,3,2] row_mask:0xf bank_mask:0xf
	s_waitcnt lgkmcnt(0)
	v_add_f32_e32 v14, v14, v15
	s_nop 1
	v_mov_b32_dpp v15, v14 quad_perm:[2,3,0,1] row_mask:0xf bank_mask:0xf
	s_and_saveexec_b64 s[0:1], s[8:9]
	s_cbranch_execz .LBB0_1582
	s_waitcnt lgkmcnt(0)
	v_add_f32_e32 v14, v14, v15
	ds_write_b32 v6, v14 offset:56
.LBB0_1582:
	s_or_b64 exec, exec, s[0:1]
	v_add_f32_e32 v14, v54, v55
	s_waitcnt lgkmcnt(0)
	v_add_f32_e32 v15, v50, v51
	v_add_f32_e32 v14, v15, v14
	v_cndmask_b32_e32 v13, v12, v13, vcc
	v_add_f32_e32 v13, v13, v14
	s_nop 1
	v_mov_b32_dpp v14, v13 quad_perm:[1,0,3,2] row_mask:0xf bank_mask:0xf
	s_waitcnt lgkmcnt(0)
	v_add_f32_e32 v13, v13, v14
	s_nop 1
	v_mov_b32_dpp v14, v13 quad_perm:[2,3,0,1] row_mask:0xf bank_mask:0xf
	s_and_saveexec_b64 s[0:1], s[8:9]
	s_cbranch_execz .LBB0_1584
	s_waitcnt lgkmcnt(0)
	v_add_f32_e32 v13, v13, v14
	ds_write_b32 v6, v13 offset:64
.LBB0_1584:
	s_or_b64 exec, exec, s[0:1]
	v_add_f32_e32 v13, v56, v57
	s_waitcnt lgkmcnt(0)
	v_add_f32_e32 v14, v52, v53
	v_add_f32_e32 v13, v14, v13
	v_cndmask_b32_e32 v12, v11, v12, vcc
	v_add_f32_e32 v12, v12, v13
	s_nop 1
	v_mov_b32_dpp v13, v12 quad_perm:[1,0,3,2] row_mask:0xf bank_mask:0xf
	s_waitcnt lgkmcnt(0)
	v_add_f32_e32 v12, v12, v13
	s_nop 1
	v_mov_b32_dpp v13, v12 quad_perm:[2,3,0,1] row_mask:0xf bank_mask:0xf
	s_and_saveexec_b64 s[0:1], s[8:9]
	s_cbranch_execz .LBB0_1586
	s_waitcnt lgkmcnt(0)
	v_add_f32_e32 v12, v12, v13
	ds_write_b32 v6, v12 offset:72
.LBB0_1586:
	s_or_b64 exec, exec, s[0:1]
	v_add_f32_e32 v12, v96, v97
	s_waitcnt lgkmcnt(0)
	v_add_f32_e32 v13, v76, v77
	v_add_f32_e32 v12, v13, v12
	v_cndmask_b32_e32 v11, v10, v11, vcc
	v_add_f32_e32 v11, v11, v12
	s_nop 1
	v_mov_b32_dpp v12, v11 quad_perm:[1,0,3,2] row_mask:0xf bank_mask:0xf
	s_waitcnt lgkmcnt(0)
	v_add_f32_e32 v11, v11, v12
	s_nop 1
	v_mov_b32_dpp v12, v11 quad_perm:[2,3,0,1] row_mask:0xf bank_mask:0xf
	s_and_saveexec_b64 s[0:1], s[8:9]
	s_cbranch_execz .LBB0_1588
	s_waitcnt lgkmcnt(0)
	v_add_f32_e32 v11, v11, v12
	ds_write_b32 v6, v11 offset:80
.LBB0_1588:
	s_or_b64 exec, exec, s[0:1]
	v_add_f32_e32 v11, v46, v47
	s_waitcnt lgkmcnt(0)
	v_add_f32_e32 v12, v40, v41
	v_add_f32_e32 v11, v12, v11
	v_cndmask_b32_e32 v10, v9, v10, vcc
	v_add_f32_e32 v10, v10, v11
	s_nop 1
	v_mov_b32_dpp v11, v10 quad_perm:[1,0,3,2] row_mask:0xf bank_mask:0xf
	s_waitcnt lgkmcnt(0)
	v_add_f32_e32 v10, v10, v11
	s_nop 1
	v_mov_b32_dpp v11, v10 quad_perm:[2,3,0,1] row_mask:0xf bank_mask:0xf
	s_and_saveexec_b64 s[0:1], s[8:9]
	s_cbranch_execz .LBB0_1590
	s_waitcnt lgkmcnt(0)
	v_add_f32_e32 v10, v10, v11
	ds_write_b32 v6, v10 offset:88
.LBB0_1590:
	s_or_b64 exec, exec, s[0:1]
	v_add_f32_e32 v10, v72, v73
	s_waitcnt lgkmcnt(0)
	v_add_f32_e32 v11, v64, v65
	v_add_f32_e32 v10, v11, v10
	v_cndmask_b32_e32 v9, v8, v9, vcc
	v_add_f32_e32 v9, v9, v10
	s_nop 1
	v_mov_b32_dpp v10, v9 quad_perm:[1,0,3,2] row_mask:0xf bank_mask:0xf
	s_waitcnt lgkmcnt(0)
	v_add_f32_e32 v9, v9, v10
	s_nop 1
	v_mov_b32_dpp v10, v9 quad_perm:[2,3,0,1] row_mask:0xf bank_mask:0xf
	s_and_saveexec_b64 s[0:1], s[8:9]
	s_cbranch_execz .LBB0_1592
	s_waitcnt lgkmcnt(0)
	v_add_f32_e32 v9, v9, v10
	ds_write_b32 v6, v9 offset:96
.LBB0_1592:
	s_or_b64 exec, exec, s[0:1]
	v_add_f32_e32 v9, v74, v75
	s_waitcnt lgkmcnt(0)
	v_add_f32_e32 v10, v66, v67
	v_add_f32_e32 v9, v10, v9
	v_cndmask_b32_e32 v8, v5, v8, vcc
	v_add_f32_e32 v8, v8, v9
	s_nop 1
	v_mov_b32_dpp v9, v8 quad_perm:[1,0,3,2] row_mask:0xf bank_mask:0xf
	s_waitcnt lgkmcnt(0)
	v_add_f32_e32 v8, v8, v9
	s_nop 1
	v_mov_b32_dpp v9, v8 quad_perm:[2,3,0,1] row_mask:0xf bank_mask:0xf
	s_and_saveexec_b64 s[0:1], s[8:9]
	s_cbranch_execz .LBB0_1594
	s_waitcnt lgkmcnt(0)
	v_add_f32_e32 v8, v8, v9
	ds_write_b32 v6, v8 offset:104
.LBB0_1594:
	s_or_b64 exec, exec, s[0:1]
	v_add_f32_e32 v8, v70, v71
	s_waitcnt lgkmcnt(0)
	v_add_f32_e32 v9, v112, v113
	v_add_f32_e32 v8, v9, v8
	v_cndmask_b32_e32 v5, v0, v5, vcc
	v_add_f32_e32 v5, v5, v8
	s_nop 1
	v_mov_b32_dpp v8, v5 quad_perm:[1,0,3,2] row_mask:0xf bank_mask:0xf
	s_waitcnt lgkmcnt(0)
	v_add_f32_e32 v5, v5, v8
	s_nop 1
	v_mov_b32_dpp v8, v5 quad_perm:[2,3,0,1] row_mask:0xf bank_mask:0xf
	s_and_saveexec_b64 s[0:1], s[8:9]
	s_cbranch_execz .LBB0_1596
	s_waitcnt lgkmcnt(0)
	v_add_f32_e32 v5, v5, v8
	ds_write_b32 v6, v5 offset:112
.LBB0_1596:
	s_or_b64 exec, exec, s[0:1]
	v_add_f32_e32 v5, v68, v69
	s_waitcnt lgkmcnt(0)
	v_add_f32_e32 v8, v44, v45
	v_add_f32_e32 v5, v8, v5
	v_cndmask_b32_e32 v0, v2, v0, vcc
	v_add_f32_e32 v0, v0, v5
	s_nop 1
	v_mov_b32_dpp v2, v0 quad_perm:[1,0,3,2] row_mask:0xf bank_mask:0xf
	s_waitcnt lgkmcnt(0)
	v_add_f32_e32 v0, v0, v2
	s_nop 1
	v_mov_b32_dpp v2, v0 quad_perm:[2,3,0,1] row_mask:0xf bank_mask:0xf
	s_and_saveexec_b64 s[0:1], s[8:9]
	s_cbranch_execz .LBB0_1598
	s_waitcnt lgkmcnt(0)
	v_add_f32_e32 v0, v0, v2
	ds_write_b32 v6, v0 offset:120

.LBB0_1612:
	s_lshl_b32 s4, s0, 6
	v_lshrrev_b32_e32 v0, s0, v190
	s_or_b32 s1, s4, 63
	v_and_b32_e32 v0, 1, v0
	s_cmp_gt_i32 s1, s89
	v_cmp_eq_u32_e64 s[8:9], 1, v0
	s_mov_b64 s[0:1], -1
	s_cbranch_scc1 .LBB0_1619
	v_cndmask_b32_e64 v0, 0, 1, s[8:9]
	v_cmp_ne_u32_e32 vcc, 0, v0
	s_nop 0
	v_max_i32_e32 v0, v66, v50
	v_max3_i32 v0, v64, v48, v0
	v_max_i32_e32 v186, v67, v51
	v_max_i32_e32 v187, v68, v52
	v_max_i32_e32 v185, v70, v54
	v_max3_i32 v186, v65, v49, v186
	v_max_i32_e32 v184, v69, v53
	v_max3_i32 v0, v0, v187, v185
	v_max_i32_e32 v187, v71, v55
	v_max3_i32 v186, v186, v184, v187
	v_max_i32_e32 v187, v72, v56
	v_max_i32_e32 v185, v74, v58
	v_max_i32_e32 v184, v73, v57
	v_max3_i32 v0, v0, v187, v185
	v_max_i32_e32 v187, v75, v59
	v_max3_i32 v186, v186, v184, v187
	v_max_i32_e32 v187, v76, v60
	v_max_i32_e32 v185, v78, v62
	v_max_i32_e32 v184, v77, v61
	v_max3_i32 v0, v0, v187, v185
	v_max_i32_e32 v187, v79, v63
	v_max3_i32 v186, v186, v184, v187
	s_cmp_eq_u64 vcc, exec
	v_max3_i32 v195, v0, v186, 0
	s_cbranch_scc1 .LBB0_1615
	v_cndmask_b32_e64 v0, v239, v195, s[8:9]
	v_mov_b32_e32 v186, v0
	s_nop 1
	v_permlane32_swap_b32 v186, v0
	s_mov_b64 s[0:1], 0
	s_waitcnt lgkmcnt(0)
	v_max3_f32 v194, v193, v0, v186
	v_cmp_neq_f32_e32 vcc, s69, v194
	s_nop 1
	v_cndmask_b32_e32 v184, 0, v194, vcc
	v_mul_f32_e32 v0, 0xbe38aa3b, v184
	v_cndmask_b32_e64 v209, v239, v0, s[8:9]
	v_fmamk_f32 v0, v64, 0x3e38aa3b, v209
	v_fmamk_f32 v186, v48, 0x3e38aa3b, v209
	v_fmamk_f32 v187, v65, 0x3e38aa3b, v209
	v_exp_f32_e32 v166, v0
	v_exp_f32_e32 v227, v186
	v_fmamk_f32 v0, v49, 0x3e38aa3b, v209
	v_exp_f32_e32 v158, v187
	v_exp_f32_e32 v0, v0
	v_add_f32_e32 v159, v166, v227
	v_cvt_pk_bf16_f32 v210, v166, v158
	v_pk_add_f32 v[186:187], v[158:159], v[0:1]
	s_nop 0
	v_pk_add_f32 v[202:203], v[186:187], v[186:187] op_sel_hi:[0,1]
	v_fmamk_f32 v186, v66, 0x3e38aa3b, v209
	v_exp_f32_e32 v159, v186
	v_fmamk_f32 v186, v50, 0x3e38aa3b, v209
	v_exp_f32_e32 v229, v186
	v_fmamk_f32 v186, v67, 0x3e38aa3b, v209
	v_exp_f32_e32 v160, v186
	v_fmamk_f32 v186, v51, 0x3e38aa3b, v209
	v_exp_f32_e32 v202, v186
	v_add_f32_e32 v161, v159, v229
	v_cvt_pk_bf16_f32 v211, v159, v160
	v_pk_add_f32 v[186:187], v[160:161], v[202:203]
	s_nop 0
	v_pk_add_f32 v[214:215], v[186:187], v[186:187] op_sel_hi:[0,1]
	v_fmamk_f32 v186, v68, 0x3e38aa3b, v209
	v_exp_f32_e32 v161, v186
	v_fmamk_f32 v186, v52, 0x3e38aa3b, v209
	v_exp_f32_e32 v203, v186
	v_fmamk_f32 v186, v69, 0x3e38aa3b, v209
	v_exp_f32_e32 v162, v186
	v_fmamk_f32 v186, v53, 0x3e38aa3b, v209
	v_exp_f32_e32 v214, v186
	v_add_f32_e32 v163, v161, v203
	v_cvt_pk_bf16_f32 v212, v161, v162
	v_pk_add_f32 v[186:187], v[162:163], v[214:215]
	s_nop 0
	v_pk_add_f32 v[216:217], v[186:187], v[186:187] op_sel_hi:[0,1]
	v_fmamk_f32 v186, v70, 0x3e38aa3b, v209
	v_exp_f32_e32 v163, v186
	v_fmamk_f32 v186, v54, 0x3e38aa3b, v209
	v_exp_f32_e32 v215, v186
	v_fmamk_f32 v186, v71, 0x3e38aa3b, v209
	v_exp_f32_e32 v164, v186
	v_fmamk_f32 v186, v55, 0x3e38aa3b, v209
	v_exp_f32_e32 v216, v186
	v_add_f32_e32 v165, v163, v215
	v_cvt_pk_bf16_f32 v213, v163, v164
	v_pk_add_f32 v[186:187], v[164:165], v[216:217]
	s_nop 0
	v_pk_add_f32 v[218:219], v[186:187], v[186:187] op_sel_hi:[0,1]
	v_fmamk_f32 v186, v72, 0x3e38aa3b, v209
	v_exp_f32_e32 v217, v186
	v_fmamk_f32 v186, v56, 0x3e38aa3b, v209
	v_exp_f32_e32 v231, v186
	v_fmamk_f32 v186, v73, 0x3e38aa3b, v209
	v_exp_f32_e32 v220, v186
	v_fmamk_f32 v186, v57, 0x3e38aa3b, v209
	v_exp_f32_e32 v218, v186
	v_sub_f32_e32 v186, v193, v184
	v_add_f32_e32 v221, v217, v231
	v_mul_f32_e32 v184, 0x3e38aa3b, v186
	v_pk_add_f32 v[186:187], v[220:221], v[218:219]
	v_exp_f32_e32 v226, v184
	v_pk_add_f32 v[222:223], v[186:187], v[186:187] op_sel_hi:[0,1]
	v_fmamk_f32 v186, v74, 0x3e38aa3b, v209
	v_exp_f32_e32 v219, v186
	v_fmamk_f32 v186, v58, 0x3e38aa3b, v209
	v_exp_f32_e32 v232, v186
	v_fmamk_f32 v186, v75, 0x3e38aa3b, v209
	v_exp_f32_e32 v224, v186
	v_fmamk_f32 v186, v76, 0x3e38aa3b, v209
	v_exp_f32_e32 v233, v186
	v_fmamk_f32 v186, v77, 0x3e38aa3b, v209
	v_exp_f32_e32 v228, v186
	v_pk_mul_f32 v[16:17], v[16:17], v[226:227] op_sel_hi:[1,0]
	v_pk_mul_f32 v[32:33], v[32:33], v[226:227] op_sel_hi:[1,0]
	v_pk_mul_f32 v[18:19], v[18:19], v[226:227] op_sel_hi:[1,0]
	v_pk_mul_f32 v[20:21], v[20:21], v[226:227] op_sel_hi:[1,0]
	v_pk_mul_f32 v[22:23], v[22:23], v[226:227] op_sel_hi:[1,0]
	v_pk_mul_f32 v[24:25], v[24:25], v[226:227] op_sel_hi:[1,0]
	v_pk_mul_f32 v[26:27], v[26:27], v[226:227] op_sel_hi:[1,0]
	v_pk_mul_f32 v[28:29], v[28:29], v[226:227] op_sel_hi:[1,0]
	v_pk_mul_f32 v[30:31], v[30:31], v[226:227] op_sel_hi:[1,0]
	v_pk_mul_f32 v[34:35], v[34:35], v[226:227] op_sel_hi:[1,0]
	v_pk_mul_f32 v[36:37], v[36:37], v[226:227] op_sel_hi:[1,0]
	v_pk_mul_f32 v[38:39], v[38:39], v[226:227] op_sel_hi:[1,0]
	v_pk_mul_f32 v[40:41], v[40:41], v[226:227] op_sel_hi:[1,0]
	v_pk_mul_f32 v[42:43], v[42:43], v[226:227] op_sel_hi:[1,0]
	v_pk_mul_f32 v[44:45], v[44:45], v[226:227] op_sel_hi:[1,0]
	v_pk_mul_f32 v[46:47], v[46:47], v[226:227] op_sel_hi:[1,0]
	s_waitcnt vmcnt(15)
	v_mfma_f32_32x32x16_bf16 v[16:31], v[144:147], v[210:213], v[16:31]
	v_fmamk_f32 v221, v78, 0x3e38aa3b, v209
	v_exp_f32_e32 v241, v221
	v_add_f32_e32 v225, v219, v232
	s_waitcnt vmcnt(14)
	v_mfma_f32_32x32x16_bf16 v[32:47], v[140:143], v[210:213], v[32:47]
	v_fmamk_f32 v210, v79, 0x3e38aa3b, v209
	v_exp_f32_e32 v230, v210
	v_cvt_pk_bf16_f32 v210, v217, v220
	v_fmamk_f32 v217, v59, 0x3e38aa3b, v209
	v_cvt_pk_bf16_f32 v211, v219, v224
	v_cvt_pk_bf16_f32 v212, v233, v228
	v_cvt_pk_bf16_f32 v213, v241, v230
	v_exp_f32_e32 v222, v217
	v_fmamk_f32 v219, v61, 0x3e38aa3b, v209
	s_waitcnt vmcnt(13)
	v_mfma_f32_32x32x16_bf16 v[16:31], v[136:139], v[210:213], v[16:31]
	v_add_f32_e64 v220, v224, v222
	v_add_f32_e64 v221, v225, v223
	v_pk_add_f32 v[220:221], v[220:221], v[220:221] op_sel_hi:[0,1]
	v_exp_f32_e32 v220, v219
	s_waitcnt vmcnt(12)
	v_mfma_f32_32x32x16_bf16 v[32:47], v[132:135], v[210:213], v[32:47]
	v_fmamk_f32 v210, v60, 0x3e38aa3b, v209
	v_exp_f32_e32 v217, v210
	v_cvt_pk_bf16_f32 v210, v227, v0
	v_cvt_pk_bf16_f32 v211, v229, v202
	v_cvt_pk_bf16_f32 v212, v203, v214
	v_cvt_pk_bf16_f32 v213, v215, v216
	v_add_f32_e32 v229, v233, v217
	v_pk_add_f32 v[202:203], v[228:229], v[220:221]
	s_waitcnt vmcnt(11)
	v_mfma_f32_32x32x16_bf16 v[16:31], v[128:131], v[210:213], v[16:31]
	v_pk_add_f32 v[202:203], v[202:203], v[202:203] op_sel_hi:[0,1]
	v_fmamk_f32 v0, v62, 0x3e38aa3b, v209
	v_fmac_f32_e32 v209, 0x3e38aa3b, v63
	v_exp_f32_e32 v0, v0
	v_exp_f32_e32 v202, v209
	s_waitcnt vmcnt(10)
	v_mfma_f32_32x32x16_bf16 v[32:47], v[124:127], v[210:213], v[32:47]
	v_cvt_pk_bf16_f32 v210, v231, v218
	v_cvt_pk_bf16_f32 v211, v232, v222
	v_cvt_pk_bf16_f32 v212, v217, v220
	v_cvt_pk_bf16_f32 v213, v0, v202
	v_add_f32_e32 v231, v241, v0
	v_pk_add_f32 v[202:203], v[230:231], v[202:203]
	s_waitcnt vmcnt(9)
	v_mfma_f32_32x32x16_bf16 v[16:31], v[120:123], v[210:213], v[16:31]
	v_add_f32_e32 v0, v202, v203
	v_fmac_f32_e32 v0, v192, v226
	s_waitcnt vmcnt(8)
	v_mfma_f32_32x32x16_bf16 v[32:47], v[116:119], v[210:213], v[32:47]
.LBB0_1615:
	s_andn2_b64 vcc, exec, s[0:1]
	s_cbranch_vccnz .LBB0_1617
	v_mov_b32_e32 v0, v195
	s_nop 1
	v_permlane32_swap_b32 v0, v195
	s_waitcnt lgkmcnt(0)
	v_max3_f32 v194, v193, v195, v0
	v_cmp_neq_f32_e32 vcc, s69, v194
	s_nop 1
	v_cndmask_b32_e32 v184, 0, v194, vcc
	v_mul_f32_e32 v195, 0xbe38aa3b, v184
	v_fmamk_f32 v0, v64, 0x3e38aa3b, v195
	v_fmamk_f32 v186, v48, 0x3e38aa3b, v195
	v_fmamk_f32 v187, v65, 0x3e38aa3b, v195
	v_exp_f32_e32 v166, v0
	v_exp_f32_e32 v209, v186
	v_fmamk_f32 v0, v49, 0x3e38aa3b, v195
	v_exp_f32_e32 v158, v187
	v_exp_f32_e32 v0, v0
	v_add_f32_e32 v159, v166, v209
	v_cvt_pk_bf16_f32 v210, v166, v158
	v_pk_add_f32 v[186:187], v[158:159], v[0:1]
	s_nop 0
	v_pk_add_f32 v[202:203], v[186:187], v[186:187] op_sel_hi:[0,1]
	v_fmamk_f32 v186, v66, 0x3e38aa3b, v195
	v_exp_f32_e32 v159, v186
	v_fmamk_f32 v186, v50, 0x3e38aa3b, v195
	v_exp_f32_e32 v227, v186
	v_fmamk_f32 v186, v67, 0x3e38aa3b, v195
	v_exp_f32_e32 v160, v186
	v_fmamk_f32 v186, v51, 0x3e38aa3b, v195
	v_exp_f32_e32 v202, v186
	v_add_f32_e32 v161, v159, v227
	v_cvt_pk_bf16_f32 v211, v159, v160
	v_pk_add_f32 v[186:187], v[160:161], v[202:203]
	s_nop 0
	v_pk_add_f32 v[214:215], v[186:187], v[186:187] op_sel_hi:[0,1]
	v_fmamk_f32 v186, v68, 0x3e38aa3b, v195
	v_exp_f32_e32 v161, v186
	v_fmamk_f32 v186, v52, 0x3e38aa3b, v195
	v_exp_f32_e32 v203, v186
	v_fmamk_f32 v186, v69, 0x3e38aa3b, v195
	v_exp_f32_e32 v162, v186
	v_fmamk_f32 v186, v53, 0x3e38aa3b, v195
	v_exp_f32_e32 v214, v186
	v_add_f32_e32 v163, v161, v203
	v_cvt_pk_bf16_f32 v212, v161, v162
	v_pk_add_f32 v[186:187], v[162:163], v[214:215]
	s_nop 0
	v_pk_add_f32 v[216:217], v[186:187], v[186:187] op_sel_hi:[0,1]
	v_fmamk_f32 v186, v70, 0x3e38aa3b, v195
	v_exp_f32_e32 v163, v186
	v_fmamk_f32 v186, v54, 0x3e38aa3b, v195
	v_exp_f32_e32 v215, v186
	v_fmamk_f32 v186, v71, 0x3e38aa3b, v195
	v_exp_f32_e32 v164, v186
	v_fmamk_f32 v186, v55, 0x3e38aa3b, v195
	v_exp_f32_e32 v216, v186
	v_add_f32_e32 v165, v163, v215
	v_cvt_pk_bf16_f32 v213, v163, v164
	v_pk_add_f32 v[186:187], v[164:165], v[216:217]
	s_nop 0
	v_pk_add_f32 v[218:219], v[186:187], v[186:187] op_sel_hi:[0,1]
	v_fmamk_f32 v186, v72, 0x3e38aa3b, v195
	v_exp_f32_e32 v217, v186
	v_fmamk_f32 v186, v56, 0x3e38aa3b, v195
	v_exp_f32_e32 v231, v186
	v_fmamk_f32 v186, v73, 0x3e38aa3b, v195
	v_exp_f32_e32 v220, v186
	v_fmamk_f32 v186, v57, 0x3e38aa3b, v195
	v_exp_f32_e32 v218, v186
	v_sub_f32_e32 v186, v193, v184
	v_add_f32_e32 v221, v217, v231
	v_mul_f32_e32 v184, 0x3e38aa3b, v186
	v_pk_add_f32 v[186:187], v[220:221], v[218:219]
	v_exp_f32_e32 v226, v184
	v_pk_add_f32 v[222:223], v[186:187], v[186:187] op_sel_hi:[0,1]
	v_fmamk_f32 v186, v74, 0x3e38aa3b, v195
	v_exp_f32_e32 v219, v186
	v_fmamk_f32 v186, v58, 0x3e38aa3b, v195
	v_exp_f32_e32 v232, v186
	v_fmamk_f32 v186, v75, 0x3e38aa3b, v195
	v_exp_f32_e32 v224, v186
	v_fmamk_f32 v186, v76, 0x3e38aa3b, v195
	v_exp_f32_e32 v229, v186
	v_fmamk_f32 v186, v77, 0x3e38aa3b, v195
	v_exp_f32_e32 v228, v186
	v_pk_mul_f32 v[16:17], v[16:17], v[226:227] op_sel_hi:[1,0]
	v_pk_mul_f32 v[32:33], v[32:33], v[226:227] op_sel_hi:[1,0]
	v_pk_mul_f32 v[18:19], v[18:19], v[226:227] op_sel_hi:[1,0]
	v_pk_mul_f32 v[20:21], v[20:21], v[226:227] op_sel_hi:[1,0]
	v_pk_mul_f32 v[22:23], v[22:23], v[226:227] op_sel_hi:[1,0]
	v_pk_mul_f32 v[24:25], v[24:25], v[226:227] op_sel_hi:[1,0]
	v_pk_mul_f32 v[26:27], v[26:27], v[226:227] op_sel_hi:[1,0]
	v_pk_mul_f32 v[28:29], v[28:29], v[226:227] op_sel_hi:[1,0]
	v_pk_mul_f32 v[30:31], v[30:31], v[226:227] op_sel_hi:[1,0]
	v_pk_mul_f32 v[34:35], v[34:35], v[226:227] op_sel_hi:[1,0]
	v_pk_mul_f32 v[36:37], v[36:37], v[226:227] op_sel_hi:[1,0]
	v_pk_mul_f32 v[38:39], v[38:39], v[226:227] op_sel_hi:[1,0]
	v_pk_mul_f32 v[40:41], v[40:41], v[226:227] op_sel_hi:[1,0]
	v_pk_mul_f32 v[42:43], v[42:43], v[226:227] op_sel_hi:[1,0]
	v_pk_mul_f32 v[44:45], v[44:45], v[226:227] op_sel_hi:[1,0]
	v_pk_mul_f32 v[46:47], v[46:47], v[226:227] op_sel_hi:[1,0]
	s_waitcnt vmcnt(15)
	v_mfma_f32_32x32x16_bf16 v[16:31], v[144:147], v[210:213], v[16:31]
	v_fmamk_f32 v221, v78, 0x3e38aa3b, v195
	v_exp_f32_e32 v233, v221
	v_add_f32_e32 v225, v219, v232
	s_waitcnt vmcnt(14)
	v_mfma_f32_32x32x16_bf16 v[32:47], v[140:143], v[210:213], v[32:47]
	v_fmamk_f32 v210, v79, 0x3e38aa3b, v195
	v_exp_f32_e32 v230, v210
	v_cvt_pk_bf16_f32 v210, v217, v220
	v_fmamk_f32 v217, v59, 0x3e38aa3b, v195
	v_cvt_pk_bf16_f32 v211, v219, v224
	v_cvt_pk_bf16_f32 v212, v229, v228
	v_cvt_pk_bf16_f32 v213, v233, v230
	v_exp_f32_e32 v222, v217
	v_fmamk_f32 v219, v61, 0x3e38aa3b, v195
	s_waitcnt vmcnt(13)
	v_mfma_f32_32x32x16_bf16 v[16:31], v[136:139], v[210:213], v[16:31]
	v_add_f32_e64 v220, v224, v222
	v_add_f32_e64 v221, v225, v223
	v_pk_add_f32 v[220:221], v[220:221], v[220:221] op_sel_hi:[0,1]
	v_exp_f32_e32 v220, v219
	s_waitcnt vmcnt(12)
	v_mfma_f32_32x32x16_bf16 v[32:47], v[132:135], v[210:213], v[32:47]
	v_fmamk_f32 v210, v60, 0x3e38aa3b, v195
	v_exp_f32_e32 v217, v210
	v_cvt_pk_bf16_f32 v210, v209, v0
	v_cvt_pk_bf16_f32 v211, v227, v202
	v_cvt_pk_bf16_f32 v212, v203, v214
	v_cvt_pk_bf16_f32 v213, v215, v216
	v_add_f32_e32 v229, v229, v217
	v_pk_add_f32 v[202:203], v[228:229], v[220:221]
	s_waitcnt vmcnt(11)
	v_mfma_f32_32x32x16_bf16 v[16:31], v[128:131], v[210:213], v[16:31]
	v_pk_add_f32 v[202:203], v[202:203], v[202:203] op_sel_hi:[0,1]
	v_fmamk_f32 v0, v62, 0x3e38aa3b, v195
	v_fmac_f32_e32 v195, 0x3e38aa3b, v63
	v_exp_f32_e32 v0, v0
	v_exp_f32_e32 v202, v195
	s_waitcnt vmcnt(10)
	v_mfma_f32_32x32x16_bf16 v[32:47], v[124:127], v[210:213], v[32:47]
	v_cvt_pk_bf16_f32 v210, v231, v218
	v_cvt_pk_bf16_f32 v211, v232, v222
	v_cvt_pk_bf16_f32 v212, v217, v220
	v_cvt_pk_bf16_f32 v213, v0, v202
	v_add_f32_e32 v231, v233, v0
	v_pk_add_f32 v[202:203], v[230:231], v[202:203]
	s_waitcnt vmcnt(9)
	v_mfma_f32_32x32x16_bf16 v[16:31], v[120:123], v[210:213], v[16:31]
	v_add_f32_e32 v0, v202, v203
	v_fmac_f32_e32 v0, v192, v226
	s_waitcnt vmcnt(8)
	v_mfma_f32_32x32x16_bf16 v[32:47], v[116:119], v[210:213], v[32:47]

.LBB0_1620:
	v_add_u32_e32 v0, s4, v208
	v_cmp_le_i32_e32 vcc, v0, v197
	v_cmp_le_i32_e64 s[0:1], v0, v191
	s_and_b64 vcc, s[8:9], vcc
	s_nop 2
	v_cndmask_b32_e32 v186, v239, v64, vcc
	s_and_b64 vcc, s[8:9], s[0:1]
	v_cndmask_b32_e32 v187, v239, v48, vcc
	v_cmp_lt_i32_e32 vcc, v0, v197
	v_cmp_lt_i32_e64 s[0:1], v0, v191
	s_and_b64 vcc, s[8:9], vcc
	v_cndmask_b32_e32 v184, v239, v65, vcc
	s_and_b64 vcc, s[8:9], s[0:1]
	v_or_b32_e32 v182, 2, v0
	v_cndmask_b32_e32 v185, v239, v49, vcc
	v_cmp_le_i32_e32 vcc, v182, v197
	v_cmp_le_i32_e64 s[0:1], v182, v191
	s_and_b64 vcc, s[8:9], vcc
	v_cndmask_b32_e32 v182, v239, v66, vcc
	s_and_b64 vcc, s[8:9], s[0:1]
	v_or_b32_e32 v180, 3, v0
	v_cndmask_b32_e32 v183, v239, v50, vcc
	v_cmp_le_i32_e32 vcc, v180, v197
	v_cmp_le_i32_e64 s[0:1], v180, v191
	s_and_b64 vcc, s[8:9], vcc
	v_cndmask_b32_e32 v180, v239, v67, vcc
	s_and_b64 vcc, s[8:9], s[0:1]
	v_add_u32_e32 v178, 8, v0
	v_cndmask_b32_e32 v181, v239, v51, vcc
	v_cmp_le_i32_e32 vcc, v178, v197
	v_cmp_le_i32_e64 s[0:1], v178, v191
	s_and_b64 vcc, s[8:9], vcc
	v_cndmask_b32_e32 v178, v239, v68, vcc
	s_and_b64 vcc, s[8:9], s[0:1]
	v_add_u32_e32 v176, 9, v0
	v_cndmask_b32_e32 v179, v239, v52, vcc
	v_cmp_le_i32_e32 vcc, v176, v197
	v_cmp_le_i32_e64 s[0:1], v176, v191
	s_and_b64 vcc, s[8:9], vcc
	v_cndmask_b32_e32 v176, v239, v69, vcc
	s_and_b64 vcc, s[8:9], s[0:1]
	v_add_u32_e32 v174, 10, v0
	v_cndmask_b32_e32 v177, v239, v53, vcc
	v_cmp_le_i32_e32 vcc, v174, v197
	v_cmp_le_i32_e64 s[0:1], v174, v191
	s_and_b64 vcc, s[8:9], vcc
	v_cndmask_b32_e32 v174, v239, v70, vcc
	s_and_b64 vcc, s[8:9], s[0:1]
	v_add_u32_e32 v172, 11, v0
	v_cndmask_b32_e32 v175, v239, v54, vcc
	v_cmp_le_i32_e32 vcc, v172, v197
	v_cmp_le_i32_e64 s[0:1], v172, v191
	s_and_b64 vcc, s[8:9], vcc
	v_cndmask_b32_e32 v172, v239, v71, vcc
	s_and_b64 vcc, s[8:9], s[0:1]
	v_add_u32_e32 v188, 16, v0
	v_cndmask_b32_e32 v173, v239, v55, vcc
	v_cmp_le_i32_e32 vcc, v188, v197
	v_cmp_le_i32_e64 s[0:1], v188, v191
	s_and_b64 vcc, s[8:9], vcc
	v_cndmask_b32_e32 v188, v239, v72, vcc
	s_and_b64 vcc, s[8:9], s[0:1]
	v_add_u32_e32 v158, 17, v0
	v_cndmask_b32_e32 v189, v239, v56, vcc
	v_cmp_le_i32_e32 vcc, v158, v197
	v_cmp_le_i32_e64 s[0:1], v158, v191
	s_and_b64 vcc, s[8:9], vcc
	v_cndmask_b32_e32 v166, v239, v73, vcc
	s_and_b64 vcc, s[8:9], s[0:1]
	v_add_u32_e32 v158, 18, v0
	v_cndmask_b32_e32 v167, v239, v57, vcc
	v_cmp_le_i32_e32 vcc, v158, v197
	v_cmp_le_i32_e64 s[0:1], v158, v191
	s_and_b64 vcc, s[8:9], vcc
	v_cndmask_b32_e32 v168, v239, v74, vcc
	s_and_b64 vcc, s[8:9], s[0:1]
	v_add_u32_e32 v158, 19, v0
	v_cndmask_b32_e32 v169, v239, v58, vcc
	v_cmp_le_i32_e32 vcc, v158, v197
	v_cmp_le_i32_e64 s[0:1], v158, v191
	s_and_b64 vcc, s[8:9], vcc
	v_cndmask_b32_e32 v170, v239, v75, vcc
	s_and_b64 vcc, s[8:9], s[0:1]
	v_add_u32_e32 v158, 24, v0
	v_cndmask_b32_e32 v65, v239, v59, vcc
	v_cmp_le_i32_e32 vcc, v158, v197
	v_cmp_le_i32_e64 s[0:1], v158, v191
	s_and_b64 vcc, s[8:9], vcc
	v_cndmask_b32_e32 v171, v239, v76, vcc
	s_and_b64 vcc, s[8:9], s[0:1]
	v_add_u32_e32 v158, 25, v0
	v_cndmask_b32_e32 v67, v239, v60, vcc
	v_cmp_le_i32_e32 vcc, v158, v197
	v_cmp_le_i32_e64 s[0:1], v158, v191
	s_and_b64 vcc, s[8:9], vcc
	v_cndmask_b32_e32 v48, v239, v77, vcc
	s_and_b64 vcc, s[8:9], s[0:1]
	v_add_u32_e32 v158, 26, v0
	v_cndmask_b32_e32 v69, v239, v61, vcc
	v_cmp_le_i32_e32 vcc, v158, v197
	v_cmp_le_i32_e64 s[0:1], v158, v191
	s_and_b64 vcc, s[8:9], vcc
	v_cndmask_b32_e32 v49, v239, v78, vcc
	s_and_b64 vcc, s[8:9], s[0:1]
	v_add_u32_e32 v0, 27, v0
	v_cndmask_b32_e32 v71, v239, v62, vcc
	v_cmp_le_i32_e32 vcc, v0, v197
	v_cmp_le_i32_e64 s[0:1], v0, v191
	v_max_i32_e32 v0, v182, v183
	v_max3_i32 v0, v186, v187, v0
	v_max_i32_e32 v158, v180, v181
	v_max_i32_e32 v159, v178, v179
	v_max_i32_e32 v161, v174, v175
	v_max3_i32 v158, v184, v185, v158
	v_max_i32_e32 v160, v176, v177
	v_max3_i32 v0, v0, v159, v161
	v_max_i32_e32 v159, v172, v173
	s_and_b64 vcc, s[8:9], vcc
	v_max3_i32 v158, v158, v160, v159
	v_max_i32_e32 v159, v188, v189
	v_max_i32_e32 v161, v168, v169
	v_cndmask_b32_e32 v70, v239, v79, vcc
	s_and_b64 vcc, s[8:9], s[0:1]
	v_max_i32_e32 v160, v166, v167
	v_max3_i32 v0, v0, v159, v161
	v_max_i32_e32 v159, v170, v65
	v_cndmask_b32_e32 v72, v239, v63, vcc
	v_max3_i32 v158, v158, v160, v159
	v_max_i32_e32 v159, v171, v67
	v_max_i32_e32 v161, v49, v71
	v_max_i32_e32 v160, v48, v69
	v_max3_i32 v0, v0, v159, v161
	v_max_i32_e32 v159, v70, v72
	v_max3_i32 v158, v158, v160, v159
	v_max3_i32 v0, v0, v158, 0
	v_mov_b32_e32 v158, v0
	s_nop 1
	v_permlane32_swap_b32 v158, v0
	s_waitcnt lgkmcnt(0)
	v_max3_f32 v194, v193, v0, v158
	v_cmp_neq_f32_e32 vcc, s69, v194
	s_nop 1
	v_cndmask_b32_e32 v50, 0, v194, vcc
	v_mul_f32_e32 v73, 0xbe38aa3b, v50
	v_fmamk_f32 v0, v186, 0x3e38aa3b, v73
	v_exp_f32_e32 v51, v0
	v_fmamk_f32 v0, v187, 0x3e38aa3b, v73
	v_exp_f32_e32 v74, v0
	v_fmamk_f32 v0, v184, 0x3e38aa3b, v73
	v_exp_f32_e32 v158, v0
	v_fmamk_f32 v0, v185, 0x3e38aa3b, v73
	v_exp_f32_e32 v0, v0
	v_add_f32_e32 v159, v51, v74
	v_pk_add_f32 v[186:187], v[158:159], v[0:1]
	s_nop 0
	v_pk_add_f32 v[52:53], v[186:187], v[186:187] op_sel_hi:[0,1]
	v_fmamk_f32 v186, v182, 0x3e38aa3b, v73
	v_exp_f32_e32 v159, v186
	v_fmamk_f32 v186, v183, 0x3e38aa3b, v73
	v_exp_f32_e32 v75, v186
	v_fmamk_f32 v186, v180, 0x3e38aa3b, v73
	v_exp_f32_e32 v160, v186
	v_fmamk_f32 v186, v181, 0x3e38aa3b, v73
	v_exp_f32_e32 v52, v186
	v_add_f32_e32 v161, v159, v75
	v_pk_add_f32 v[186:187], v[160:161], v[52:53]
	s_nop 0
	v_pk_add_f32 v[54:55], v[186:187], v[186:187] op_sel_hi:[0,1]
	v_fmamk_f32 v186, v178, 0x3e38aa3b, v73
	v_exp_f32_e32 v161, v186
	v_fmamk_f32 v186, v179, 0x3e38aa3b, v73
	v_exp_f32_e32 v53, v186
	v_fmamk_f32 v186, v176, 0x3e38aa3b, v73
	v_exp_f32_e32 v162, v186
	v_fmamk_f32 v186, v177, 0x3e38aa3b, v73
	v_exp_f32_e32 v54, v186
	v_add_f32_e32 v163, v161, v53
	v_pk_add_f32 v[186:187], v[162:163], v[54:55]
	s_nop 0
	v_pk_add_f32 v[56:57], v[186:187], v[186:187] op_sel_hi:[0,1]
	v_fmamk_f32 v186, v174, 0x3e38aa3b, v73
	v_exp_f32_e32 v163, v186
	v_fmamk_f32 v186, v175, 0x3e38aa3b, v73
	v_exp_f32_e32 v55, v186
	v_fmamk_f32 v186, v172, 0x3e38aa3b, v73
	v_exp_f32_e32 v164, v186
	v_fmamk_f32 v186, v173, 0x3e38aa3b, v73
	v_exp_f32_e32 v56, v186
	v_add_f32_e32 v165, v163, v55
	v_pk_add_f32 v[186:187], v[164:165], v[56:57]
	s_nop 0
	v_pk_add_f32 v[58:59], v[186:187], v[186:187] op_sel_hi:[0,1]
	v_fmamk_f32 v186, v188, 0x3e38aa3b, v73
	v_exp_f32_e32 v57, v186
	v_fmamk_f32 v186, v189, 0x3e38aa3b, v73
	v_exp_f32_e32 v76, v186
	v_fmamk_f32 v186, v166, 0x3e38aa3b, v73
	v_exp_f32_e32 v60, v186
	v_fmamk_f32 v186, v167, 0x3e38aa3b, v73
	v_exp_f32_e32 v58, v186
	v_sub_f32_e32 v186, v193, v50
	v_add_f32_e32 v61, v57, v76
	v_mul_f32_e32 v184, 0x3e38aa3b, v186
	v_pk_add_f32 v[186:187], v[60:61], v[58:59]
	v_exp_f32_e32 v66, v184
	v_pk_add_f32 v[62:63], v[186:187], v[186:187] op_sel_hi:[0,1]
	v_fmamk_f32 v186, v168, 0x3e38aa3b, v73
	v_exp_f32_e32 v59, v186
	v_fmamk_f32 v186, v169, 0x3e38aa3b, v73
	v_exp_f32_e32 v77, v186
	v_fmamk_f32 v186, v170, 0x3e38aa3b, v73
	v_exp_f32_e32 v64, v186
	v_fmamk_f32 v186, v171, 0x3e38aa3b, v73
	v_exp_f32_e32 v78, v186
	v_fmamk_f32 v186, v48, 0x3e38aa3b, v73
	v_exp_f32_e32 v68, v186
	v_fmamk_f32 v61, v49, 0x3e38aa3b, v73
	v_pk_mul_f32 v[16:17], v[16:17], v[66:67] op_sel_hi:[1,0]
	v_pk_mul_f32 v[32:33], v[32:33], v[66:67] op_sel_hi:[1,0]
	v_pk_mul_f32 v[18:19], v[18:19], v[66:67] op_sel_hi:[1,0]
	v_pk_mul_f32 v[20:21], v[20:21], v[66:67] op_sel_hi:[1,0]
	v_pk_mul_f32 v[22:23], v[22:23], v[66:67] op_sel_hi:[1,0]
	v_pk_mul_f32 v[24:25], v[24:25], v[66:67] op_sel_hi:[1,0]
	v_pk_mul_f32 v[26:27], v[26:27], v[66:67] op_sel_hi:[1,0]
	v_pk_mul_f32 v[28:29], v[28:29], v[66:67] op_sel_hi:[1,0]
	v_pk_mul_f32 v[30:31], v[30:31], v[66:67] op_sel_hi:[1,0]
	v_cvt_pk_bf16_f32 v48, v51, v158
	v_cvt_pk_bf16_f32 v49, v159, v160
	v_cvt_pk_bf16_f32 v50, v161, v162
	v_cvt_pk_bf16_f32 v51, v163, v164
	v_pk_mul_f32 v[34:35], v[34:35], v[66:67] op_sel_hi:[1,0]
	v_pk_mul_f32 v[36:37], v[36:37], v[66:67] op_sel_hi:[1,0]
	v_pk_mul_f32 v[38:39], v[38:39], v[66:67] op_sel_hi:[1,0]
	v_pk_mul_f32 v[40:41], v[40:41], v[66:67] op_sel_hi:[1,0]
	v_pk_mul_f32 v[42:43], v[42:43], v[66:67] op_sel_hi:[1,0]
	v_pk_mul_f32 v[44:45], v[44:45], v[66:67] op_sel_hi:[1,0]
	v_pk_mul_f32 v[46:47], v[46:47], v[66:67] op_sel_hi:[1,0]
	s_waitcnt vmcnt(15)
	v_mfma_f32_32x32x16_bf16 v[16:31], v[144:147], v[48:51], v[16:31]
	v_exp_f32_e32 v79, v61
	s_waitcnt vmcnt(14)
	v_mfma_f32_32x32x16_bf16 v[32:47], v[140:143], v[48:51], v[32:47]
	v_fmamk_f32 v48, v70, 0x3e38aa3b, v73
	v_exp_f32_e32 v70, v48
	v_cvt_pk_bf16_f32 v48, v57, v60
	v_fmamk_f32 v57, v65, 0x3e38aa3b, v73
	v_cvt_pk_bf16_f32 v49, v59, v64
	v_cvt_pk_bf16_f32 v50, v78, v68
	v_cvt_pk_bf16_f32 v51, v79, v70
	v_exp_f32_e32 v62, v57
	v_add_f32_e32 v65, v59, v77
	s_waitcnt vmcnt(13)
	v_mfma_f32_32x32x16_bf16 v[16:31], v[136:139], v[48:51], v[16:31]
	v_fmamk_f32 v59, v69, 0x3e38aa3b, v73
	v_add_f32_e64 v60, v64, v62
	v_add_f32_e64 v61, v65, v63
	v_pk_add_f32 v[60:61], v[60:61], v[60:61] op_sel_hi:[0,1]
	v_exp_f32_e32 v60, v59
	s_waitcnt vmcnt(12)
	v_mfma_f32_32x32x16_bf16 v[32:47], v[132:135], v[48:51], v[32:47]
	v_fmamk_f32 v48, v67, 0x3e38aa3b, v73
	v_exp_f32_e32 v57, v48
	v_cvt_pk_bf16_f32 v48, v74, v0
	v_cvt_pk_bf16_f32 v49, v75, v52
	v_cvt_pk_bf16_f32 v50, v53, v54
	v_cvt_pk_bf16_f32 v51, v55, v56
	v_add_f32_e32 v69, v78, v57
	v_pk_add_f32 v[52:53], v[68:69], v[60:61]
	s_waitcnt vmcnt(11)
	v_mfma_f32_32x32x16_bf16 v[16:31], v[128:131], v[48:51], v[16:31]
	v_pk_add_f32 v[52:53], v[52:53], v[52:53] op_sel_hi:[0,1]
	v_fmamk_f32 v0, v71, 0x3e38aa3b, v73
	v_fmac_f32_e32 v73, 0x3e38aa3b, v72
	v_exp_f32_e32 v0, v0
	v_exp_f32_e32 v52, v73
	v_add_f32_e32 v71, v79, v0
	s_waitcnt vmcnt(10)
	v_mfma_f32_32x32x16_bf16 v[32:47], v[124:127], v[48:51], v[32:47]
	v_cvt_pk_bf16_f32 v48, v76, v58
	v_cvt_pk_bf16_f32 v49, v77, v62
	v_cvt_pk_bf16_f32 v50, v57, v60
	v_cvt_pk_bf16_f32 v51, v0, v52
	v_add_f32_e64 v52, v70, v52
	v_add_f32_e64 v53, v71, v53
	v_add_f32_e32 v0, v52, v53
	s_waitcnt vmcnt(9)
	v_mfma_f32_32x32x16_bf16 v[16:31], v[120:123], v[48:51], v[16:31]
	v_fmac_f32_e32 v0, v192, v66
	s_waitcnt vmcnt(8)
	v_mfma_f32_32x32x16_bf16 v[32:47], v[116:119], v[48:51], v[32:47]
	s_xor_b64 s[0:1], s[22:23], -1
	s_andn2_b64 vcc, exec, s[0:1]
	s_cbranch_vccz .LBB0_1623

.LBB0_1623:
	s_waitcnt vmcnt(7)
	v_mov_b32_e32 v2, v0
	s_nop 1
	v_permlane32_swap_b32 v2, v0
	s_lshl_b64 s[8:9], s[18:19], 1
	s_waitcnt lgkmcnt(0)
	v_add_f32_e32 v0, v0, v2
	global_load_dword v2, v[150:151], off offset:4
	v_max_f32_e32 v0, 0xda24260, v0
	s_waitcnt vmcnt(0)
	v_div_scale_f32 v3, s[0:1], v0, v0, v2
	v_rcp_f32_e32 v4, v3
	v_readlane_b32 s0, v255, 24
	s_add_u32 s4, s0, s8
	v_readlane_b32 s0, v255, 25
	v_fma_f32 v5, -v3, v4, 1.0
	v_fmac_f32_e32 v4, v5, v4
	v_div_scale_f32 v5, vcc, v2, v0, v2
	v_mul_f32_e32 v6, v5, v4
	v_fma_f32 v7, -v3, v6, v5
	v_fmac_f32_e32 v6, v7, v4
	v_fma_f32 v3, -v3, v6, v5
	v_div_fmas_f32 v3, v3, v4, v6
	v_div_fixup_f32 v0, v3, v0, v2
	ds_read2st64_b32 v[2:3], v206 offset0:4 offset1:5
	ds_read2st64_b32 v[4:5], v206 offset0:20 offset1:21
	s_addc_u32 s5, s0, s9
	s_max_i32 s0, s89, 0x1ff
	s_addk_i32 s0, 0xfe01
	s_waitcnt lgkmcnt(1)
	v_fma_f32 v2, v16, v0, v2
	s_waitcnt lgkmcnt(0)
	v_fma_f32 v4, v32, v0, v4
	v_fmac_f32_e32 v3, v17, v0
	v_fmac_f32_e32 v5, v33, v0
	ds_write2st64_b32 v206, v2, v3 offset0:4 offset1:5
	ds_write2st64_b32 v206, v4, v5 offset0:20 offset1:21
	ds_read2st64_b32 v[2:3], v206 offset0:6 offset1:7
	ds_read2st64_b32 v[4:5], v206 offset0:22 offset1:23
	s_lshr_b32 s0, s0, 6
	s_cmp_gt_u32 s0, s48
	s_waitcnt lgkmcnt(1)
	v_fma_f32 v2, v18, v0, v2
	s_waitcnt lgkmcnt(0)
	v_fma_f32 v4, v34, v0, v4
	v_fmac_f32_e32 v3, v19, v0
	v_fmac_f32_e32 v5, v35, v0
	ds_write2st64_b32 v206, v2, v3 offset0:6 offset1:7
	ds_write2st64_b32 v206, v4, v5 offset0:22 offset1:23
	ds_read2st64_b32 v[2:3], v206 offset0:8 offset1:9
	ds_read2st64_b32 v[4:5], v206 offset0:24 offset1:25
	s_waitcnt lgkmcnt(1)
	v_fma_f32 v2, v20, v0, v2
	s_waitcnt lgkmcnt(0)
	v_fma_f32 v4, v36, v0, v4
	v_fmac_f32_e32 v3, v21, v0
	v_fmac_f32_e32 v5, v37, v0
	ds_write2st64_b32 v206, v2, v3 offset0:8 offset1:9
	ds_write2st64_b32 v206, v4, v5 offset0:24 offset1:25
	ds_read2st64_b32 v[2:3], v206 offset0:10 offset1:11
	ds_read2st64_b32 v[4:5], v206 offset0:26 offset1:27
	s_waitcnt lgkmcnt(1)
	v_fma_f32 v2, v22, v0, v2
	s_waitcnt lgkmcnt(0)
	v_fma_f32 v4, v38, v0, v4
	v_fmac_f32_e32 v3, v23, v0
	v_fmac_f32_e32 v5, v39, v0
	ds_write2st64_b32 v206, v2, v3 offset0:10 offset1:11
	ds_write2st64_b32 v206, v4, v5 offset0:26 offset1:27
	ds_read2st64_b32 v[2:3], v206 offset0:12 offset1:13
	ds_read2st64_b32 v[4:5], v206 offset0:28 offset1:29
	s_waitcnt lgkmcnt(1)
	v_fma_f32 v2, v24, v0, v2
	s_waitcnt lgkmcnt(0)
	v_fma_f32 v4, v40, v0, v4
	v_fmac_f32_e32 v3, v25, v0
	v_fmac_f32_e32 v5, v41, v0
	ds_write2st64_b32 v206, v2, v3 offset0:12 offset1:13
	ds_write2st64_b32 v206, v4, v5 offset0:28 offset1:29
	ds_read2st64_b32 v[2:3], v206 offset0:14 offset1:15
	ds_read2st64_b32 v[4:5], v206 offset0:30 offset1:31
	s_waitcnt lgkmcnt(1)
	v_fma_f32 v2, v26, v0, v2
	s_waitcnt lgkmcnt(0)
	v_fma_f32 v4, v42, v0, v4
	v_fmac_f32_e32 v3, v27, v0
	v_fmac_f32_e32 v5, v43, v0
	ds_write2st64_b32 v206, v2, v3 offset0:14 offset1:15
	ds_write2st64_b32 v206, v4, v5 offset0:30 offset1:31
	ds_read2st64_b32 v[2:3], v206 offset0:16 offset1:17
	ds_read2st64_b32 v[4:5], v206 offset0:32 offset1:33
	s_waitcnt lgkmcnt(1)
	v_fma_f32 v2, v28, v0, v2
	s_waitcnt lgkmcnt(0)
	v_fma_f32 v4, v44, v0, v4
	v_fmac_f32_e32 v3, v29, v0
	v_fmac_f32_e32 v5, v45, v0
	ds_write2st64_b32 v206, v2, v3 offset0:16 offset1:17
	ds_write2st64_b32 v206, v4, v5 offset0:32 offset1:33
	ds_read2st64_b32 v[2:3], v206 offset0:18 offset1:19
	ds_read2st64_b32 v[4:5], v206 offset0:34 offset1:35
	s_waitcnt lgkmcnt(1)
	v_fma_f32 v2, v30, v0, v2
	s_waitcnt lgkmcnt(0)
	v_fma_f32 v4, v46, v0, v4
	v_fmac_f32_e32 v3, v31, v0
	v_fmac_f32_e32 v5, v47, v0
	ds_write2st64_b32 v206, v2, v3 offset0:18 offset1:19
	ds_write2st64_b32 v206, v4, v5 offset0:34 offset1:35
	s_waitcnt lgkmcnt(0)
	s_cbranch_scc0 .LBB0_1626
	s_cmp_gt_i32 s0, s48
	s_cbranch_scc1 .LBB0_1490
	s_branch .LBB0_1631

.LBB0_1638:
	s_lshl_b32 s4, s0, 6
	s_or_b32 s0, s4, 63
	s_cmp_le_i32 s0, s89
	s_cselect_b64 s[0:1], -1, 0
	s_cmp_gt_i32 s4, s22
	s_cselect_b64 s[2:3], -1, 0
	s_and_b64 s[0:1], s[0:1], s[2:3]
	s_andn2_b64 vcc, exec, s[0:1]
	s_mov_b64 s[0:1], -1
	s_cbranch_vccz .LBB0_1641
	v_add_u32_e32 v0, s4, v208
	v_add_u32_e32 v172, 32, v0
	v_cmp_le_i32_e32 vcc, v0, v197
	v_cmp_gt_i32_e64 s[0:1], v0, v209
	s_and_b64 vcc, vcc, s[0:1]
	v_cmp_le_i32_e64 s[0:1], v172, v197
	v_cmp_gt_i32_e64 s[8:9], v172, v209
	s_and_b64 s[0:1], s[0:1], s[8:9]
	v_cndmask_b32_e32 v172, v239, v18, vcc
	v_cndmask_b32_e64 v173, v239, v2, s[0:1]
	v_add_u32_e32 v168, 33, v0
	v_cmp_lt_i32_e32 vcc, v0, v197
	v_cmp_ge_i32_e64 s[0:1], v0, v209
	s_and_b64 vcc, vcc, s[0:1]
	v_cmp_le_i32_e64 s[0:1], v168, v197
	v_cmp_gt_i32_e64 s[8:9], v168, v209
	s_and_b64 s[0:1], s[0:1], s[8:9]
	v_or_b32_e32 v164, 2, v0
	v_cndmask_b32_e32 v168, v239, v19, vcc
	v_cndmask_b32_e64 v169, v239, v3, s[0:1]
	v_add_u32_e32 v165, 34, v0
	v_cmp_le_i32_e32 vcc, v164, v197
	v_cmp_gt_i32_e64 s[0:1], v164, v209
	s_and_b64 vcc, vcc, s[0:1]
	v_cmp_le_i32_e64 s[0:1], v165, v197
	v_cmp_gt_i32_e64 s[8:9], v165, v209
	s_and_b64 s[0:1], s[0:1], s[8:9]
	v_or_b32_e32 v162, 3, v0
	v_cndmask_b32_e32 v164, v239, v20, vcc
	v_cndmask_b32_e64 v165, v239, v4, s[0:1]
	v_add_u32_e32 v163, 35, v0
	v_cmp_le_i32_e32 vcc, v162, v197
	v_cmp_gt_i32_e64 s[0:1], v162, v209
	s_and_b64 vcc, vcc, s[0:1]
	v_cmp_le_i32_e64 s[0:1], v163, v197
	v_cmp_gt_i32_e64 s[8:9], v163, v209
	s_and_b64 s[0:1], s[0:1], s[8:9]
	v_add_u32_e32 v160, 8, v0
	v_cndmask_b32_e32 v162, v239, v21, vcc
	v_cndmask_b32_e64 v163, v239, v5, s[0:1]
	v_add_u32_e32 v161, 40, v0
	v_cmp_le_i32_e32 vcc, v160, v197
	v_cmp_gt_i32_e64 s[0:1], v160, v209
	s_and_b64 vcc, vcc, s[0:1]
	v_cmp_le_i32_e64 s[0:1], v161, v197
	v_cmp_gt_i32_e64 s[8:9], v161, v209
	s_and_b64 s[0:1], s[0:1], s[8:9]
	v_add_u32_e32 v158, 9, v0
	v_cndmask_b32_e32 v160, v239, v22, vcc
	v_cndmask_b32_e64 v161, v239, v6, s[0:1]
	v_add_u32_e32 v159, 41, v0
	v_cmp_le_i32_e32 vcc, v158, v197
	v_cmp_gt_i32_e64 s[0:1], v158, v209
	s_and_b64 vcc, vcc, s[0:1]
	v_cmp_le_i32_e64 s[0:1], v159, v197
	v_cmp_gt_i32_e64 s[8:9], v159, v209
	s_and_b64 s[0:1], s[0:1], s[8:9]
	v_add_u32_e32 v156, 10, v0
	v_cndmask_b32_e32 v158, v239, v23, vcc
	v_cndmask_b32_e64 v159, v239, v7, s[0:1]
	v_add_u32_e32 v157, 42, v0
	v_cmp_le_i32_e32 vcc, v156, v197
	v_cmp_gt_i32_e64 s[0:1], v156, v209
	s_and_b64 vcc, vcc, s[0:1]
	v_cmp_le_i32_e64 s[0:1], v157, v197
	v_cmp_gt_i32_e64 s[8:9], v157, v209
	s_and_b64 s[0:1], s[0:1], s[8:9]
	v_add_u32_e32 v154, 11, v0
	v_cndmask_b32_e32 v156, v239, v24, vcc
	v_cndmask_b32_e64 v157, v239, v8, s[0:1]
	v_add_u32_e32 v155, 43, v0
	v_cmp_le_i32_e32 vcc, v154, v197
	v_cmp_gt_i32_e64 s[0:1], v154, v209
	s_and_b64 vcc, vcc, s[0:1]
	v_cmp_le_i32_e64 s[0:1], v155, v197
	v_cmp_gt_i32_e64 s[8:9], v155, v209
	s_and_b64 s[0:1], s[0:1], s[8:9]
	v_add_u32_e32 v184, 16, v0
	v_cndmask_b32_e32 v154, v239, v25, vcc
	v_cndmask_b32_e64 v155, v239, v9, s[0:1]
	v_add_u32_e32 v185, 48, v0
	v_cmp_le_i32_e32 vcc, v184, v197
	v_cmp_gt_i32_e64 s[0:1], v184, v209
	s_and_b64 vcc, vcc, s[0:1]
	v_cmp_le_i32_e64 s[0:1], v185, v197
	v_cmp_gt_i32_e64 s[8:9], v185, v209
	s_and_b64 s[0:1], s[0:1], s[8:9]
	v_add_u32_e32 v182, 17, v0
	v_cndmask_b32_e32 v184, v239, v26, vcc
	v_cndmask_b32_e64 v185, v239, v10, s[0:1]
	v_add_u32_e32 v183, 49, v0
	v_cmp_le_i32_e32 vcc, v182, v197
	v_cmp_gt_i32_e64 s[0:1], v182, v209
	s_and_b64 vcc, vcc, s[0:1]
	v_cmp_le_i32_e64 s[0:1], v183, v197
	v_cmp_gt_i32_e64 s[8:9], v183, v209
	s_and_b64 s[0:1], s[0:1], s[8:9]
	v_add_u32_e32 v182, 18, v0
	v_cndmask_b32_e32 v174, v239, v27, vcc
	v_cndmask_b32_e64 v175, v239, v11, s[0:1]
	v_add_u32_e32 v183, 50, v0
	v_cmp_le_i32_e32 vcc, v182, v197
	v_cmp_gt_i32_e64 s[0:1], v182, v209
	s_and_b64 vcc, vcc, s[0:1]
	v_cmp_le_i32_e64 s[0:1], v183, v197
	v_cmp_gt_i32_e64 s[8:9], v183, v209
	s_and_b64 s[0:1], s[0:1], s[8:9]
	v_add_u32_e32 v182, 19, v0
	v_cndmask_b32_e32 v170, v239, v28, vcc
	v_cndmask_b32_e64 v171, v239, v12, s[0:1]
	v_add_u32_e32 v183, 51, v0
	v_cmp_le_i32_e32 vcc, v182, v197
	v_cmp_gt_i32_e64 s[0:1], v182, v209
	s_and_b64 vcc, vcc, s[0:1]
	v_cmp_le_i32_e64 s[0:1], v183, v197
	v_cmp_gt_i32_e64 s[8:9], v183, v209
	s_and_b64 s[0:1], s[0:1], s[8:9]
	v_add_u32_e32 v182, 24, v0
	v_cndmask_b32_e32 v166, v239, v29, vcc
	v_cndmask_b32_e64 v213, v239, v13, s[0:1]
	v_add_u32_e32 v183, 56, v0
	v_cmp_le_i32_e32 vcc, v182, v197
	v_cmp_gt_i32_e64 s[0:1], v182, v209
	s_and_b64 vcc, vcc, s[0:1]
	v_cmp_le_i32_e64 s[0:1], v183, v197
	v_cmp_gt_i32_e64 s[8:9], v183, v209
	s_and_b64 s[0:1], s[0:1], s[8:9]
	v_add_u32_e32 v182, 25, v0
	v_cndmask_b32_e32 v167, v239, v30, vcc
	v_cndmask_b32_e64 v221, v239, v14, s[0:1]
	v_add_u32_e32 v183, 57, v0
	v_cmp_le_i32_e32 vcc, v182, v197
	v_cmp_gt_i32_e64 s[0:1], v182, v209
	s_and_b64 vcc, vcc, s[0:1]
	v_cmp_le_i32_e64 s[0:1], v183, v197
	v_cmp_gt_i32_e64 s[8:9], v183, v209
	s_and_b64 s[0:1], s[0:1], s[8:9]
	v_add_u32_e32 v182, 26, v0
	v_cndmask_b32_e32 v214, v239, v31, vcc
	v_cndmask_b32_e64 v223, v239, v15, s[0:1]
	v_add_u32_e32 v183, 58, v0
	v_cmp_le_i32_e32 vcc, v182, v197
	v_cmp_gt_i32_e64 s[0:1], v182, v209
	s_and_b64 vcc, vcc, s[0:1]
	v_cmp_le_i32_e64 s[0:1], v183, v197
	v_cmp_gt_i32_e64 s[8:9], v183, v209
	s_and_b64 s[0:1], s[0:1], s[8:9]
	v_add_u32_e32 v182, 27, v0
	v_cndmask_b32_e32 v215, v239, v32, vcc
	v_cndmask_b32_e64 v225, v239, v16, s[0:1]
	v_add_u32_e32 v0, 59, v0
	v_cmp_le_i32_e32 vcc, v182, v197
	v_cmp_gt_i32_e64 s[0:1], v182, v209
	s_and_b64 vcc, vcc, s[0:1]
	v_cmp_le_i32_e64 s[0:1], v0, v197
	v_cmp_gt_i32_e64 s[8:9], v0, v209
	v_max_i32_e32 v0, v164, v165
	v_max3_i32 v0, v172, v173, v0
	v_max_i32_e32 v182, v162, v163
	v_max_i32_e32 v183, v160, v161
	v_max_i32_e32 v181, v156, v157
	v_max3_i32 v182, v168, v169, v182
	v_max_i32_e32 v180, v158, v159
	v_max3_i32 v0, v0, v183, v181
	v_max_i32_e32 v183, v154, v155
	v_max3_i32 v182, v182, v180, v183
	v_max_i32_e32 v183, v184, v185
	v_max_i32_e32 v181, v170, v171
	s_and_b64 s[0:1], s[0:1], s[8:9]
	v_max_i32_e32 v180, v174, v175
	v_max3_i32 v0, v0, v183, v181
	v_max_i32_e32 v183, v166, v213
	v_cndmask_b32_e32 v219, v239, v33, vcc
	v_cndmask_b32_e64 v226, v239, v17, s[0:1]
	v_max3_i32 v182, v182, v180, v183
	v_max_i32_e32 v183, v167, v221
	v_max_i32_e32 v181, v215, v225
	v_max_i32_e32 v180, v214, v223
	v_max3_i32 v0, v0, v183, v181
	v_max_i32_e32 v183, v219, v226
	v_max3_i32 v182, v182, v180, v183
	v_max3_i32 v0, v0, v182, 0
	v_mov_b32_e32 v182, v0
	s_nop 1
	v_permlane32_swap_b32 v182, v0
	s_waitcnt lgkmcnt(0)
	v_max3_f32 v212, v211, v0, v182
	v_cmp_neq_f32_e32 vcc, s69, v212
	s_nop 1
	v_cndmask_b32_e32 v194, 0, v212, vcc
	v_mul_f32_e32 v227, 0xbe38aa3b, v194
	v_fmamk_f32 v0, v172, 0x3e38aa3b, v227
	v_exp_f32_e32 v216, v0
	v_fmamk_f32 v0, v173, 0x3e38aa3b, v227
	v_exp_f32_e32 v228, v0
	v_fmamk_f32 v0, v168, 0x3e38aa3b, v227
	v_exp_f32_e32 v182, v0
	v_fmamk_f32 v0, v169, 0x3e38aa3b, v227
	v_exp_f32_e32 v0, v0
	v_add_f32_e32 v183, v216, v228
	v_pk_add_f32 v[172:173], v[182:183], v[0:1]
	s_nop 0
	v_pk_add_f32 v[186:187], v[172:173], v[172:173] op_sel_hi:[0,1]
	v_fmamk_f32 v172, v164, 0x3e38aa3b, v227
	v_exp_f32_e32 v183, v172
	v_fmamk_f32 v172, v165, 0x3e38aa3b, v227
	v_exp_f32_e32 v229, v172
	v_fmamk_f32 v172, v162, 0x3e38aa3b, v227
	v_exp_f32_e32 v180, v172
	v_fmamk_f32 v172, v163, 0x3e38aa3b, v227
	v_exp_f32_e32 v186, v172
	v_add_f32_e32 v181, v183, v229
	v_pk_add_f32 v[172:173], v[180:181], v[186:187]
	s_nop 0
	v_pk_add_f32 v[188:189], v[172:173], v[172:173] op_sel_hi:[0,1]
	v_fmamk_f32 v172, v160, 0x3e38aa3b, v227
	v_exp_f32_e32 v181, v172
	v_fmamk_f32 v172, v161, 0x3e38aa3b, v227
	v_exp_f32_e32 v187, v172
	v_fmamk_f32 v172, v158, 0x3e38aa3b, v227
	v_exp_f32_e32 v178, v172
	v_fmamk_f32 v172, v159, 0x3e38aa3b, v227
	v_exp_f32_e32 v188, v172
	v_add_f32_e32 v179, v181, v187
	v_pk_add_f32 v[172:173], v[178:179], v[188:189]
	s_nop 0
	v_pk_add_f32 v[192:193], v[172:173], v[172:173] op_sel_hi:[0,1]
	v_fmamk_f32 v172, v156, 0x3e38aa3b, v227
	v_exp_f32_e32 v179, v172
	v_fmamk_f32 v172, v157, 0x3e38aa3b, v227
	v_exp_f32_e32 v189, v172
	v_fmamk_f32 v172, v154, 0x3e38aa3b, v227
	v_exp_f32_e32 v176, v172
	v_fmamk_f32 v172, v155, 0x3e38aa3b, v227
	v_exp_f32_e32 v192, v172
	v_add_f32_e32 v177, v179, v189
	v_cvt_pk_bf16_f32 v217, v179, v176
	v_pk_add_f32 v[172:173], v[176:177], v[192:193]
	s_nop 0
	v_pk_add_f32 v[190:191], v[172:173], v[172:173] op_sel_hi:[0,1]
	v_fmamk_f32 v172, v184, 0x3e38aa3b, v227
	v_exp_f32_e32 v193, v172
	v_fmamk_f32 v172, v185, 0x3e38aa3b, v227
	v_exp_f32_e32 v230, v172
	v_fmamk_f32 v172, v174, 0x3e38aa3b, v227
	v_exp_f32_e32 v202, v172
	v_fmamk_f32 v172, v175, 0x3e38aa3b, v227
	v_exp_f32_e32 v190, v172
	v_sub_f32_e32 v172, v211, v194
	v_add_f32_e32 v203, v193, v230
	v_mul_f32_e32 v168, 0x3e38aa3b, v172
	v_pk_add_f32 v[172:173], v[202:203], v[190:191]
	v_exp_f32_e32 v220, v168
	v_pk_add_f32 v[194:195], v[172:173], v[172:173] op_sel_hi:[0,1]
	v_fmamk_f32 v172, v170, 0x3e38aa3b, v227
	v_exp_f32_e32 v191, v172
	v_fmamk_f32 v172, v171, 0x3e38aa3b, v227
	v_exp_f32_e32 v231, v172
	v_fmamk_f32 v172, v166, 0x3e38aa3b, v227
	v_exp_f32_e32 v218, v172
	v_fmamk_f32 v172, v167, 0x3e38aa3b, v227
	v_exp_f32_e32 v232, v172
	v_fmamk_f32 v172, v214, 0x3e38aa3b, v227
	v_exp_f32_e32 v222, v172
	v_fmamk_f32 v194, v215, 0x3e38aa3b, v227
	v_pk_mul_f32 v[34:35], v[34:35], v[220:221] op_sel_hi:[1,0]
	v_pk_mul_f32 v[50:51], v[50:51], v[220:221] op_sel_hi:[1,0]
	v_pk_mul_f32 v[36:37], v[36:37], v[220:221] op_sel_hi:[1,0]
	v_pk_mul_f32 v[38:39], v[38:39], v[220:221] op_sel_hi:[1,0]
	v_pk_mul_f32 v[40:41], v[40:41], v[220:221] op_sel_hi:[1,0]
	v_pk_mul_f32 v[42:43], v[42:43], v[220:221] op_sel_hi:[1,0]
	v_pk_mul_f32 v[44:45], v[44:45], v[220:221] op_sel_hi:[1,0]
	v_pk_mul_f32 v[46:47], v[46:47], v[220:221] op_sel_hi:[1,0]
	v_pk_mul_f32 v[48:49], v[48:49], v[220:221] op_sel_hi:[1,0]
	v_cvt_pk_bf16_f32 v214, v216, v182
	v_cvt_pk_bf16_f32 v215, v183, v180
	v_cvt_pk_bf16_f32 v216, v181, v178
	v_pk_mul_f32 v[52:53], v[52:53], v[220:221] op_sel_hi:[1,0]
	v_pk_mul_f32 v[54:55], v[54:55], v[220:221] op_sel_hi:[1,0]
	v_pk_mul_f32 v[56:57], v[56:57], v[220:221] op_sel_hi:[1,0]
	v_pk_mul_f32 v[58:59], v[58:59], v[220:221] op_sel_hi:[1,0]
	v_pk_mul_f32 v[60:61], v[60:61], v[220:221] op_sel_hi:[1,0]
	v_pk_mul_f32 v[62:63], v[62:63], v[220:221] op_sel_hi:[1,0]
	v_pk_mul_f32 v[64:65], v[64:65], v[220:221] op_sel_hi:[1,0]
	s_waitcnt vmcnt(15)
	v_mfma_f32_32x32x16_bf16 v[34:49], v[144:147], v[214:217], v[34:49]
	v_exp_f32_e32 v233, v194
	v_fmamk_f32 v194, v219, 0x3e38aa3b, v227
	v_exp_f32_e32 v224, v194
	v_add_f32_e32 v219, v191, v231
	s_waitcnt vmcnt(14)
	v_mfma_f32_32x32x16_bf16 v[50:65], v[140:143], v[214:217], v[50:65]
	v_cvt_pk_bf16_f32 v214, v193, v202
	v_fmamk_f32 v193, v213, 0x3e38aa3b, v227
	v_exp_f32_e32 v194, v193
	v_cvt_pk_bf16_f32 v215, v191, v218
	v_cvt_pk_bf16_f32 v216, v232, v222
	v_cvt_pk_bf16_f32 v217, v233, v224
	v_pk_add_f32 v[202:203], v[218:219], v[194:195]
	v_fmamk_f32 v191, v221, 0x3e38aa3b, v227
	s_waitcnt vmcnt(13)
	v_mfma_f32_32x32x16_bf16 v[34:49], v[136:139], v[214:217], v[34:49]
	v_pk_add_f32 v[202:203], v[202:203], v[202:203] op_sel_hi:[0,1]
	v_exp_f32_e32 v191, v191
	v_fmamk_f32 v193, v223, 0x3e38aa3b, v227
	v_exp_f32_e32 v202, v193
	v_add_f32_e32 v223, v232, v191
	s_waitcnt vmcnt(12)
	v_mfma_f32_32x32x16_bf16 v[50:65], v[132:135], v[214:217], v[50:65]
	v_cvt_pk_bf16_f32 v214, v228, v0
	v_cvt_pk_bf16_f32 v215, v229, v186
	v_cvt_pk_bf16_f32 v216, v187, v188
	v_cvt_pk_bf16_f32 v217, v189, v192
	v_add_f32_e64 v186, v222, v202
	v_add_f32_e64 v187, v223, v203
	v_fmamk_f32 v0, v225, 0x3e38aa3b, v227
	v_pk_add_f32 v[186:187], v[186:187], v[186:187] op_sel_hi:[0,1]
	s_waitcnt vmcnt(11)
	v_mfma_f32_32x32x16_bf16 v[34:49], v[128:131], v[214:217], v[34:49]
	v_exp_f32_e32 v0, v0
	v_fmac_f32_e32 v227, 0x3e38aa3b, v226
	v_exp_f32_e32 v186, v227
	v_cvt_pk_bf16_f32 v188, v230, v190
	v_add_f32_e32 v225, v233, v0
	v_cvt_pk_bf16_f32 v190, v191, v202
	v_cvt_pk_bf16_f32 v191, v0, v186
	s_waitcnt vmcnt(10)
	v_mfma_f32_32x32x16_bf16 v[50:65], v[124:127], v[214:217], v[50:65]
	v_add_f32_e64 v186, v224, v186
	v_add_f32_e64 v187, v225, v187
	v_cvt_pk_bf16_f32 v189, v231, v194
	v_add_f32_e32 v187, v186, v187
	v_fmac_f32_e32 v187, v210, v220
	s_waitcnt vmcnt(9)
	v_mfma_f32_32x32x16_bf16 v[34:49], v[120:123], v[188:191], v[34:49]
	s_waitcnt vmcnt(8)
	v_mfma_f32_32x32x16_bf16 v[50:65], v[116:119], v[188:191], v[50:65]
	s_cbranch_execz .LBB0_1642

.LBB0_1642:
	v_max_i32_e32 v0, v20, v4
	v_max3_i32 v0, v18, v2, v0
	s_nop 6
	v_max_i32_e32 v172, v21, v5
	v_max_i32_e32 v173, v22, v6
	v_max_i32_e32 v169, v24, v8
	v_max3_i32 v172, v19, v3, v172
	v_max_i32_e32 v168, v23, v7
	v_max3_i32 v0, v0, v173, v169
	v_max_i32_e32 v173, v25, v9
	v_max3_i32 v172, v172, v168, v173
	v_max_i32_e32 v173, v26, v10
	v_max_i32_e32 v169, v28, v12
	v_max_i32_e32 v168, v27, v11
	v_max3_i32 v0, v0, v173, v169
	v_max_i32_e32 v173, v29, v13
	v_max3_i32 v172, v172, v168, v173
	v_max_i32_e32 v173, v30, v14
	v_max_i32_e32 v169, v32, v16
	v_max_i32_e32 v168, v31, v15
	v_max3_i32 v0, v0, v173, v169
	v_max_i32_e32 v173, v33, v17
	v_max3_i32 v172, v172, v168, v173
	v_max3_i32 v0, v0, v172, 0
	v_mov_b32_e32 v172, v0
	s_nop 1
	v_permlane32_swap_b32 v172, v0
	s_waitcnt lgkmcnt(0)
	v_max3_f32 v212, v211, v0, v172
	v_cmp_neq_f32_e32 vcc, s69, v212
	s_nop 1
	v_cndmask_b32_e32 v0, 0, v212, vcc
	v_mul_f32_e32 v173, 0xbe38aa3b, v0
	v_sub_f32_e32 v172, v211, v0
	v_fmamk_f32 v0, v18, 0x3e38aa3b, v173
	v_exp_f32_e32 v192, v0
	v_fmamk_f32 v0, v2, 0x3e38aa3b, v173
	v_exp_f32_e32 v193, v0
	v_fmamk_f32 v0, v19, 0x3e38aa3b, v173
	v_exp_f32_e32 v186, v0
	v_fmamk_f32 v0, v3, 0x3e38aa3b, v173
	v_exp_f32_e32 v0, v0
	v_add_f32_e32 v187, v192, v193
	v_mul_f32_e32 v172, 0x3e38aa3b, v172
	v_pk_add_f32 v[2:3], v[186:187], v[0:1]
	s_nop 0
	v_pk_add_f32 v[2:3], v[2:3], v[2:3] op_sel_hi:[0,1]
	v_fmamk_f32 v2, v20, 0x3e38aa3b, v173
	v_exp_f32_e32 v194, v2
	v_fmamk_f32 v2, v4, 0x3e38aa3b, v173
	v_exp_f32_e32 v195, v2
	v_fmamk_f32 v2, v21, 0x3e38aa3b, v173
	v_exp_f32_e32 v188, v2
	v_fmamk_f32 v2, v5, 0x3e38aa3b, v173
	v_exp_f32_e32 v2, v2
	v_add_f32_e32 v189, v194, v195
	v_pk_add_f32 v[4:5], v[188:189], v[2:3]
	s_nop 0
	v_pk_add_f32 v[4:5], v[4:5], v[4:5] op_sel_hi:[0,1]
	v_fmamk_f32 v4, v6, 0x3e38aa3b, v173
	v_fmamk_f32 v3, v22, 0x3e38aa3b, v173
	v_exp_f32_e32 v189, v4
	v_fmamk_f32 v4, v23, 0x3e38aa3b, v173
	v_exp_f32_e32 v3, v3
	v_exp_f32_e32 v190, v4
	v_fmamk_f32 v4, v7, 0x3e38aa3b, v173
	v_exp_f32_e32 v4, v4
	v_add_f32_e32 v191, v3, v189
	v_pk_add_f32 v[6:7], v[190:191], v[4:5]
	s_nop 0
	v_pk_add_f32 v[18:19], v[6:7], v[6:7] op_sel_hi:[0,1]
	v_fmamk_f32 v6, v8, 0x3e38aa3b, v173
	v_fmamk_f32 v5, v24, 0x3e38aa3b, v173
	v_exp_f32_e32 v191, v6
	v_fmamk_f32 v6, v25, 0x3e38aa3b, v173
	v_exp_f32_e32 v5, v5
	v_exp_f32_e32 v22, v6
	v_fmamk_f32 v6, v9, 0x3e38aa3b, v173
	v_exp_f32_e32 v18, v6
	v_add_f32_e32 v23, v5, v191
	v_pk_add_f32 v[6:7], v[22:23], v[18:19]
	s_nop 0
	v_pk_add_f32 v[6:7], v[6:7], v[6:7] op_sel_hi:[0,1]
	v_fmamk_f32 v6, v26, 0x3e38aa3b, v173
	v_exp_f32_e32 v19, v6
	v_fmamk_f32 v6, v10, 0x3e38aa3b, v173
	v_exp_f32_e32 v202, v6
	v_fmamk_f32 v6, v27, 0x3e38aa3b, v173
	v_exp_f32_e32 v20, v6
	v_fmamk_f32 v6, v11, 0x3e38aa3b, v173
	v_exp_f32_e32 v6, v6
	v_add_f32_e32 v21, v19, v202
	v_pk_add_f32 v[8:9], v[20:21], v[6:7]
	s_nop 0
	v_pk_add_f32 v[8:9], v[8:9], v[8:9] op_sel_hi:[0,1]
	v_fmamk_f32 v8, v12, 0x3e38aa3b, v173
	v_fmamk_f32 v7, v28, 0x3e38aa3b, v173
	v_exp_f32_e32 v203, v8
	v_fmamk_f32 v8, v29, 0x3e38aa3b, v173
	v_exp_f32_e32 v7, v7
	v_exp_f32_e32 v24, v8
	v_fmamk_f32 v8, v13, 0x3e38aa3b, v173
	v_exp_f32_e32 v8, v8
	v_add_f32_e32 v25, v7, v203
	v_cvt_pk_bf16_f32 v28, v192, v186
	v_cvt_pk_bf16_f32 v29, v194, v188
	v_pk_add_f32 v[10:11], v[24:25], v[8:9]
	v_fmamk_f32 v9, v30, 0x3e38aa3b, v173
	v_pk_add_f32 v[10:11], v[10:11], v[10:11] op_sel_hi:[0,1]
	v_fmamk_f32 v10, v14, 0x3e38aa3b, v173
	v_exp_f32_e32 v25, v10
	v_fmamk_f32 v10, v31, 0x3e38aa3b, v173
	v_exp_f32_e32 v9, v9
	v_exp_f32_e32 v26, v10
	v_fmamk_f32 v10, v15, 0x3e38aa3b, v173
	v_exp_f32_e32 v10, v10
	v_add_f32_e32 v27, v9, v25
	v_cvt_pk_bf16_f32 v30, v3, v190
	v_cvt_pk_bf16_f32 v31, v5, v22
	v_pk_add_f32 v[12:13], v[26:27], v[10:11]
	v_fmamk_f32 v11, v32, 0x3e38aa3b, v173
	v_pk_add_f32 v[12:13], v[12:13], v[12:13] op_sel_hi:[0,1]
	v_fmamk_f32 v12, v16, 0x3e38aa3b, v173
	v_exp_f32_e32 v11, v11
	v_exp_f32_e32 v27, v12
	v_fmamk_f32 v12, v33, 0x3e38aa3b, v173
	v_fmac_f32_e32 v173, 0x3e38aa3b, v17
	v_exp_f32_e32 v14, v12
	v_exp_f32_e32 v12, v173
	v_add_f32_e32 v15, v11, v27
	v_cvt_pk_bf16_f32 v20, v19, v20
	v_cvt_pk_bf16_f32 v21, v7, v24
	v_pk_add_f32 v[16:17], v[14:15], v[12:13]
	v_cvt_pk_bf16_f32 v22, v9, v26
	v_add_f32_e32 v187, v16, v17
	v_exp_f32_e32 v16, v172
	v_cvt_pk_bf16_f32 v23, v11, v14
	v_cvt_pk_bf16_f32 v14, v193, v0
	v_cvt_pk_bf16_f32 v15, v195, v2
	v_pk_mul_f32 v[34:35], v[34:35], v[16:17] op_sel_hi:[1,0]
	v_pk_mul_f32 v[50:51], v[50:51], v[16:17] op_sel_hi:[1,0]
	v_pk_mul_f32 v[36:37], v[36:37], v[16:17] op_sel_hi:[1,0]
	v_pk_mul_f32 v[52:53], v[52:53], v[16:17] op_sel_hi:[1,0]
	v_pk_mul_f32 v[38:39], v[38:39], v[16:17] op_sel_hi:[1,0]
	v_pk_mul_f32 v[54:55], v[54:55], v[16:17] op_sel_hi:[1,0]
	v_pk_mul_f32 v[40:41], v[40:41], v[16:17] op_sel_hi:[1,0]
	v_pk_mul_f32 v[56:57], v[56:57], v[16:17] op_sel_hi:[1,0]
	v_pk_mul_f32 v[42:43], v[42:43], v[16:17] op_sel_hi:[1,0]
	v_pk_mul_f32 v[58:59], v[58:59], v[16:17] op_sel_hi:[1,0]
	v_pk_mul_f32 v[44:45], v[44:45], v[16:17] op_sel_hi:[1,0]
	v_pk_mul_f32 v[60:61], v[60:61], v[16:17] op_sel_hi:[1,0]
	v_pk_mul_f32 v[46:47], v[46:47], v[16:17] op_sel_hi:[1,0]
	v_pk_mul_f32 v[62:63], v[62:63], v[16:17] op_sel_hi:[1,0]
	v_pk_mul_f32 v[48:49], v[48:49], v[16:17] op_sel_hi:[1,0]
	v_pk_mul_f32 v[64:65], v[64:65], v[16:17] op_sel_hi:[1,0]
	v_fmac_f32_e32 v187, v210, v16
	s_waitcnt vmcnt(15)
	v_mfma_f32_32x32x16_bf16 v[34:49], v[144:147], v[28:31], v[34:49]
	v_cvt_pk_bf16_f32 v16, v189, v4
	v_cvt_pk_bf16_f32 v17, v191, v18
	v_cvt_pk_bf16_f32 v2, v202, v6
	v_cvt_pk_bf16_f32 v3, v203, v8
	v_cvt_pk_bf16_f32 v4, v25, v10
	v_cvt_pk_bf16_f32 v5, v27, v12
	s_waitcnt vmcnt(14)
	v_mfma_f32_32x32x16_bf16 v[50:65], v[140:143], v[28:31], v[50:65]
	s_waitcnt vmcnt(13)
	v_mfma_f32_32x32x16_bf16 v[34:49], v[136:139], v[20:23], v[34:49]
	s_waitcnt vmcnt(12)
	v_mfma_f32_32x32x16_bf16 v[50:65], v[132:135], v[20:23], v[50:65]
	s_waitcnt vmcnt(11)
	v_mfma_f32_32x32x16_bf16 v[34:49], v[128:131], v[14:17], v[34:49]
	s_waitcnt vmcnt(10)
	v_mfma_f32_32x32x16_bf16 v[50:65], v[124:127], v[14:17], v[50:65]
	s_waitcnt vmcnt(9)
	v_mfma_f32_32x32x16_bf16 v[34:49], v[120:123], v[2:5], v[34:49]
	s_waitcnt vmcnt(8)
	v_mfma_f32_32x32x16_bf16 v[50:65], v[116:119], v[2:5], v[50:65]
	s_xor_b64 s[0:1], s[20:21], -1
	s_andn2_b64 vcc, exec, s[0:1]
	s_cbranch_vccz .LBB0_1491
